# inproj0: 256x128 block tiles (two output tiles share the weight tile; compiled epilogue run twice with the second accumulator set parked in spare VGPRs/LDS), A direct from fragment-major hdn, B via LD
# speedup vs baseline: 1.0340x; 1.0152x over previous
.LBB0_168:
	s_or_b64 exec, exec, s[0:1]
	s_add_u32 s36, s50, 0x5a00000
	s_addc_u32 s37, s51, 0
	s_add_u32 s0, s50, 0xda00000
	v_writelane_b32 v247, s0, 3
	s_addc_u32 s0, s51, 0
	v_bfe_u32 v134, v131, 4, 2
	v_bfe_u32 v139, v131, 1, 3
	s_cmpk_gt_i32 s2, 0x1bff
	v_and_b32_e32 v138, 15, v131
	v_lshlrev_b32_e32 v149, 8, v131
	v_lshrrev_b32_e32 v153, 1, v131
	v_or_b32_e32 v136, 4, v134
	v_bitop3_b32 v152, v134, v139, 4 bitop3:0x36
	v_lshlrev_b32_e32 v137, 9, v134
	v_or_b32_e32 v132, 8, v134
	v_or_b32_e32 v130, 12, v134
	s_waitcnt lgkmcnt(0)
	s_barrier
	v_writelane_b32 v247, s0, 4
	s_cbranch_scc1 .LBB0_196
	v_xor_b32_e32 v0, v128, v131
	v_and_b32_e32 v142, 0x3f800, v149
	v_mov_b32_e32 v143, 0
	v_lshlrev_b32_e32 v0, 4, v0
	v_and_b32_e32 v0, 0x70, v0
	v_mov_b32_e32 v1, v143
	v_lshl_add_u64 v[2:3], s[50:51], 0, v[142:143]
	v_lshl_add_u64 v[0:1], v[2:3], 0, v[0:1]
	s_mov_b64 s[0:1], 0x3a00000
	v_lshl_add_u64 v[144:145], v[0:1], 0, s[0:1]
	s_mov_b64 s[0:1], 0x1a00000
	v_lshl_add_u64 v[146:147], v[0:1], 0, s[0:1]
	s_movk_i32 s0, 0x1e0
	v_and_or_b32 v0, v153, s0, v138
	v_bitop3_b32 v1, v128, v139, 3 bitop3:0x6c
	v_lshlrev_b32_e32 v159, 7, v0
	v_lshlrev_b32_e32 v0, 13, v135
	v_lshlrev_b32_e32 v158, 4, v1
	v_lshl_add_u32 v1, v134, 3, v138
	v_lshl_or_b32 v2, v134, 11, v0
	v_lshlrev_b32_e32 v4, 5, v138
	v_or3_b32 v161, v0, v137, v4
	v_lshl_or_b32 v162, v1, 2, v2
	v_add_u32_e32 v4, 0x60, v1
	v_add_u32_e32 v1, 0x70, v1
	v_and_b32_e32 v4, 0x7f, v4
	v_and_b32_e32 v1, 0x7f, v1
	v_lshl_or_b32 v163, v4, 2, v2
	v_lshl_or_b32 v164, v1, 2, v2
	v_add_u32_e32 v2, 8, v133
	v_and_b32_e32 v2, 0x78, v2
	v_lshlrev_b32_e32 v1, 9, v136
	v_lshlrev_b32_e32 v2, 2, v2
	v_or3_b32 v166, v0, v1, v2
	v_add_u32_e32 v2, 16, v133
	v_and_b32_e32 v2, 0x78, v2
	v_lshlrev_b32_e32 v1, 9, v132
	v_lshlrev_b32_e32 v2, 2, v2
	v_or3_b32 v168, v0, v1, v2
	v_add_u32_e32 v2, 24, v133
	v_and_b32_e32 v2, 0x78, v2
	v_lshlrev_b32_e32 v3, 5, v135
	v_lshlrev_b32_e32 v1, 9, v130
	v_lshlrev_b32_e32 v2, 2, v2
	v_or3_b32 v170, v0, v1, v2
	v_or_b32_e32 v0, 16, v3
	v_add_u32_e32 v4, 0x100, v131
	v_add_u32_e32 v5, 0x200, v131
	v_add_u32_e32 v6, 0x300, v131
	v_add_u32_e32 v7, 0x500, v131
	v_add_u32_e32 v8, 0x600, v131
	v_add_u32_e32 v9, 0x700, v131
	v_or_b32_e32 v172, v0, v134
	v_or_b32_e32 v173, v136, v0
	v_or_b32_e32 v174, v132, v0
	v_or_b32_e32 v175, v130, v0
	v_and_b32_e32 v0, 24, v153
	s_movk_i32 s0, 0x3c0
	v_lshrrev_b32_e32 v176, 4, v4
	v_lshrrev_b32_e32 v177, 4, v5
	v_lshrrev_b32_e32 v178, 4, v6
	v_lshrrev_b32_e32 v180, 4, v7
	v_lshrrev_b32_e32 v181, 4, v8
	v_lshrrev_b32_e32 v182, 4, v9
	v_bitop3_b32 v10, v128, 7, v131 bitop3:0x48
	v_or_b32_e32 v165, v134, v3
	v_or_b32_e32 v167, v136, v3
	v_or_b32_e32 v169, v132, v3
	v_or_b32_e32 v171, v130, v3
	v_and_or_b32 v0, v131, s0, v0
	v_mul_u32_u24_e32 v1, 0x110, v138
	v_lshlrev_b32_e32 v2, 4, v138
	v_mul_u32_u24_e32 v3, 0x110, v128
	v_mul_u32_u24_e32 v4, 0x110, v176
	v_mul_u32_u24_e32 v5, 0x110, v177
	v_mul_u32_u24_e32 v6, 0x110, v178
	v_mul_u32_u24_e32 v7, 0x110, v180
	v_mul_u32_u24_e32 v8, 0x110, v181
	v_mul_u32_u24_e32 v9, 0x110, v182
	s_add_u32 s33, s48, 0x2000000
	v_lshl_or_b32 v142, v10, 4, v142
	v_lshlrev_b32_e32 v156, 7, v138
	v_lshlrev_b32_e32 v160, 4, v152
	v_lshlrev_b32_e32 v148, 3, v138
	v_or_b32_e32 v179, 64, v128
	s_addc_u32 s39, s49, 0
	v_lshl_add_u64 v[150:151], s[50:51], 0, v[142:143]
	s_mov_b64 s[8:9], 0x10000
	v_add_u32_e32 v183, 0x1000, v129
	s_mov_b64 s[10:11], 0x20000
	v_add_u32_e32 v184, 0x2000, v129
	s_mov_b64 s[12:13], 0x30000
	v_add_u32_e32 v185, 0x3000, v129
	v_or_b32_e32 v186, 0x4000, v129
	v_add_u32_e32 v187, 0x5000, v129
	v_add_u32_e32 v188, 0x6000, v129
	v_add_u32_e32 v189, 0x7000, v129
	s_mov_b64 s[14:15], 0x3a00080
	s_mov_b64 s[16:17], 0x3a10080
	s_mov_b64 s[18:19], 0x3a20080
	s_mov_b64 s[20:21], 0x3a30080
	s_mov_b64 s[22:23], 0x1a00080
	s_mov_b64 s[24:25], 0x1a10080
	s_mov_b64 s[28:29], 0x1a20080
	s_mov_b64 s[30:31], 0x1a30080
	s_mov_b32 s35, 0
	v_lshlrev_b32_e32 v190, 2, v138
	s_brev_b32 s38, 60
	s_mov_b32 s46, 0x358637bd
	s_mov_b32 s47, 0x800000
	s_mov_b32 s52, 0x45800000
	s_mov_b32 s60, 0x3e0293ee
	s_mov_b32 s53, 0x9a00000
	s_movk_i32 s61, 0x7fff
	s_mov_b32 s74, 0x7060302
	v_add_u32_e32 v191, v0, v1
	v_add_u32_e32 v192, v2, v3
	v_add_u32_e32 v193, v2, v4
	v_add_u32_e32 v194, v2, v5
	v_add_u32_e32 v195, v2, v6
	v_add_u32_e32 v196, v2, v7
	v_add_u32_e32 v197, v2, v8
	v_add_u32_e32 v198, v2, v9
	v_mbcnt_hi_u32_b32 v199, -1, v155
	s_mov_b32 s75, s2
	s_mov_b32 s89, 0
	s_branch .LBB0_171
.LBB0_170:
	s_xor_b32 s89, s89, 1
	s_cmp_lg_u32 s89, 0
	s_cbranch_scc1 .LBB0_171
	s_add_i32 s75, s75, s3
	s_cmpk_lt_i32 s75, 0xe00
	s_cbranch_scc0 .LBB0_196
.LBB0_171:
	s_lshr_b32 s88, s75, 3
	s_lshl_b32 s88, s88, 4
	s_and_b32 s90, s75, 7
	s_or_b32 s88, s88, s90
	s_lshl_b32 s90, s89, 3
	s_add_i32 s88, s88, s90
	s_ashr_i32 s1, s88, 31
	s_lshr_b32 s1, s1, 23
	s_add_i32 s1, s88, s1
	s_ashr_i32 s1, s1, 9
	s_and_b32 s0, s88, 7
	s_lshl_b32 s1, s1, 3
	s_or_b32 s34, s1, s0
	s_mul_hi_i32 s0, s34, 0x92492493
	s_add_i32 s0, s0, s34
	s_lshr_b32 s1, s0, 31
	s_ashr_i32 s70, s0, 2
	s_add_i32 s70, s70, s1
	s_lshl_b32 s0, s70, 3
	s_bfe_u32 s1, s88, 0x30003
	s_or_b32 s66, s0, s1
	s_mul_i32 s0, s70, 7
	s_sub_i32 s77, s34, s0
	s_lshl_b32 s0, s77, 3
	s_bfe_u32 s76, s88, 0x30006
	s_or_b32 s0, s0, s76
	s_ashr_i32 s67, s66, 31
	s_ashr_i32 s1, s0, 31
	s_lshl_b64 s[4:5], s[0:1], 18
	s_lshl_b64 s[6:7], s[66:67], 18
	s_cmp_lg_u32 s89, 0
	s_cbranch_scc1 .Lmy_ip0_pass2
	s_barrier
	s_lshl_b64 s[64:65], s[66:67], 17
	s_add_u32 s84, s50, 0x3a00000
	s_addc_u32 s85, s51, 0
	s_add_u32 s84, s84, s6
	s_addc_u32 s85, s85, s7
	s_add_u32 s92, s84, 0x40000
	s_addc_u32 s93, s85, 0
	s_add_u32 s86, s50, 0x1a00000
	s_addc_u32 s87, s51, 0
	s_add_u32 s86, s86, s4
	s_addc_u32 s87, s87, s5
	v_readfirstlane_b32 s1, v129
	v_and_b32_e32 v200, 15, v131
	v_bfe_u32 v201, v131, 4, 2
	v_and_b32_e32 v202, 63, v131
	v_lshlrev_b32_e32 v202, 4, v202
	v_lshrrev_b32_e32 v203, 6, v131
	v_lshl_add_u32 v142, v203, 16, v202
	v_add_u32_e32 v150, 0x8000, v142
	v_bfe_u32 v202, v131, 1, 3
	v_xor_b32_e32 v202, v201, v202
	v_lshlrev_b32_e32 v202, 4, v202
	v_lshl_or_b32 v212, v200, 7, v202
	v_xor_b32_e32 v213, 64, v212
	v_bfe_u32 v200, v131, 4, 3
	v_and_b32_e32 v201, 7, v131
	v_xor_b32_e32 v200, v200, v201
	v_lshlrev_b32_e32 v200, 4, v200
	v_lshrrev_b32_e32 v201, 3, v131
	v_lshl_or_b32 v151, v201, 11, v200
	v_add_u32_e32 v156, 65536, v151
	v_add_u32_e32 v158, 131072, v151
	v_add_u32_e32 v159, 196608, v151
	s_add_u32 m0, s1, 0
	v_mov_b32_e32 v0, 0
	v_mov_b32_e32 v1, 0
	global_load_lds_dwordx4 v151, s[86:87]
	v_mov_b32_e32 v2, 0
	v_mov_b32_e32 v3, 0
	v_mov_b32_e32 v4, 0
	s_add_u32 m0, s1, 4096
	v_mov_b32_e32 v5, 0
	v_mov_b32_e32 v6, 0
	global_load_lds_dwordx4 v156, s[86:87]
	v_mov_b32_e32 v7, 0
	v_mov_b32_e32 v8, 0
	v_mov_b32_e32 v9, 0
	s_add_u32 m0, s1, 8192
	v_mov_b32_e32 v10, 0
	v_mov_b32_e32 v11, 0
	global_load_lds_dwordx4 v158, s[86:87]
	v_mov_b32_e32 v12, 0
	v_mov_b32_e32 v13, 0
	v_mov_b32_e32 v14, 0
	s_add_u32 m0, s1, 12288
	v_mov_b32_e32 v15, 0
	v_mov_b32_e32 v16, 0
	global_load_lds_dwordx4 v159, s[86:87]
	s_add_u32 s86, s86, 128
	s_addc_u32 s87, s87, 0
	v_mov_b32_e32 v17, 0
	v_mov_b32_e32 v18, 0
	v_mov_b32_e32 v19, 0
	global_load_dwordx4 v[64:67], v142, s[84:85] offset:0
	v_mov_b32_e32 v20, 0
	v_mov_b32_e32 v21, 0
	v_mov_b32_e32 v22, 0
	global_load_dwordx4 v[68:71], v150, s[84:85] offset:0
	v_mov_b32_e32 v23, 0
	v_mov_b32_e32 v24, 0
	v_mov_b32_e32 v25, 0
	global_load_dwordx4 v[72:75], v142, s[92:93] offset:0
	v_mov_b32_e32 v26, 0
	v_mov_b32_e32 v27, 0
	v_mov_b32_e32 v28, 0
	global_load_dwordx4 v[76:79], v150, s[92:93] offset:0
	v_mov_b32_e32 v29, 0
	v_mov_b32_e32 v30, 0
	v_mov_b32_e32 v31, 0
	global_load_dwordx4 v[80:83], v142, s[84:85] offset:1024
	v_mov_b32_e32 v32, 0
	v_mov_b32_e32 v33, 0
	v_mov_b32_e32 v34, 0
	global_load_dwordx4 v[84:87], v150, s[84:85] offset:1024
	v_mov_b32_e32 v35, 0
	v_mov_b32_e32 v36, 0
	v_mov_b32_e32 v37, 0
	global_load_dwordx4 v[88:91], v142, s[92:93] offset:1024
	v_mov_b32_e32 v38, 0
	v_mov_b32_e32 v39, 0
	v_mov_b32_e32 v40, 0
	global_load_dwordx4 v[92:95], v150, s[92:93] offset:1024
	s_add_u32 s84, s84, 0x800
	s_addc_u32 s85, s85, 0
	s_add_u32 s92, s92, 0x800
	s_addc_u32 s93, s93, 0
	v_mov_b32_e32 v41, 0
	v_mov_b32_e32 v42, 0
	v_mov_b32_e32 v43, 0
	s_add_u32 m0, s1, 16384
	v_mov_b32_e32 v44, 0
	v_mov_b32_e32 v45, 0
	global_load_lds_dwordx4 v151, s[86:87]
	v_mov_b32_e32 v46, 0
	v_mov_b32_e32 v47, 0
	v_mov_b32_e32 v48, 0
	s_add_u32 m0, s1, 20480
	v_mov_b32_e32 v49, 0
	v_mov_b32_e32 v50, 0
	global_load_lds_dwordx4 v156, s[86:87]
	v_mov_b32_e32 v51, 0
	v_mov_b32_e32 v52, 0
	v_mov_b32_e32 v53, 0
	s_add_u32 m0, s1, 24576
	v_mov_b32_e32 v54, 0
	v_mov_b32_e32 v55, 0
	global_load_lds_dwordx4 v158, s[86:87]
	v_mov_b32_e32 v56, 0
	v_mov_b32_e32 v57, 0
	v_mov_b32_e32 v58, 0
	s_add_u32 m0, s1, 28672
	v_mov_b32_e32 v59, 0
	v_mov_b32_e32 v60, 0
	global_load_lds_dwordx4 v159, s[86:87]
	s_add_u32 s86, s86, 128
	s_addc_u32 s87, s87, 0
	v_mov_b32_e32 v61, 0
	v_mov_b32_e32 v62, 0
	v_mov_b32_e32 v63, 0
	s_add_u32 m0, s1, 32768
	v_mov_b32_e32 v144, 0
	v_mov_b32_e32 v145, 0
	global_load_lds_dwordx4 v151, s[86:87]
	v_mov_b32_e32 v146, 0
	v_mov_b32_e32 v147, 0
	v_mov_b32_e32 v184, 0
	s_add_u32 m0, s1, 36864
	v_mov_b32_e32 v185, 0
	v_mov_b32_e32 v186, 0
	global_load_lds_dwordx4 v156, s[86:87]
	v_mov_b32_e32 v187, 0
	v_mov_b32_e32 v204, 0
	v_mov_b32_e32 v205, 0
	s_add_u32 m0, s1, 40960
	v_mov_b32_e32 v206, 0
	v_mov_b32_e32 v207, 0
	global_load_lds_dwordx4 v158, s[86:87]
	v_mov_b32_e32 v208, 0
	v_mov_b32_e32 v209, 0
	v_mov_b32_e32 v210, 0
	s_add_u32 m0, s1, 45056
	v_mov_b32_e32 v211, 0
	v_mov_b32_e32 v232, 0
	global_load_lds_dwordx4 v159, s[86:87]
	s_add_u32 s86, s86, 128
	s_addc_u32 s87, s87, 0
	v_mov_b32_e32 v233, 0
	v_mov_b32_e32 v234, 0
	v_mov_b32_e32 v235, 0
	v_mov_b32_e32 v236, 0
	v_mov_b32_e32 v237, 0
	v_mov_b32_e32 v238, 0
	v_mov_b32_e32 v239, 0
	v_mov_b32_e32 v240, 0
	v_mov_b32_e32 v241, 0
	v_mov_b32_e32 v242, 0
	v_mov_b32_e32 v243, 0
	v_mov_b32_e32 v248, 0
	v_mov_b32_e32 v249, 0
	v_mov_b32_e32 v250, 0
	v_mov_b32_e32 v251, 0
	v_mov_b32_e32 v252, 0
	v_mov_b32_e32 v253, 0
	v_mov_b32_e32 v254, 0
	v_mov_b32_e32 v255, 0
	v_mov_b32_e32 v100, 0
	v_mov_b32_e32 v101, 0
	v_mov_b32_e32 v102, 0
	v_mov_b32_e32 v103, 0
	v_mov_b32_e32 v104, 0
	v_mov_b32_e32 v105, 0
	v_mov_b32_e32 v106, 0
	v_mov_b32_e32 v107, 0
	v_mov_b32_e32 v108, 0
	v_mov_b32_e32 v109, 0
	v_mov_b32_e32 v110, 0
	v_mov_b32_e32 v111, 0
	v_mov_b32_e32 v112, 0
	v_mov_b32_e32 v113, 0
	v_mov_b32_e32 v114, 0
	v_mov_b32_e32 v115, 0
	v_mov_b32_e32 v116, 0
	v_mov_b32_e32 v117, 0
	v_mov_b32_e32 v118, 0
	v_mov_b32_e32 v119, 0
	v_mov_b32_e32 v120, 0
	v_mov_b32_e32 v121, 0
	v_mov_b32_e32 v122, 0
	v_mov_b32_e32 v123, 0
	v_mov_b32_e32 v124, 0
	v_mov_b32_e32 v125, 0
	v_mov_b32_e32 v126, 0
	v_mov_b32_e32 v127, 0
	s_waitcnt vmcnt(12)
	s_barrier
	ds_read_b128 v[160:163], v212 offset:0
	ds_read_b128 v[176:179], v212 offset:2048
	ds_read_b128 v[180:183], v212 offset:4096
	ds_read_b128 v[188:191], v212 offset:6144
	ds_read_b128 v[192:195], v212 offset:8192
	global_load_dwordx4 v[96:99], v142, s[84:85] offset:0
	s_waitcnt lgkmcnt(4)
	v_mfma_f32_16x16x32_bf16 v[0:3], v[64:67], v[160:163], v[0:3]
	v_mfma_f32_16x16x32_bf16 v[32:35], v[68:71], v[160:163], v[32:35]
	v_mfma_f32_16x16x32_bf16 v[144:147], v[72:75], v[160:163], v[144:147]
	v_mfma_f32_16x16x32_bf16 v[252:255], v[76:79], v[160:163], v[252:255]
	ds_read_b128 v[196:199], v212 offset:10240
	global_load_dwordx4 v[164:167], v150, s[84:85] offset:0
	s_waitcnt lgkmcnt(4)
	v_mfma_f32_16x16x32_bf16 v[4:7], v[64:67], v[176:179], v[4:7]
	v_mfma_f32_16x16x32_bf16 v[36:39], v[68:71], v[176:179], v[36:39]
	v_mfma_f32_16x16x32_bf16 v[184:187], v[72:75], v[176:179], v[184:187]
	v_mfma_f32_16x16x32_bf16 v[100:103], v[76:79], v[176:179], v[100:103]
	ds_read_b128 v[160:163], v212 offset:12288
	global_load_dwordx4 v[168:171], v142, s[92:93] offset:0
	s_waitcnt lgkmcnt(4)
	v_mfma_f32_16x16x32_bf16 v[8:11], v[64:67], v[180:183], v[8:11]
	v_mfma_f32_16x16x32_bf16 v[40:43], v[68:71], v[180:183], v[40:43]
	v_mfma_f32_16x16x32_bf16 v[204:207], v[72:75], v[180:183], v[204:207]
	v_mfma_f32_16x16x32_bf16 v[104:107], v[76:79], v[180:183], v[104:107]
	ds_read_b128 v[176:179], v212 offset:14336
	global_load_dwordx4 v[172:175], v150, s[92:93] offset:0
	s_waitcnt lgkmcnt(4)
	v_mfma_f32_16x16x32_bf16 v[12:15], v[64:67], v[188:191], v[12:15]
	v_mfma_f32_16x16x32_bf16 v[44:47], v[68:71], v[188:191], v[44:47]
	v_mfma_f32_16x16x32_bf16 v[208:211], v[72:75], v[188:191], v[208:211]
	v_mfma_f32_16x16x32_bf16 v[108:111], v[76:79], v[188:191], v[108:111]
	ds_read_b128 v[180:183], v213 offset:0
	s_waitcnt lgkmcnt(4)
	v_mfma_f32_16x16x32_bf16 v[16:19], v[64:67], v[192:195], v[16:19]
	v_mfma_f32_16x16x32_bf16 v[48:51], v[68:71], v[192:195], v[48:51]
	v_mfma_f32_16x16x32_bf16 v[232:235], v[72:75], v[192:195], v[232:235]
	v_mfma_f32_16x16x32_bf16 v[112:115], v[76:79], v[192:195], v[112:115]
	ds_read_b128 v[188:191], v213 offset:2048
	s_waitcnt lgkmcnt(4)
	v_mfma_f32_16x16x32_bf16 v[20:23], v[64:67], v[196:199], v[20:23]
	v_mfma_f32_16x16x32_bf16 v[52:55], v[68:71], v[196:199], v[52:55]
	v_mfma_f32_16x16x32_bf16 v[236:239], v[72:75], v[196:199], v[236:239]
	v_mfma_f32_16x16x32_bf16 v[116:119], v[76:79], v[196:199], v[116:119]
	ds_read_b128 v[192:195], v213 offset:4096
	s_waitcnt lgkmcnt(4)
	v_mfma_f32_16x16x32_bf16 v[24:27], v[64:67], v[160:163], v[24:27]
	v_mfma_f32_16x16x32_bf16 v[56:59], v[68:71], v[160:163], v[56:59]
	v_mfma_f32_16x16x32_bf16 v[240:243], v[72:75], v[160:163], v[240:243]
	v_mfma_f32_16x16x32_bf16 v[120:123], v[76:79], v[160:163], v[120:123]
	ds_read_b128 v[196:199], v213 offset:6144
	s_waitcnt lgkmcnt(4)
	v_mfma_f32_16x16x32_bf16 v[28:31], v[64:67], v[176:179], v[28:31]
	v_mfma_f32_16x16x32_bf16 v[60:63], v[68:71], v[176:179], v[60:63]
	v_mfma_f32_16x16x32_bf16 v[248:251], v[72:75], v[176:179], v[248:251]
	v_mfma_f32_16x16x32_bf16 v[124:127], v[76:79], v[176:179], v[124:127]
	s_waitcnt vmcnt(8)
	s_barrier
	s_waitcnt vmcnt(12)
	ds_read_b128 v[160:163], v213 offset:8192
	global_load_dwordx4 v[64:67], v142, s[84:85] offset:1024
	s_waitcnt lgkmcnt(4)
	v_mfma_f32_16x16x32_bf16 v[0:3], v[80:83], v[180:183], v[0:3]
	v_mfma_f32_16x16x32_bf16 v[32:35], v[84:87], v[180:183], v[32:35]
	v_mfma_f32_16x16x32_bf16 v[144:147], v[88:91], v[180:183], v[144:147]
	v_mfma_f32_16x16x32_bf16 v[252:255], v[92:95], v[180:183], v[252:255]
	ds_read_b128 v[176:179], v213 offset:10240
	global_load_dwordx4 v[68:71], v150, s[84:85] offset:1024
	s_waitcnt lgkmcnt(4)
	v_mfma_f32_16x16x32_bf16 v[4:7], v[80:83], v[188:191], v[4:7]
	v_mfma_f32_16x16x32_bf16 v[36:39], v[84:87], v[188:191], v[36:39]
	v_mfma_f32_16x16x32_bf16 v[184:187], v[88:91], v[188:191], v[184:187]
	v_mfma_f32_16x16x32_bf16 v[100:103], v[92:95], v[188:191], v[100:103]
	ds_read_b128 v[180:183], v213 offset:12288
	global_load_dwordx4 v[72:75], v142, s[92:93] offset:1024
	s_waitcnt lgkmcnt(4)
	v_mfma_f32_16x16x32_bf16 v[8:11], v[80:83], v[192:195], v[8:11]
	v_mfma_f32_16x16x32_bf16 v[40:43], v[84:87], v[192:195], v[40:43]
	v_mfma_f32_16x16x32_bf16 v[204:207], v[88:91], v[192:195], v[204:207]
	v_mfma_f32_16x16x32_bf16 v[104:107], v[92:95], v[192:195], v[104:107]
	ds_read_b128 v[188:191], v213 offset:14336
	global_load_dwordx4 v[76:79], v150, s[92:93] offset:1024
	s_add_u32 s84, s84, 0x800
	s_addc_u32 s85, s85, 0
	s_add_u32 s92, s92, 0x800
	s_addc_u32 s93, s93, 0
	s_waitcnt lgkmcnt(4)
	v_mfma_f32_16x16x32_bf16 v[12:15], v[80:83], v[196:199], v[12:15]
	v_mfma_f32_16x16x32_bf16 v[44:47], v[84:87], v[196:199], v[44:47]
	v_mfma_f32_16x16x32_bf16 v[208:211], v[88:91], v[196:199], v[208:211]
	v_mfma_f32_16x16x32_bf16 v[108:111], v[92:95], v[196:199], v[108:111]
	ds_read_b128 v[192:195], v212 offset:16384
	s_add_u32 m0, s1, 49152
	s_nop 0
	global_load_lds_dwordx4 v151, s[86:87]
	s_waitcnt lgkmcnt(4)
	v_mfma_f32_16x16x32_bf16 v[16:19], v[80:83], v[160:163], v[16:19]
	v_mfma_f32_16x16x32_bf16 v[48:51], v[84:87], v[160:163], v[48:51]
	v_mfma_f32_16x16x32_bf16 v[232:235], v[88:91], v[160:163], v[232:235]
	v_mfma_f32_16x16x32_bf16 v[112:115], v[92:95], v[160:163], v[112:115]
	ds_read_b128 v[196:199], v212 offset:18432
	s_add_u32 m0, s1, 53248
	s_nop 0
	global_load_lds_dwordx4 v156, s[86:87]
	s_waitcnt lgkmcnt(4)
	v_mfma_f32_16x16x32_bf16 v[20:23], v[80:83], v[176:179], v[20:23]
	v_mfma_f32_16x16x32_bf16 v[52:55], v[84:87], v[176:179], v[52:55]
	v_mfma_f32_16x16x32_bf16 v[236:239], v[88:91], v[176:179], v[236:239]
	v_mfma_f32_16x16x32_bf16 v[116:119], v[92:95], v[176:179], v[116:119]
	ds_read_b128 v[160:163], v212 offset:20480
	s_add_u32 m0, s1, 57344
	s_nop 0
	global_load_lds_dwordx4 v158, s[86:87]
	s_waitcnt lgkmcnt(4)
	v_mfma_f32_16x16x32_bf16 v[24:27], v[80:83], v[180:183], v[24:27]
	v_mfma_f32_16x16x32_bf16 v[56:59], v[84:87], v[180:183], v[56:59]
	v_mfma_f32_16x16x32_bf16 v[240:243], v[88:91], v[180:183], v[240:243]
	v_mfma_f32_16x16x32_bf16 v[120:123], v[92:95], v[180:183], v[120:123]
	ds_read_b128 v[176:179], v212 offset:22528
	s_add_u32 m0, s1, 61440
	s_nop 0
	global_load_lds_dwordx4 v159, s[86:87]
	s_add_u32 s86, s86, 128
	s_addc_u32 s87, s87, 0
	s_waitcnt lgkmcnt(4)
	v_mfma_f32_16x16x32_bf16 v[28:31], v[80:83], v[188:191], v[28:31]
	v_mfma_f32_16x16x32_bf16 v[60:63], v[84:87], v[188:191], v[60:63]
	v_mfma_f32_16x16x32_bf16 v[248:251], v[88:91], v[188:191], v[248:251]
	v_mfma_f32_16x16x32_bf16 v[124:127], v[92:95], v[188:191], v[124:127]
	s_waitcnt vmcnt(8)
	ds_read_b128 v[180:183], v212 offset:24576
	global_load_dwordx4 v[80:83], v142, s[84:85] offset:0
	s_waitcnt lgkmcnt(4)
	v_mfma_f32_16x16x32_bf16 v[0:3], v[96:99], v[192:195], v[0:3]
	v_mfma_f32_16x16x32_bf16 v[32:35], v[164:167], v[192:195], v[32:35]
	v_mfma_f32_16x16x32_bf16 v[144:147], v[168:171], v[192:195], v[144:147]
	v_mfma_f32_16x16x32_bf16 v[252:255], v[172:175], v[192:195], v[252:255]
	ds_read_b128 v[188:191], v212 offset:26624
	global_load_dwordx4 v[84:87], v150, s[84:85] offset:0
	s_waitcnt lgkmcnt(4)
	v_mfma_f32_16x16x32_bf16 v[4:7], v[96:99], v[196:199], v[4:7]
	v_mfma_f32_16x16x32_bf16 v[36:39], v[164:167], v[196:199], v[36:39]
	v_mfma_f32_16x16x32_bf16 v[184:187], v[168:171], v[196:199], v[184:187]
	v_mfma_f32_16x16x32_bf16 v[100:103], v[172:175], v[196:199], v[100:103]
	ds_read_b128 v[192:195], v212 offset:28672
	global_load_dwordx4 v[88:91], v142, s[92:93] offset:0
	s_waitcnt lgkmcnt(4)
	v_mfma_f32_16x16x32_bf16 v[8:11], v[96:99], v[160:163], v[8:11]
	v_mfma_f32_16x16x32_bf16 v[40:43], v[164:167], v[160:163], v[40:43]
	v_mfma_f32_16x16x32_bf16 v[204:207], v[168:171], v[160:163], v[204:207]
	v_mfma_f32_16x16x32_bf16 v[104:107], v[172:175], v[160:163], v[104:107]
	ds_read_b128 v[196:199], v212 offset:30720
	global_load_dwordx4 v[92:95], v150, s[92:93] offset:0
	s_waitcnt lgkmcnt(4)
	v_mfma_f32_16x16x32_bf16 v[12:15], v[96:99], v[176:179], v[12:15]
	v_mfma_f32_16x16x32_bf16 v[44:47], v[164:167], v[176:179], v[44:47]
	v_mfma_f32_16x16x32_bf16 v[208:211], v[168:171], v[176:179], v[208:211]
	v_mfma_f32_16x16x32_bf16 v[108:111], v[172:175], v[176:179], v[108:111]
	ds_read_b128 v[160:163], v213 offset:16384
	s_waitcnt lgkmcnt(4)
	v_mfma_f32_16x16x32_bf16 v[16:19], v[96:99], v[180:183], v[16:19]
	v_mfma_f32_16x16x32_bf16 v[48:51], v[164:167], v[180:183], v[48:51]
	v_mfma_f32_16x16x32_bf16 v[232:235], v[168:171], v[180:183], v[232:235]
	v_mfma_f32_16x16x32_bf16 v[112:115], v[172:175], v[180:183], v[112:115]
	ds_read_b128 v[176:179], v213 offset:18432
	s_waitcnt lgkmcnt(4)
	v_mfma_f32_16x16x32_bf16 v[20:23], v[96:99], v[188:191], v[20:23]
	v_mfma_f32_16x16x32_bf16 v[52:55], v[164:167], v[188:191], v[52:55]
	v_mfma_f32_16x16x32_bf16 v[236:239], v[168:171], v[188:191], v[236:239]
	v_mfma_f32_16x16x32_bf16 v[116:119], v[172:175], v[188:191], v[116:119]
	ds_read_b128 v[180:183], v213 offset:20480
	s_waitcnt lgkmcnt(4)
	v_mfma_f32_16x16x32_bf16 v[24:27], v[96:99], v[192:195], v[24:27]
	v_mfma_f32_16x16x32_bf16 v[56:59], v[164:167], v[192:195], v[56:59]
	v_mfma_f32_16x16x32_bf16 v[240:243], v[168:171], v[192:195], v[240:243]
	v_mfma_f32_16x16x32_bf16 v[120:123], v[172:175], v[192:195], v[120:123]
	ds_read_b128 v[188:191], v213 offset:22528
	s_waitcnt lgkmcnt(4)
	v_mfma_f32_16x16x32_bf16 v[28:31], v[96:99], v[196:199], v[28:31]
	v_mfma_f32_16x16x32_bf16 v[60:63], v[164:167], v[196:199], v[60:63]
	v_mfma_f32_16x16x32_bf16 v[248:251], v[168:171], v[196:199], v[248:251]
	v_mfma_f32_16x16x32_bf16 v[124:127], v[172:175], v[196:199], v[124:127]
	s_waitcnt vmcnt(16)
	s_barrier
	s_waitcnt vmcnt(8)
	ds_read_b128 v[192:195], v213 offset:24576
	global_load_dwordx4 v[96:99], v142, s[84:85] offset:1024
	s_waitcnt lgkmcnt(4)
	v_mfma_f32_16x16x32_bf16 v[0:3], v[64:67], v[160:163], v[0:3]
	v_mfma_f32_16x16x32_bf16 v[32:35], v[68:71], v[160:163], v[32:35]
	v_mfma_f32_16x16x32_bf16 v[144:147], v[72:75], v[160:163], v[144:147]
	v_mfma_f32_16x16x32_bf16 v[252:255], v[76:79], v[160:163], v[252:255]
	ds_read_b128 v[196:199], v213 offset:26624
	global_load_dwordx4 v[164:167], v150, s[84:85] offset:1024
	s_waitcnt lgkmcnt(4)
	v_mfma_f32_16x16x32_bf16 v[4:7], v[64:67], v[176:179], v[4:7]
	v_mfma_f32_16x16x32_bf16 v[36:39], v[68:71], v[176:179], v[36:39]
	v_mfma_f32_16x16x32_bf16 v[184:187], v[72:75], v[176:179], v[184:187]
	v_mfma_f32_16x16x32_bf16 v[100:103], v[76:79], v[176:179], v[100:103]
	ds_read_b128 v[160:163], v213 offset:28672
	global_load_dwordx4 v[168:171], v142, s[92:93] offset:1024
	s_waitcnt lgkmcnt(4)
	v_mfma_f32_16x16x32_bf16 v[8:11], v[64:67], v[180:183], v[8:11]
	v_mfma_f32_16x16x32_bf16 v[40:43], v[68:71], v[180:183], v[40:43]
	v_mfma_f32_16x16x32_bf16 v[204:207], v[72:75], v[180:183], v[204:207]
	v_mfma_f32_16x16x32_bf16 v[104:107], v[76:79], v[180:183], v[104:107]
	ds_read_b128 v[176:179], v213 offset:30720
	global_load_dwordx4 v[172:175], v150, s[92:93] offset:1024
	s_add_u32 s84, s84, 0x800
	s_addc_u32 s85, s85, 0
	s_add_u32 s92, s92, 0x800
	s_addc_u32 s93, s93, 0
	s_waitcnt lgkmcnt(4)
	v_mfma_f32_16x16x32_bf16 v[12:15], v[64:67], v[188:191], v[12:15]
	v_mfma_f32_16x16x32_bf16 v[44:47], v[68:71], v[188:191], v[44:47]
	v_mfma_f32_16x16x32_bf16 v[208:211], v[72:75], v[188:191], v[208:211]
	v_mfma_f32_16x16x32_bf16 v[108:111], v[76:79], v[188:191], v[108:111]
	ds_read_b128 v[180:183], v212 offset:32768
	s_add_u32 m0, s1, 0
	s_nop 0
	global_load_lds_dwordx4 v151, s[86:87]
	s_waitcnt lgkmcnt(4)
	v_mfma_f32_16x16x32_bf16 v[16:19], v[64:67], v[192:195], v[16:19]
	v_mfma_f32_16x16x32_bf16 v[48:51], v[68:71], v[192:195], v[48:51]
	v_mfma_f32_16x16x32_bf16 v[232:235], v[72:75], v[192:195], v[232:235]
	v_mfma_f32_16x16x32_bf16 v[112:115], v[76:79], v[192:195], v[112:115]
	ds_read_b128 v[188:191], v212 offset:34816
	s_add_u32 m0, s1, 4096
	s_nop 0
	global_load_lds_dwordx4 v156, s[86:87]
	s_waitcnt lgkmcnt(4)
	v_mfma_f32_16x16x32_bf16 v[20:23], v[64:67], v[196:199], v[20:23]
	v_mfma_f32_16x16x32_bf16 v[52:55], v[68:71], v[196:199], v[52:55]
	v_mfma_f32_16x16x32_bf16 v[236:239], v[72:75], v[196:199], v[236:239]
	v_mfma_f32_16x16x32_bf16 v[116:119], v[76:79], v[196:199], v[116:119]
	ds_read_b128 v[192:195], v212 offset:36864
	s_add_u32 m0, s1, 8192
	s_nop 0
	global_load_lds_dwordx4 v158, s[86:87]
	s_waitcnt lgkmcnt(4)
	v_mfma_f32_16x16x32_bf16 v[24:27], v[64:67], v[160:163], v[24:27]
	v_mfma_f32_16x16x32_bf16 v[56:59], v[68:71], v[160:163], v[56:59]
	v_mfma_f32_16x16x32_bf16 v[240:243], v[72:75], v[160:163], v[240:243]
	v_mfma_f32_16x16x32_bf16 v[120:123], v[76:79], v[160:163], v[120:123]
	ds_read_b128 v[196:199], v212 offset:38912
	s_add_u32 m0, s1, 12288
	s_nop 0
	global_load_lds_dwordx4 v159, s[86:87]
	s_add_u32 s86, s86, 128
	s_addc_u32 s87, s87, 0
	s_waitcnt lgkmcnt(4)
	v_mfma_f32_16x16x32_bf16 v[28:31], v[64:67], v[176:179], v[28:31]
	v_mfma_f32_16x16x32_bf16 v[60:63], v[68:71], v[176:179], v[60:63]
	v_mfma_f32_16x16x32_bf16 v[248:251], v[72:75], v[176:179], v[248:251]
	v_mfma_f32_16x16x32_bf16 v[124:127], v[76:79], v[176:179], v[124:127]
	s_waitcnt vmcnt(8)
	ds_read_b128 v[160:163], v212 offset:40960
	global_load_dwordx4 v[64:67], v142, s[84:85] offset:0
	s_waitcnt lgkmcnt(4)
	v_mfma_f32_16x16x32_bf16 v[0:3], v[80:83], v[180:183], v[0:3]
	v_mfma_f32_16x16x32_bf16 v[32:35], v[84:87], v[180:183], v[32:35]
	v_mfma_f32_16x16x32_bf16 v[144:147], v[88:91], v[180:183], v[144:147]
	v_mfma_f32_16x16x32_bf16 v[252:255], v[92:95], v[180:183], v[252:255]
	ds_read_b128 v[176:179], v212 offset:43008
	global_load_dwordx4 v[68:71], v150, s[84:85] offset:0
	s_waitcnt lgkmcnt(4)
	v_mfma_f32_16x16x32_bf16 v[4:7], v[80:83], v[188:191], v[4:7]
	v_mfma_f32_16x16x32_bf16 v[36:39], v[84:87], v[188:191], v[36:39]
	v_mfma_f32_16x16x32_bf16 v[184:187], v[88:91], v[188:191], v[184:187]
	v_mfma_f32_16x16x32_bf16 v[100:103], v[92:95], v[188:191], v[100:103]
	ds_read_b128 v[180:183], v212 offset:45056
	global_load_dwordx4 v[72:75], v142, s[92:93] offset:0
	s_waitcnt lgkmcnt(4)
	v_mfma_f32_16x16x32_bf16 v[8:11], v[80:83], v[192:195], v[8:11]
	v_mfma_f32_16x16x32_bf16 v[40:43], v[84:87], v[192:195], v[40:43]
	v_mfma_f32_16x16x32_bf16 v[204:207], v[88:91], v[192:195], v[204:207]
	v_mfma_f32_16x16x32_bf16 v[104:107], v[92:95], v[192:195], v[104:107]
	ds_read_b128 v[188:191], v212 offset:47104
	global_load_dwordx4 v[76:79], v150, s[92:93] offset:0
	s_waitcnt lgkmcnt(4)
	v_mfma_f32_16x16x32_bf16 v[12:15], v[80:83], v[196:199], v[12:15]
	v_mfma_f32_16x16x32_bf16 v[44:47], v[84:87], v[196:199], v[44:47]
	v_mfma_f32_16x16x32_bf16 v[208:211], v[88:91], v[196:199], v[208:211]
	v_mfma_f32_16x16x32_bf16 v[108:111], v[92:95], v[196:199], v[108:111]
	ds_read_b128 v[192:195], v213 offset:32768
	s_waitcnt lgkmcnt(4)
	v_mfma_f32_16x16x32_bf16 v[16:19], v[80:83], v[160:163], v[16:19]
	v_mfma_f32_16x16x32_bf16 v[48:51], v[84:87], v[160:163], v[48:51]
	v_mfma_f32_16x16x32_bf16 v[232:235], v[88:91], v[160:163], v[232:235]
	v_mfma_f32_16x16x32_bf16 v[112:115], v[92:95], v[160:163], v[112:115]
	ds_read_b128 v[196:199], v213 offset:34816
	s_waitcnt lgkmcnt(4)
	v_mfma_f32_16x16x32_bf16 v[20:23], v[80:83], v[176:179], v[20:23]
	v_mfma_f32_16x16x32_bf16 v[52:55], v[84:87], v[176:179], v[52:55]
	v_mfma_f32_16x16x32_bf16 v[236:239], v[88:91], v[176:179], v[236:239]
	v_mfma_f32_16x16x32_bf16 v[116:119], v[92:95], v[176:179], v[116:119]
	ds_read_b128 v[160:163], v213 offset:36864
	s_waitcnt lgkmcnt(4)
	v_mfma_f32_16x16x32_bf16 v[24:27], v[80:83], v[180:183], v[24:27]
	v_mfma_f32_16x16x32_bf16 v[56:59], v[84:87], v[180:183], v[56:59]
	v_mfma_f32_16x16x32_bf16 v[240:243], v[88:91], v[180:183], v[240:243]
	v_mfma_f32_16x16x32_bf16 v[120:123], v[92:95], v[180:183], v[120:123]
	ds_read_b128 v[176:179], v213 offset:38912
	s_waitcnt lgkmcnt(4)
	v_mfma_f32_16x16x32_bf16 v[28:31], v[80:83], v[188:191], v[28:31]
	v_mfma_f32_16x16x32_bf16 v[60:63], v[84:87], v[188:191], v[60:63]
	v_mfma_f32_16x16x32_bf16 v[248:251], v[88:91], v[188:191], v[248:251]
	v_mfma_f32_16x16x32_bf16 v[124:127], v[92:95], v[188:191], v[124:127]
	s_waitcnt vmcnt(16)
	s_barrier
	s_waitcnt vmcnt(8)
	ds_read_b128 v[180:183], v213 offset:40960
	global_load_dwordx4 v[80:83], v142, s[84:85] offset:1024
	s_waitcnt lgkmcnt(4)
	v_mfma_f32_16x16x32_bf16 v[0:3], v[96:99], v[192:195], v[0:3]
	v_mfma_f32_16x16x32_bf16 v[32:35], v[164:167], v[192:195], v[32:35]
	v_mfma_f32_16x16x32_bf16 v[144:147], v[168:171], v[192:195], v[144:147]
	v_mfma_f32_16x16x32_bf16 v[252:255], v[172:175], v[192:195], v[252:255]
	ds_read_b128 v[188:191], v213 offset:43008
	global_load_dwordx4 v[84:87], v150, s[84:85] offset:1024
	s_waitcnt lgkmcnt(4)
	v_mfma_f32_16x16x32_bf16 v[4:7], v[96:99], v[196:199], v[4:7]
	v_mfma_f32_16x16x32_bf16 v[36:39], v[164:167], v[196:199], v[36:39]
	v_mfma_f32_16x16x32_bf16 v[184:187], v[168:171], v[196:199], v[184:187]
	v_mfma_f32_16x16x32_bf16 v[100:103], v[172:175], v[196:199], v[100:103]
	ds_read_b128 v[192:195], v213 offset:45056
	global_load_dwordx4 v[88:91], v142, s[92:93] offset:1024
	s_waitcnt lgkmcnt(4)
	v_mfma_f32_16x16x32_bf16 v[8:11], v[96:99], v[160:163], v[8:11]
	v_mfma_f32_16x16x32_bf16 v[40:43], v[164:167], v[160:163], v[40:43]
	v_mfma_f32_16x16x32_bf16 v[204:207], v[168:171], v[160:163], v[204:207]
	v_mfma_f32_16x16x32_bf16 v[104:107], v[172:175], v[160:163], v[104:107]
	ds_read_b128 v[196:199], v213 offset:47104
	global_load_dwordx4 v[92:95], v150, s[92:93] offset:1024
	s_add_u32 s84, s84, 0x800
	s_addc_u32 s85, s85, 0
	s_add_u32 s92, s92, 0x800
	s_addc_u32 s93, s93, 0
	s_waitcnt lgkmcnt(4)
	v_mfma_f32_16x16x32_bf16 v[12:15], v[96:99], v[176:179], v[12:15]
	v_mfma_f32_16x16x32_bf16 v[44:47], v[164:167], v[176:179], v[44:47]
	v_mfma_f32_16x16x32_bf16 v[208:211], v[168:171], v[176:179], v[208:211]
	v_mfma_f32_16x16x32_bf16 v[108:111], v[172:175], v[176:179], v[108:111]
	ds_read_b128 v[160:163], v212 offset:49152
	s_add_u32 m0, s1, 16384
	s_nop 0
	global_load_lds_dwordx4 v151, s[86:87]
	s_waitcnt lgkmcnt(4)
	v_mfma_f32_16x16x32_bf16 v[16:19], v[96:99], v[180:183], v[16:19]
	v_mfma_f32_16x16x32_bf16 v[48:51], v[164:167], v[180:183], v[48:51]
	v_mfma_f32_16x16x32_bf16 v[232:235], v[168:171], v[180:183], v[232:235]
	v_mfma_f32_16x16x32_bf16 v[112:115], v[172:175], v[180:183], v[112:115]
	ds_read_b128 v[176:179], v212 offset:51200
	s_add_u32 m0, s1, 20480
	s_nop 0
	global_load_lds_dwordx4 v156, s[86:87]
	s_waitcnt lgkmcnt(4)
	v_mfma_f32_16x16x32_bf16 v[20:23], v[96:99], v[188:191], v[20:23]
	v_mfma_f32_16x16x32_bf16 v[52:55], v[164:167], v[188:191], v[52:55]
	v_mfma_f32_16x16x32_bf16 v[236:239], v[168:171], v[188:191], v[236:239]
	v_mfma_f32_16x16x32_bf16 v[116:119], v[172:175], v[188:191], v[116:119]
	ds_read_b128 v[180:183], v212 offset:53248
	s_add_u32 m0, s1, 24576
	s_nop 0
	global_load_lds_dwordx4 v158, s[86:87]
	s_waitcnt lgkmcnt(4)
	v_mfma_f32_16x16x32_bf16 v[24:27], v[96:99], v[192:195], v[24:27]
	v_mfma_f32_16x16x32_bf16 v[56:59], v[164:167], v[192:195], v[56:59]
	v_mfma_f32_16x16x32_bf16 v[240:243], v[168:171], v[192:195], v[240:243]
	v_mfma_f32_16x16x32_bf16 v[120:123], v[172:175], v[192:195], v[120:123]
	ds_read_b128 v[188:191], v212 offset:55296
	s_add_u32 m0, s1, 28672
	s_nop 0
	global_load_lds_dwordx4 v159, s[86:87]
	s_add_u32 s86, s86, 128
	s_addc_u32 s87, s87, 0
	s_waitcnt lgkmcnt(4)
	v_mfma_f32_16x16x32_bf16 v[28:31], v[96:99], v[196:199], v[28:31]
	v_mfma_f32_16x16x32_bf16 v[60:63], v[164:167], v[196:199], v[60:63]
	v_mfma_f32_16x16x32_bf16 v[248:251], v[168:171], v[196:199], v[248:251]
	v_mfma_f32_16x16x32_bf16 v[124:127], v[172:175], v[196:199], v[124:127]
	s_waitcnt vmcnt(8)
	ds_read_b128 v[192:195], v212 offset:57344
	global_load_dwordx4 v[96:99], v142, s[84:85] offset:0
	s_waitcnt lgkmcnt(4)
	v_mfma_f32_16x16x32_bf16 v[0:3], v[64:67], v[160:163], v[0:3]
	v_mfma_f32_16x16x32_bf16 v[32:35], v[68:71], v[160:163], v[32:35]
	v_mfma_f32_16x16x32_bf16 v[144:147], v[72:75], v[160:163], v[144:147]
	v_mfma_f32_16x16x32_bf16 v[252:255], v[76:79], v[160:163], v[252:255]
	ds_read_b128 v[196:199], v212 offset:59392
	global_load_dwordx4 v[164:167], v150, s[84:85] offset:0
	s_waitcnt lgkmcnt(4)
	v_mfma_f32_16x16x32_bf16 v[4:7], v[64:67], v[176:179], v[4:7]
	v_mfma_f32_16x16x32_bf16 v[36:39], v[68:71], v[176:179], v[36:39]
	v_mfma_f32_16x16x32_bf16 v[184:187], v[72:75], v[176:179], v[184:187]
	v_mfma_f32_16x16x32_bf16 v[100:103], v[76:79], v[176:179], v[100:103]
	ds_read_b128 v[160:163], v212 offset:61440
	global_load_dwordx4 v[168:171], v142, s[92:93] offset:0
	s_waitcnt lgkmcnt(4)
	v_mfma_f32_16x16x32_bf16 v[8:11], v[64:67], v[180:183], v[8:11]
	v_mfma_f32_16x16x32_bf16 v[40:43], v[68:71], v[180:183], v[40:43]
	v_mfma_f32_16x16x32_bf16 v[204:207], v[72:75], v[180:183], v[204:207]
	v_mfma_f32_16x16x32_bf16 v[104:107], v[76:79], v[180:183], v[104:107]
	ds_read_b128 v[176:179], v212 offset:63488
	global_load_dwordx4 v[172:175], v150, s[92:93] offset:0
	s_waitcnt lgkmcnt(4)
	v_mfma_f32_16x16x32_bf16 v[12:15], v[64:67], v[188:191], v[12:15]
	v_mfma_f32_16x16x32_bf16 v[44:47], v[68:71], v[188:191], v[44:47]
	v_mfma_f32_16x16x32_bf16 v[208:211], v[72:75], v[188:191], v[208:211]
	v_mfma_f32_16x16x32_bf16 v[108:111], v[76:79], v[188:191], v[108:111]
	ds_read_b128 v[180:183], v213 offset:49152
	s_waitcnt lgkmcnt(4)
	v_mfma_f32_16x16x32_bf16 v[16:19], v[64:67], v[192:195], v[16:19]
	v_mfma_f32_16x16x32_bf16 v[48:51], v[68:71], v[192:195], v[48:51]
	v_mfma_f32_16x16x32_bf16 v[232:235], v[72:75], v[192:195], v[232:235]
	v_mfma_f32_16x16x32_bf16 v[112:115], v[76:79], v[192:195], v[112:115]
	ds_read_b128 v[188:191], v213 offset:51200
	s_waitcnt lgkmcnt(4)
	v_mfma_f32_16x16x32_bf16 v[20:23], v[64:67], v[196:199], v[20:23]
	v_mfma_f32_16x16x32_bf16 v[52:55], v[68:71], v[196:199], v[52:55]
	v_mfma_f32_16x16x32_bf16 v[236:239], v[72:75], v[196:199], v[236:239]
	v_mfma_f32_16x16x32_bf16 v[116:119], v[76:79], v[196:199], v[116:119]
	ds_read_b128 v[192:195], v213 offset:53248
	s_waitcnt lgkmcnt(4)
	v_mfma_f32_16x16x32_bf16 v[24:27], v[64:67], v[160:163], v[24:27]
	v_mfma_f32_16x16x32_bf16 v[56:59], v[68:71], v[160:163], v[56:59]
	v_mfma_f32_16x16x32_bf16 v[240:243], v[72:75], v[160:163], v[240:243]
	v_mfma_f32_16x16x32_bf16 v[120:123], v[76:79], v[160:163], v[120:123]
	ds_read_b128 v[196:199], v213 offset:55296
	s_waitcnt lgkmcnt(4)
	v_mfma_f32_16x16x32_bf16 v[28:31], v[64:67], v[176:179], v[28:31]
	v_mfma_f32_16x16x32_bf16 v[60:63], v[68:71], v[176:179], v[60:63]
	v_mfma_f32_16x16x32_bf16 v[248:251], v[72:75], v[176:179], v[248:251]
	v_mfma_f32_16x16x32_bf16 v[124:127], v[76:79], v[176:179], v[124:127]
	s_waitcnt vmcnt(16)
	s_barrier
	s_waitcnt vmcnt(8)
	ds_read_b128 v[160:163], v213 offset:57344
	global_load_dwordx4 v[64:67], v142, s[84:85] offset:1024
	s_waitcnt lgkmcnt(4)
	v_mfma_f32_16x16x32_bf16 v[0:3], v[80:83], v[180:183], v[0:3]
	v_mfma_f32_16x16x32_bf16 v[32:35], v[84:87], v[180:183], v[32:35]
	v_mfma_f32_16x16x32_bf16 v[144:147], v[88:91], v[180:183], v[144:147]
	v_mfma_f32_16x16x32_bf16 v[252:255], v[92:95], v[180:183], v[252:255]
	ds_read_b128 v[176:179], v213 offset:59392
	global_load_dwordx4 v[68:71], v150, s[84:85] offset:1024
	s_waitcnt lgkmcnt(4)
	v_mfma_f32_16x16x32_bf16 v[4:7], v[80:83], v[188:191], v[4:7]
	v_mfma_f32_16x16x32_bf16 v[36:39], v[84:87], v[188:191], v[36:39]
	v_mfma_f32_16x16x32_bf16 v[184:187], v[88:91], v[188:191], v[184:187]
	v_mfma_f32_16x16x32_bf16 v[100:103], v[92:95], v[188:191], v[100:103]
	ds_read_b128 v[180:183], v213 offset:61440
	global_load_dwordx4 v[72:75], v142, s[92:93] offset:1024
	s_waitcnt lgkmcnt(4)
	v_mfma_f32_16x16x32_bf16 v[8:11], v[80:83], v[192:195], v[8:11]
	v_mfma_f32_16x16x32_bf16 v[40:43], v[84:87], v[192:195], v[40:43]
	v_mfma_f32_16x16x32_bf16 v[204:207], v[88:91], v[192:195], v[204:207]
	v_mfma_f32_16x16x32_bf16 v[104:107], v[92:95], v[192:195], v[104:107]
	ds_read_b128 v[188:191], v213 offset:63488
	global_load_dwordx4 v[76:79], v150, s[92:93] offset:1024
	s_add_u32 s84, s84, 0x800
	s_addc_u32 s85, s85, 0
	s_add_u32 s92, s92, 0x800
	s_addc_u32 s93, s93, 0
	s_waitcnt lgkmcnt(4)
	v_mfma_f32_16x16x32_bf16 v[12:15], v[80:83], v[196:199], v[12:15]
	v_mfma_f32_16x16x32_bf16 v[44:47], v[84:87], v[196:199], v[44:47]
	v_mfma_f32_16x16x32_bf16 v[208:211], v[88:91], v[196:199], v[208:211]
	v_mfma_f32_16x16x32_bf16 v[108:111], v[92:95], v[196:199], v[108:111]
	ds_read_b128 v[192:195], v212 offset:0
	s_add_u32 m0, s1, 32768
	s_nop 0
	global_load_lds_dwordx4 v151, s[86:87]
	s_waitcnt lgkmcnt(4)
	v_mfma_f32_16x16x32_bf16 v[16:19], v[80:83], v[160:163], v[16:19]
	v_mfma_f32_16x16x32_bf16 v[48:51], v[84:87], v[160:163], v[48:51]
	v_mfma_f32_16x16x32_bf16 v[232:235], v[88:91], v[160:163], v[232:235]
	v_mfma_f32_16x16x32_bf16 v[112:115], v[92:95], v[160:163], v[112:115]
	ds_read_b128 v[196:199], v212 offset:2048
	s_add_u32 m0, s1, 36864
	s_nop 0
	global_load_lds_dwordx4 v156, s[86:87]
	s_waitcnt lgkmcnt(4)
	v_mfma_f32_16x16x32_bf16 v[20:23], v[80:83], v[176:179], v[20:23]
	v_mfma_f32_16x16x32_bf16 v[52:55], v[84:87], v[176:179], v[52:55]
	v_mfma_f32_16x16x32_bf16 v[236:239], v[88:91], v[176:179], v[236:239]
	v_mfma_f32_16x16x32_bf16 v[116:119], v[92:95], v[176:179], v[116:119]
	ds_read_b128 v[160:163], v212 offset:4096
	s_add_u32 m0, s1, 40960
	s_nop 0
	global_load_lds_dwordx4 v158, s[86:87]
	s_waitcnt lgkmcnt(4)
	v_mfma_f32_16x16x32_bf16 v[24:27], v[80:83], v[180:183], v[24:27]
	v_mfma_f32_16x16x32_bf16 v[56:59], v[84:87], v[180:183], v[56:59]
	v_mfma_f32_16x16x32_bf16 v[240:243], v[88:91], v[180:183], v[240:243]
	v_mfma_f32_16x16x32_bf16 v[120:123], v[92:95], v[180:183], v[120:123]
	ds_read_b128 v[176:179], v212 offset:6144
	s_add_u32 m0, s1, 45056
	s_nop 0
	global_load_lds_dwordx4 v159, s[86:87]
	s_add_u32 s86, s86, 128
	s_addc_u32 s87, s87, 0
	s_waitcnt lgkmcnt(4)
	v_mfma_f32_16x16x32_bf16 v[28:31], v[80:83], v[188:191], v[28:31]
	v_mfma_f32_16x16x32_bf16 v[60:63], v[84:87], v[188:191], v[60:63]
	v_mfma_f32_16x16x32_bf16 v[248:251], v[88:91], v[188:191], v[248:251]
	v_mfma_f32_16x16x32_bf16 v[124:127], v[92:95], v[188:191], v[124:127]
	s_waitcnt vmcnt(8)
	ds_read_b128 v[180:183], v212 offset:8192
	global_load_dwordx4 v[80:83], v142, s[84:85] offset:0
	s_waitcnt lgkmcnt(4)
	v_mfma_f32_16x16x32_bf16 v[0:3], v[96:99], v[192:195], v[0:3]
	v_mfma_f32_16x16x32_bf16 v[32:35], v[164:167], v[192:195], v[32:35]
	v_mfma_f32_16x16x32_bf16 v[144:147], v[168:171], v[192:195], v[144:147]
	v_mfma_f32_16x16x32_bf16 v[252:255], v[172:175], v[192:195], v[252:255]
	ds_read_b128 v[188:191], v212 offset:10240
	global_load_dwordx4 v[84:87], v150, s[84:85] offset:0
	s_waitcnt lgkmcnt(4)
	v_mfma_f32_16x16x32_bf16 v[4:7], v[96:99], v[196:199], v[4:7]
	v_mfma_f32_16x16x32_bf16 v[36:39], v[164:167], v[196:199], v[36:39]
	v_mfma_f32_16x16x32_bf16 v[184:187], v[168:171], v[196:199], v[184:187]
	v_mfma_f32_16x16x32_bf16 v[100:103], v[172:175], v[196:199], v[100:103]
	ds_read_b128 v[192:195], v212 offset:12288
	global_load_dwordx4 v[88:91], v142, s[92:93] offset:0
	s_waitcnt lgkmcnt(4)
	v_mfma_f32_16x16x32_bf16 v[8:11], v[96:99], v[160:163], v[8:11]
	v_mfma_f32_16x16x32_bf16 v[40:43], v[164:167], v[160:163], v[40:43]
	v_mfma_f32_16x16x32_bf16 v[204:207], v[168:171], v[160:163], v[204:207]
	v_mfma_f32_16x16x32_bf16 v[104:107], v[172:175], v[160:163], v[104:107]
	ds_read_b128 v[196:199], v212 offset:14336
	global_load_dwordx4 v[92:95], v150, s[92:93] offset:0
	s_waitcnt lgkmcnt(4)
	v_mfma_f32_16x16x32_bf16 v[12:15], v[96:99], v[176:179], v[12:15]
	v_mfma_f32_16x16x32_bf16 v[44:47], v[164:167], v[176:179], v[44:47]
	v_mfma_f32_16x16x32_bf16 v[208:211], v[168:171], v[176:179], v[208:211]
	v_mfma_f32_16x16x32_bf16 v[108:111], v[172:175], v[176:179], v[108:111]
	ds_read_b128 v[160:163], v213 offset:0
	s_waitcnt lgkmcnt(4)
	v_mfma_f32_16x16x32_bf16 v[16:19], v[96:99], v[180:183], v[16:19]
	v_mfma_f32_16x16x32_bf16 v[48:51], v[164:167], v[180:183], v[48:51]
	v_mfma_f32_16x16x32_bf16 v[232:235], v[168:171], v[180:183], v[232:235]
	v_mfma_f32_16x16x32_bf16 v[112:115], v[172:175], v[180:183], v[112:115]
	ds_read_b128 v[176:179], v213 offset:2048
	s_waitcnt lgkmcnt(4)
	v_mfma_f32_16x16x32_bf16 v[20:23], v[96:99], v[188:191], v[20:23]
	v_mfma_f32_16x16x32_bf16 v[52:55], v[164:167], v[188:191], v[52:55]
	v_mfma_f32_16x16x32_bf16 v[236:239], v[168:171], v[188:191], v[236:239]
	v_mfma_f32_16x16x32_bf16 v[116:119], v[172:175], v[188:191], v[116:119]
	ds_read_b128 v[180:183], v213 offset:4096
	s_waitcnt lgkmcnt(4)
	v_mfma_f32_16x16x32_bf16 v[24:27], v[96:99], v[192:195], v[24:27]
	v_mfma_f32_16x16x32_bf16 v[56:59], v[164:167], v[192:195], v[56:59]
	v_mfma_f32_16x16x32_bf16 v[240:243], v[168:171], v[192:195], v[240:243]
	v_mfma_f32_16x16x32_bf16 v[120:123], v[172:175], v[192:195], v[120:123]
	ds_read_b128 v[188:191], v213 offset:6144
	s_waitcnt lgkmcnt(4)
	v_mfma_f32_16x16x32_bf16 v[28:31], v[96:99], v[196:199], v[28:31]
	v_mfma_f32_16x16x32_bf16 v[60:63], v[164:167], v[196:199], v[60:63]
	v_mfma_f32_16x16x32_bf16 v[248:251], v[168:171], v[196:199], v[248:251]
	v_mfma_f32_16x16x32_bf16 v[124:127], v[172:175], v[196:199], v[124:127]
	s_waitcnt vmcnt(16)
	s_barrier
	s_waitcnt vmcnt(8)
	ds_read_b128 v[192:195], v213 offset:8192
	global_load_dwordx4 v[96:99], v142, s[84:85] offset:1024
	s_waitcnt lgkmcnt(4)
	v_mfma_f32_16x16x32_bf16 v[0:3], v[64:67], v[160:163], v[0:3]
	v_mfma_f32_16x16x32_bf16 v[32:35], v[68:71], v[160:163], v[32:35]
	v_mfma_f32_16x16x32_bf16 v[144:147], v[72:75], v[160:163], v[144:147]
	v_mfma_f32_16x16x32_bf16 v[252:255], v[76:79], v[160:163], v[252:255]
	ds_read_b128 v[196:199], v213 offset:10240
	global_load_dwordx4 v[164:167], v150, s[84:85] offset:1024
	s_waitcnt lgkmcnt(4)
	v_mfma_f32_16x16x32_bf16 v[4:7], v[64:67], v[176:179], v[4:7]
	v_mfma_f32_16x16x32_bf16 v[36:39], v[68:71], v[176:179], v[36:39]
	v_mfma_f32_16x16x32_bf16 v[184:187], v[72:75], v[176:179], v[184:187]
	v_mfma_f32_16x16x32_bf16 v[100:103], v[76:79], v[176:179], v[100:103]
	ds_read_b128 v[160:163], v213 offset:12288
	global_load_dwordx4 v[168:171], v142, s[92:93] offset:1024
	s_waitcnt lgkmcnt(4)
	v_mfma_f32_16x16x32_bf16 v[8:11], v[64:67], v[180:183], v[8:11]
	v_mfma_f32_16x16x32_bf16 v[40:43], v[68:71], v[180:183], v[40:43]
	v_mfma_f32_16x16x32_bf16 v[204:207], v[72:75], v[180:183], v[204:207]
	v_mfma_f32_16x16x32_bf16 v[104:107], v[76:79], v[180:183], v[104:107]
	ds_read_b128 v[176:179], v213 offset:14336
	global_load_dwordx4 v[172:175], v150, s[92:93] offset:1024
	s_add_u32 s84, s84, 0x800
	s_addc_u32 s85, s85, 0
	s_add_u32 s92, s92, 0x800
	s_addc_u32 s93, s93, 0
	s_waitcnt lgkmcnt(4)
	v_mfma_f32_16x16x32_bf16 v[12:15], v[64:67], v[188:191], v[12:15]
	v_mfma_f32_16x16x32_bf16 v[44:47], v[68:71], v[188:191], v[44:47]
	v_mfma_f32_16x16x32_bf16 v[208:211], v[72:75], v[188:191], v[208:211]
	v_mfma_f32_16x16x32_bf16 v[108:111], v[76:79], v[188:191], v[108:111]
	ds_read_b128 v[180:183], v212 offset:16384
	s_add_u32 m0, s1, 49152
	s_nop 0
	global_load_lds_dwordx4 v151, s[86:87]
	s_waitcnt lgkmcnt(4)
	v_mfma_f32_16x16x32_bf16 v[16:19], v[64:67], v[192:195], v[16:19]
	v_mfma_f32_16x16x32_bf16 v[48:51], v[68:71], v[192:195], v[48:51]
	v_mfma_f32_16x16x32_bf16 v[232:235], v[72:75], v[192:195], v[232:235]
	v_mfma_f32_16x16x32_bf16 v[112:115], v[76:79], v[192:195], v[112:115]
	ds_read_b128 v[188:191], v212 offset:18432
	s_add_u32 m0, s1, 53248
	s_nop 0
	global_load_lds_dwordx4 v156, s[86:87]
	s_waitcnt lgkmcnt(4)
	v_mfma_f32_16x16x32_bf16 v[20:23], v[64:67], v[196:199], v[20:23]
	v_mfma_f32_16x16x32_bf16 v[52:55], v[68:71], v[196:199], v[52:55]
	v_mfma_f32_16x16x32_bf16 v[236:239], v[72:75], v[196:199], v[236:239]
	v_mfma_f32_16x16x32_bf16 v[116:119], v[76:79], v[196:199], v[116:119]
	ds_read_b128 v[192:195], v212 offset:20480
	s_add_u32 m0, s1, 57344
	s_nop 0
	global_load_lds_dwordx4 v158, s[86:87]
	s_waitcnt lgkmcnt(4)
	v_mfma_f32_16x16x32_bf16 v[24:27], v[64:67], v[160:163], v[24:27]
	v_mfma_f32_16x16x32_bf16 v[56:59], v[68:71], v[160:163], v[56:59]
	v_mfma_f32_16x16x32_bf16 v[240:243], v[72:75], v[160:163], v[240:243]
	v_mfma_f32_16x16x32_bf16 v[120:123], v[76:79], v[160:163], v[120:123]
	ds_read_b128 v[196:199], v212 offset:22528
	s_add_u32 m0, s1, 61440
	s_nop 0
	global_load_lds_dwordx4 v159, s[86:87]
	s_add_u32 s86, s86, 128
	s_addc_u32 s87, s87, 0
	s_waitcnt lgkmcnt(4)
	v_mfma_f32_16x16x32_bf16 v[28:31], v[64:67], v[176:179], v[28:31]
	v_mfma_f32_16x16x32_bf16 v[60:63], v[68:71], v[176:179], v[60:63]
	v_mfma_f32_16x16x32_bf16 v[248:251], v[72:75], v[176:179], v[248:251]
	v_mfma_f32_16x16x32_bf16 v[124:127], v[76:79], v[176:179], v[124:127]
	s_waitcnt vmcnt(8)
	ds_read_b128 v[160:163], v212 offset:24576
	global_load_dwordx4 v[64:67], v142, s[84:85] offset:0
	s_waitcnt lgkmcnt(4)
	v_mfma_f32_16x16x32_bf16 v[0:3], v[80:83], v[180:183], v[0:3]
	v_mfma_f32_16x16x32_bf16 v[32:35], v[84:87], v[180:183], v[32:35]
	v_mfma_f32_16x16x32_bf16 v[144:147], v[88:91], v[180:183], v[144:147]
	v_mfma_f32_16x16x32_bf16 v[252:255], v[92:95], v[180:183], v[252:255]
	ds_read_b128 v[176:179], v212 offset:26624
	global_load_dwordx4 v[68:71], v150, s[84:85] offset:0
	s_waitcnt lgkmcnt(4)
	v_mfma_f32_16x16x32_bf16 v[4:7], v[80:83], v[188:191], v[4:7]
	v_mfma_f32_16x16x32_bf16 v[36:39], v[84:87], v[188:191], v[36:39]
	v_mfma_f32_16x16x32_bf16 v[184:187], v[88:91], v[188:191], v[184:187]
	v_mfma_f32_16x16x32_bf16 v[100:103], v[92:95], v[188:191], v[100:103]
	ds_read_b128 v[180:183], v212 offset:28672
	global_load_dwordx4 v[72:75], v142, s[92:93] offset:0
	s_waitcnt lgkmcnt(4)
	v_mfma_f32_16x16x32_bf16 v[8:11], v[80:83], v[192:195], v[8:11]
	v_mfma_f32_16x16x32_bf16 v[40:43], v[84:87], v[192:195], v[40:43]
	v_mfma_f32_16x16x32_bf16 v[204:207], v[88:91], v[192:195], v[204:207]
	v_mfma_f32_16x16x32_bf16 v[104:107], v[92:95], v[192:195], v[104:107]
	ds_read_b128 v[188:191], v212 offset:30720
	global_load_dwordx4 v[76:79], v150, s[92:93] offset:0
	s_waitcnt lgkmcnt(4)
	v_mfma_f32_16x16x32_bf16 v[12:15], v[80:83], v[196:199], v[12:15]
	v_mfma_f32_16x16x32_bf16 v[44:47], v[84:87], v[196:199], v[44:47]
	v_mfma_f32_16x16x32_bf16 v[208:211], v[88:91], v[196:199], v[208:211]
	v_mfma_f32_16x16x32_bf16 v[108:111], v[92:95], v[196:199], v[108:111]
	ds_read_b128 v[192:195], v213 offset:16384
	s_waitcnt lgkmcnt(4)
	v_mfma_f32_16x16x32_bf16 v[16:19], v[80:83], v[160:163], v[16:19]
	v_mfma_f32_16x16x32_bf16 v[48:51], v[84:87], v[160:163], v[48:51]
	v_mfma_f32_16x16x32_bf16 v[232:235], v[88:91], v[160:163], v[232:235]
	v_mfma_f32_16x16x32_bf16 v[112:115], v[92:95], v[160:163], v[112:115]
	ds_read_b128 v[196:199], v213 offset:18432
	s_waitcnt lgkmcnt(4)
	v_mfma_f32_16x16x32_bf16 v[20:23], v[80:83], v[176:179], v[20:23]
	v_mfma_f32_16x16x32_bf16 v[52:55], v[84:87], v[176:179], v[52:55]
	v_mfma_f32_16x16x32_bf16 v[236:239], v[88:91], v[176:179], v[236:239]
	v_mfma_f32_16x16x32_bf16 v[116:119], v[92:95], v[176:179], v[116:119]
	ds_read_b128 v[160:163], v213 offset:20480
	s_waitcnt lgkmcnt(4)
	v_mfma_f32_16x16x32_bf16 v[24:27], v[80:83], v[180:183], v[24:27]
	v_mfma_f32_16x16x32_bf16 v[56:59], v[84:87], v[180:183], v[56:59]
	v_mfma_f32_16x16x32_bf16 v[240:243], v[88:91], v[180:183], v[240:243]
	v_mfma_f32_16x16x32_bf16 v[120:123], v[92:95], v[180:183], v[120:123]
	ds_read_b128 v[176:179], v213 offset:22528
	s_waitcnt lgkmcnt(4)
	v_mfma_f32_16x16x32_bf16 v[28:31], v[80:83], v[188:191], v[28:31]
	v_mfma_f32_16x16x32_bf16 v[60:63], v[84:87], v[188:191], v[60:63]
	v_mfma_f32_16x16x32_bf16 v[248:251], v[88:91], v[188:191], v[248:251]
	v_mfma_f32_16x16x32_bf16 v[124:127], v[92:95], v[188:191], v[124:127]
	s_waitcnt vmcnt(16)
	s_barrier
	s_waitcnt vmcnt(8)
	ds_read_b128 v[180:183], v213 offset:24576
	global_load_dwordx4 v[80:83], v142, s[84:85] offset:1024
	s_waitcnt lgkmcnt(4)
	v_mfma_f32_16x16x32_bf16 v[0:3], v[96:99], v[192:195], v[0:3]
	v_mfma_f32_16x16x32_bf16 v[32:35], v[164:167], v[192:195], v[32:35]
	v_mfma_f32_16x16x32_bf16 v[144:147], v[168:171], v[192:195], v[144:147]
	v_mfma_f32_16x16x32_bf16 v[252:255], v[172:175], v[192:195], v[252:255]
	ds_read_b128 v[188:191], v213 offset:26624
	global_load_dwordx4 v[84:87], v150, s[84:85] offset:1024
	s_waitcnt lgkmcnt(4)
	v_mfma_f32_16x16x32_bf16 v[4:7], v[96:99], v[196:199], v[4:7]
	v_mfma_f32_16x16x32_bf16 v[36:39], v[164:167], v[196:199], v[36:39]
	v_mfma_f32_16x16x32_bf16 v[184:187], v[168:171], v[196:199], v[184:187]
	v_mfma_f32_16x16x32_bf16 v[100:103], v[172:175], v[196:199], v[100:103]
	ds_read_b128 v[192:195], v213 offset:28672
	global_load_dwordx4 v[88:91], v142, s[92:93] offset:1024
	s_waitcnt lgkmcnt(4)
	v_mfma_f32_16x16x32_bf16 v[8:11], v[96:99], v[160:163], v[8:11]
	v_mfma_f32_16x16x32_bf16 v[40:43], v[164:167], v[160:163], v[40:43]
	v_mfma_f32_16x16x32_bf16 v[204:207], v[168:171], v[160:163], v[204:207]
	v_mfma_f32_16x16x32_bf16 v[104:107], v[172:175], v[160:163], v[104:107]
	ds_read_b128 v[196:199], v213 offset:30720
	global_load_dwordx4 v[92:95], v150, s[92:93] offset:1024
	s_add_u32 s84, s84, 0x800
	s_addc_u32 s85, s85, 0
	s_add_u32 s92, s92, 0x800
	s_addc_u32 s93, s93, 0
	s_waitcnt lgkmcnt(4)
	v_mfma_f32_16x16x32_bf16 v[12:15], v[96:99], v[176:179], v[12:15]
	v_mfma_f32_16x16x32_bf16 v[44:47], v[164:167], v[176:179], v[44:47]
	v_mfma_f32_16x16x32_bf16 v[208:211], v[168:171], v[176:179], v[208:211]
	v_mfma_f32_16x16x32_bf16 v[108:111], v[172:175], v[176:179], v[108:111]
	ds_read_b128 v[160:163], v212 offset:32768
	s_add_u32 m0, s1, 0
	s_nop 0
	global_load_lds_dwordx4 v151, s[86:87]
	s_waitcnt lgkmcnt(4)
	v_mfma_f32_16x16x32_bf16 v[16:19], v[96:99], v[180:183], v[16:19]
	v_mfma_f32_16x16x32_bf16 v[48:51], v[164:167], v[180:183], v[48:51]
	v_mfma_f32_16x16x32_bf16 v[232:235], v[168:171], v[180:183], v[232:235]
	v_mfma_f32_16x16x32_bf16 v[112:115], v[172:175], v[180:183], v[112:115]
	ds_read_b128 v[176:179], v212 offset:34816
	s_add_u32 m0, s1, 4096
	s_nop 0
	global_load_lds_dwordx4 v156, s[86:87]
	s_waitcnt lgkmcnt(4)
	v_mfma_f32_16x16x32_bf16 v[20:23], v[96:99], v[188:191], v[20:23]
	v_mfma_f32_16x16x32_bf16 v[52:55], v[164:167], v[188:191], v[52:55]
	v_mfma_f32_16x16x32_bf16 v[236:239], v[168:171], v[188:191], v[236:239]
	v_mfma_f32_16x16x32_bf16 v[116:119], v[172:175], v[188:191], v[116:119]
	ds_read_b128 v[180:183], v212 offset:36864
	s_add_u32 m0, s1, 8192
	s_nop 0
	global_load_lds_dwordx4 v158, s[86:87]
	s_waitcnt lgkmcnt(4)
	v_mfma_f32_16x16x32_bf16 v[24:27], v[96:99], v[192:195], v[24:27]
	v_mfma_f32_16x16x32_bf16 v[56:59], v[164:167], v[192:195], v[56:59]
	v_mfma_f32_16x16x32_bf16 v[240:243], v[168:171], v[192:195], v[240:243]
	v_mfma_f32_16x16x32_bf16 v[120:123], v[172:175], v[192:195], v[120:123]
	ds_read_b128 v[188:191], v212 offset:38912
	s_add_u32 m0, s1, 12288
	s_nop 0
	global_load_lds_dwordx4 v159, s[86:87]
	s_add_u32 s86, s86, 128
	s_addc_u32 s87, s87, 0
	s_waitcnt lgkmcnt(4)
	v_mfma_f32_16x16x32_bf16 v[28:31], v[96:99], v[196:199], v[28:31]
	v_mfma_f32_16x16x32_bf16 v[60:63], v[164:167], v[196:199], v[60:63]
	v_mfma_f32_16x16x32_bf16 v[248:251], v[168:171], v[196:199], v[248:251]
	v_mfma_f32_16x16x32_bf16 v[124:127], v[172:175], v[196:199], v[124:127]
	s_waitcnt vmcnt(8)
	ds_read_b128 v[192:195], v212 offset:40960
	global_load_dwordx4 v[96:99], v142, s[84:85] offset:0
	s_waitcnt lgkmcnt(4)
	v_mfma_f32_16x16x32_bf16 v[0:3], v[64:67], v[160:163], v[0:3]
	v_mfma_f32_16x16x32_bf16 v[32:35], v[68:71], v[160:163], v[32:35]
	v_mfma_f32_16x16x32_bf16 v[144:147], v[72:75], v[160:163], v[144:147]
	v_mfma_f32_16x16x32_bf16 v[252:255], v[76:79], v[160:163], v[252:255]
	ds_read_b128 v[196:199], v212 offset:43008
	global_load_dwordx4 v[164:167], v150, s[84:85] offset:0
	s_waitcnt lgkmcnt(4)
	v_mfma_f32_16x16x32_bf16 v[4:7], v[64:67], v[176:179], v[4:7]
	v_mfma_f32_16x16x32_bf16 v[36:39], v[68:71], v[176:179], v[36:39]
	v_mfma_f32_16x16x32_bf16 v[184:187], v[72:75], v[176:179], v[184:187]
	v_mfma_f32_16x16x32_bf16 v[100:103], v[76:79], v[176:179], v[100:103]
	ds_read_b128 v[160:163], v212 offset:45056
	global_load_dwordx4 v[168:171], v142, s[92:93] offset:0
	s_waitcnt lgkmcnt(4)
	v_mfma_f32_16x16x32_bf16 v[8:11], v[64:67], v[180:183], v[8:11]
	v_mfma_f32_16x16x32_bf16 v[40:43], v[68:71], v[180:183], v[40:43]
	v_mfma_f32_16x16x32_bf16 v[204:207], v[72:75], v[180:183], v[204:207]
	v_mfma_f32_16x16x32_bf16 v[104:107], v[76:79], v[180:183], v[104:107]
	ds_read_b128 v[176:179], v212 offset:47104
	global_load_dwordx4 v[172:175], v150, s[92:93] offset:0
	s_waitcnt lgkmcnt(4)
	v_mfma_f32_16x16x32_bf16 v[12:15], v[64:67], v[188:191], v[12:15]
	v_mfma_f32_16x16x32_bf16 v[44:47], v[68:71], v[188:191], v[44:47]
	v_mfma_f32_16x16x32_bf16 v[208:211], v[72:75], v[188:191], v[208:211]
	v_mfma_f32_16x16x32_bf16 v[108:111], v[76:79], v[188:191], v[108:111]
	ds_read_b128 v[180:183], v213 offset:32768
	s_waitcnt lgkmcnt(4)
	v_mfma_f32_16x16x32_bf16 v[16:19], v[64:67], v[192:195], v[16:19]
	v_mfma_f32_16x16x32_bf16 v[48:51], v[68:71], v[192:195], v[48:51]
	v_mfma_f32_16x16x32_bf16 v[232:235], v[72:75], v[192:195], v[232:235]
	v_mfma_f32_16x16x32_bf16 v[112:115], v[76:79], v[192:195], v[112:115]
	ds_read_b128 v[188:191], v213 offset:34816
	s_waitcnt lgkmcnt(4)
	v_mfma_f32_16x16x32_bf16 v[20:23], v[64:67], v[196:199], v[20:23]
	v_mfma_f32_16x16x32_bf16 v[52:55], v[68:71], v[196:199], v[52:55]
	v_mfma_f32_16x16x32_bf16 v[236:239], v[72:75], v[196:199], v[236:239]
	v_mfma_f32_16x16x32_bf16 v[116:119], v[76:79], v[196:199], v[116:119]
	ds_read_b128 v[192:195], v213 offset:36864
	s_waitcnt lgkmcnt(4)
	v_mfma_f32_16x16x32_bf16 v[24:27], v[64:67], v[160:163], v[24:27]
	v_mfma_f32_16x16x32_bf16 v[56:59], v[68:71], v[160:163], v[56:59]
	v_mfma_f32_16x16x32_bf16 v[240:243], v[72:75], v[160:163], v[240:243]
	v_mfma_f32_16x16x32_bf16 v[120:123], v[76:79], v[160:163], v[120:123]
	ds_read_b128 v[196:199], v213 offset:38912
	s_waitcnt lgkmcnt(4)
	v_mfma_f32_16x16x32_bf16 v[28:31], v[64:67], v[176:179], v[28:31]
	v_mfma_f32_16x16x32_bf16 v[60:63], v[68:71], v[176:179], v[60:63]
	v_mfma_f32_16x16x32_bf16 v[248:251], v[72:75], v[176:179], v[248:251]
	v_mfma_f32_16x16x32_bf16 v[124:127], v[76:79], v[176:179], v[124:127]
	s_waitcnt vmcnt(16)
	s_barrier
	s_waitcnt vmcnt(8)
	ds_read_b128 v[160:163], v213 offset:40960
	global_load_dwordx4 v[64:67], v142, s[84:85] offset:1024
	s_waitcnt lgkmcnt(4)
	v_mfma_f32_16x16x32_bf16 v[0:3], v[80:83], v[180:183], v[0:3]
	v_mfma_f32_16x16x32_bf16 v[32:35], v[84:87], v[180:183], v[32:35]
	v_mfma_f32_16x16x32_bf16 v[144:147], v[88:91], v[180:183], v[144:147]
	v_mfma_f32_16x16x32_bf16 v[252:255], v[92:95], v[180:183], v[252:255]
	ds_read_b128 v[176:179], v213 offset:43008
	global_load_dwordx4 v[68:71], v150, s[84:85] offset:1024
	s_waitcnt lgkmcnt(4)
	v_mfma_f32_16x16x32_bf16 v[4:7], v[80:83], v[188:191], v[4:7]
	v_mfma_f32_16x16x32_bf16 v[36:39], v[84:87], v[188:191], v[36:39]
	v_mfma_f32_16x16x32_bf16 v[184:187], v[88:91], v[188:191], v[184:187]
	v_mfma_f32_16x16x32_bf16 v[100:103], v[92:95], v[188:191], v[100:103]
	ds_read_b128 v[180:183], v213 offset:45056
	global_load_dwordx4 v[72:75], v142, s[92:93] offset:1024
	s_waitcnt lgkmcnt(4)
	v_mfma_f32_16x16x32_bf16 v[8:11], v[80:83], v[192:195], v[8:11]
	v_mfma_f32_16x16x32_bf16 v[40:43], v[84:87], v[192:195], v[40:43]
	v_mfma_f32_16x16x32_bf16 v[204:207], v[88:91], v[192:195], v[204:207]
	v_mfma_f32_16x16x32_bf16 v[104:107], v[92:95], v[192:195], v[104:107]
	ds_read_b128 v[188:191], v213 offset:47104
	global_load_dwordx4 v[76:79], v150, s[92:93] offset:1024
	s_add_u32 s84, s84, 0x800
	s_addc_u32 s85, s85, 0
	s_add_u32 s92, s92, 0x800
	s_addc_u32 s93, s93, 0
	s_waitcnt lgkmcnt(4)
	v_mfma_f32_16x16x32_bf16 v[12:15], v[80:83], v[196:199], v[12:15]
	v_mfma_f32_16x16x32_bf16 v[44:47], v[84:87], v[196:199], v[44:47]
	v_mfma_f32_16x16x32_bf16 v[208:211], v[88:91], v[196:199], v[208:211]
	v_mfma_f32_16x16x32_bf16 v[108:111], v[92:95], v[196:199], v[108:111]
	ds_read_b128 v[192:195], v212 offset:49152
	s_add_u32 m0, s1, 16384
	s_nop 0
	global_load_lds_dwordx4 v151, s[86:87]
	s_waitcnt lgkmcnt(4)
	v_mfma_f32_16x16x32_bf16 v[16:19], v[80:83], v[160:163], v[16:19]
	v_mfma_f32_16x16x32_bf16 v[48:51], v[84:87], v[160:163], v[48:51]
	v_mfma_f32_16x16x32_bf16 v[232:235], v[88:91], v[160:163], v[232:235]
	v_mfma_f32_16x16x32_bf16 v[112:115], v[92:95], v[160:163], v[112:115]
	ds_read_b128 v[196:199], v212 offset:51200
	s_add_u32 m0, s1, 20480
	s_nop 0
	global_load_lds_dwordx4 v156, s[86:87]
	s_waitcnt lgkmcnt(4)
	v_mfma_f32_16x16x32_bf16 v[20:23], v[80:83], v[176:179], v[20:23]
	v_mfma_f32_16x16x32_bf16 v[52:55], v[84:87], v[176:179], v[52:55]
	v_mfma_f32_16x16x32_bf16 v[236:239], v[88:91], v[176:179], v[236:239]
	v_mfma_f32_16x16x32_bf16 v[116:119], v[92:95], v[176:179], v[116:119]
	ds_read_b128 v[160:163], v212 offset:53248
	s_add_u32 m0, s1, 24576
	s_nop 0
	global_load_lds_dwordx4 v158, s[86:87]
	s_waitcnt lgkmcnt(4)
	v_mfma_f32_16x16x32_bf16 v[24:27], v[80:83], v[180:183], v[24:27]
	v_mfma_f32_16x16x32_bf16 v[56:59], v[84:87], v[180:183], v[56:59]
	v_mfma_f32_16x16x32_bf16 v[240:243], v[88:91], v[180:183], v[240:243]
	v_mfma_f32_16x16x32_bf16 v[120:123], v[92:95], v[180:183], v[120:123]
	ds_read_b128 v[176:179], v212 offset:55296
	s_add_u32 m0, s1, 28672
	s_nop 0
	global_load_lds_dwordx4 v159, s[86:87]
	s_add_u32 s86, s86, 128
	s_addc_u32 s87, s87, 0
	s_waitcnt lgkmcnt(4)
	v_mfma_f32_16x16x32_bf16 v[28:31], v[80:83], v[188:191], v[28:31]
	v_mfma_f32_16x16x32_bf16 v[60:63], v[84:87], v[188:191], v[60:63]
	v_mfma_f32_16x16x32_bf16 v[248:251], v[88:91], v[188:191], v[248:251]
	v_mfma_f32_16x16x32_bf16 v[124:127], v[92:95], v[188:191], v[124:127]
	s_waitcnt vmcnt(8)
	ds_read_b128 v[180:183], v212 offset:57344
	global_load_dwordx4 v[80:83], v142, s[84:85] offset:0
	s_waitcnt lgkmcnt(4)
	v_mfma_f32_16x16x32_bf16 v[0:3], v[96:99], v[192:195], v[0:3]
	v_mfma_f32_16x16x32_bf16 v[32:35], v[164:167], v[192:195], v[32:35]
	v_mfma_f32_16x16x32_bf16 v[144:147], v[168:171], v[192:195], v[144:147]
	v_mfma_f32_16x16x32_bf16 v[252:255], v[172:175], v[192:195], v[252:255]
	ds_read_b128 v[188:191], v212 offset:59392
	global_load_dwordx4 v[84:87], v150, s[84:85] offset:0
	s_waitcnt lgkmcnt(4)
	v_mfma_f32_16x16x32_bf16 v[4:7], v[96:99], v[196:199], v[4:7]
	v_mfma_f32_16x16x32_bf16 v[36:39], v[164:167], v[196:199], v[36:39]
	v_mfma_f32_16x16x32_bf16 v[184:187], v[168:171], v[196:199], v[184:187]
	v_mfma_f32_16x16x32_bf16 v[100:103], v[172:175], v[196:199], v[100:103]
	ds_read_b128 v[192:195], v212 offset:61440
	global_load_dwordx4 v[88:91], v142, s[92:93] offset:0
	s_waitcnt lgkmcnt(4)
	v_mfma_f32_16x16x32_bf16 v[8:11], v[96:99], v[160:163], v[8:11]
	v_mfma_f32_16x16x32_bf16 v[40:43], v[164:167], v[160:163], v[40:43]
	v_mfma_f32_16x16x32_bf16 v[204:207], v[168:171], v[160:163], v[204:207]
	v_mfma_f32_16x16x32_bf16 v[104:107], v[172:175], v[160:163], v[104:107]
	ds_read_b128 v[196:199], v212 offset:63488
	global_load_dwordx4 v[92:95], v150, s[92:93] offset:0
	s_waitcnt lgkmcnt(4)
	v_mfma_f32_16x16x32_bf16 v[12:15], v[96:99], v[176:179], v[12:15]
	v_mfma_f32_16x16x32_bf16 v[44:47], v[164:167], v[176:179], v[44:47]
	v_mfma_f32_16x16x32_bf16 v[208:211], v[168:171], v[176:179], v[208:211]
	v_mfma_f32_16x16x32_bf16 v[108:111], v[172:175], v[176:179], v[108:111]
	ds_read_b128 v[160:163], v213 offset:49152
	s_waitcnt lgkmcnt(4)
	v_mfma_f32_16x16x32_bf16 v[16:19], v[96:99], v[180:183], v[16:19]
	v_mfma_f32_16x16x32_bf16 v[48:51], v[164:167], v[180:183], v[48:51]
	v_mfma_f32_16x16x32_bf16 v[232:235], v[168:171], v[180:183], v[232:235]
	v_mfma_f32_16x16x32_bf16 v[112:115], v[172:175], v[180:183], v[112:115]
	ds_read_b128 v[176:179], v213 offset:51200
	s_waitcnt lgkmcnt(4)
	v_mfma_f32_16x16x32_bf16 v[20:23], v[96:99], v[188:191], v[20:23]
	v_mfma_f32_16x16x32_bf16 v[52:55], v[164:167], v[188:191], v[52:55]
	v_mfma_f32_16x16x32_bf16 v[236:239], v[168:171], v[188:191], v[236:239]
	v_mfma_f32_16x16x32_bf16 v[116:119], v[172:175], v[188:191], v[116:119]
	ds_read_b128 v[180:183], v213 offset:53248
	s_waitcnt lgkmcnt(4)
	v_mfma_f32_16x16x32_bf16 v[24:27], v[96:99], v[192:195], v[24:27]
	v_mfma_f32_16x16x32_bf16 v[56:59], v[164:167], v[192:195], v[56:59]
	v_mfma_f32_16x16x32_bf16 v[240:243], v[168:171], v[192:195], v[240:243]
	v_mfma_f32_16x16x32_bf16 v[120:123], v[172:175], v[192:195], v[120:123]
	ds_read_b128 v[188:191], v213 offset:55296
	s_waitcnt lgkmcnt(4)
	v_mfma_f32_16x16x32_bf16 v[28:31], v[96:99], v[196:199], v[28:31]
	v_mfma_f32_16x16x32_bf16 v[60:63], v[164:167], v[196:199], v[60:63]
	v_mfma_f32_16x16x32_bf16 v[248:251], v[168:171], v[196:199], v[248:251]
	v_mfma_f32_16x16x32_bf16 v[124:127], v[172:175], v[196:199], v[124:127]
	s_waitcnt vmcnt(16)
	s_barrier
	s_waitcnt vmcnt(8)
	ds_read_b128 v[192:195], v213 offset:57344
	global_load_dwordx4 v[96:99], v142, s[84:85] offset:1024
	s_waitcnt lgkmcnt(4)
	v_mfma_f32_16x16x32_bf16 v[0:3], v[64:67], v[160:163], v[0:3]
	v_mfma_f32_16x16x32_bf16 v[32:35], v[68:71], v[160:163], v[32:35]
	v_mfma_f32_16x16x32_bf16 v[144:147], v[72:75], v[160:163], v[144:147]
	v_mfma_f32_16x16x32_bf16 v[252:255], v[76:79], v[160:163], v[252:255]
	ds_read_b128 v[196:199], v213 offset:59392
	global_load_dwordx4 v[164:167], v150, s[84:85] offset:1024
	s_waitcnt lgkmcnt(4)
	v_mfma_f32_16x16x32_bf16 v[4:7], v[64:67], v[176:179], v[4:7]
	v_mfma_f32_16x16x32_bf16 v[36:39], v[68:71], v[176:179], v[36:39]
	v_mfma_f32_16x16x32_bf16 v[184:187], v[72:75], v[176:179], v[184:187]
	v_mfma_f32_16x16x32_bf16 v[100:103], v[76:79], v[176:179], v[100:103]
	ds_read_b128 v[160:163], v213 offset:61440
	global_load_dwordx4 v[168:171], v142, s[92:93] offset:1024
	s_waitcnt lgkmcnt(4)
	v_mfma_f32_16x16x32_bf16 v[8:11], v[64:67], v[180:183], v[8:11]
	v_mfma_f32_16x16x32_bf16 v[40:43], v[68:71], v[180:183], v[40:43]
	v_mfma_f32_16x16x32_bf16 v[204:207], v[72:75], v[180:183], v[204:207]
	v_mfma_f32_16x16x32_bf16 v[104:107], v[76:79], v[180:183], v[104:107]
	ds_read_b128 v[176:179], v213 offset:63488
	global_load_dwordx4 v[172:175], v150, s[92:93] offset:1024
	s_add_u32 s84, s84, 0x800
	s_addc_u32 s85, s85, 0
	s_add_u32 s92, s92, 0x800
	s_addc_u32 s93, s93, 0
	s_waitcnt lgkmcnt(4)
	v_mfma_f32_16x16x32_bf16 v[12:15], v[64:67], v[188:191], v[12:15]
	v_mfma_f32_16x16x32_bf16 v[44:47], v[68:71], v[188:191], v[44:47]
	v_mfma_f32_16x16x32_bf16 v[208:211], v[72:75], v[188:191], v[208:211]
	v_mfma_f32_16x16x32_bf16 v[108:111], v[76:79], v[188:191], v[108:111]
	ds_read_b128 v[180:183], v212 offset:0
	s_add_u32 m0, s1, 32768
	s_nop 0
	global_load_lds_dwordx4 v151, s[86:87]
	s_waitcnt lgkmcnt(4)
	v_mfma_f32_16x16x32_bf16 v[16:19], v[64:67], v[192:195], v[16:19]
	v_mfma_f32_16x16x32_bf16 v[48:51], v[68:71], v[192:195], v[48:51]
	v_mfma_f32_16x16x32_bf16 v[232:235], v[72:75], v[192:195], v[232:235]
	v_mfma_f32_16x16x32_bf16 v[112:115], v[76:79], v[192:195], v[112:115]
	ds_read_b128 v[188:191], v212 offset:2048
	s_add_u32 m0, s1, 36864
	s_nop 0
	global_load_lds_dwordx4 v156, s[86:87]
	s_waitcnt lgkmcnt(4)
	v_mfma_f32_16x16x32_bf16 v[20:23], v[64:67], v[196:199], v[20:23]
	v_mfma_f32_16x16x32_bf16 v[52:55], v[68:71], v[196:199], v[52:55]
	v_mfma_f32_16x16x32_bf16 v[236:239], v[72:75], v[196:199], v[236:239]
	v_mfma_f32_16x16x32_bf16 v[116:119], v[76:79], v[196:199], v[116:119]
	ds_read_b128 v[192:195], v212 offset:4096
	s_add_u32 m0, s1, 40960
	s_nop 0
	global_load_lds_dwordx4 v158, s[86:87]
	s_waitcnt lgkmcnt(4)
	v_mfma_f32_16x16x32_bf16 v[24:27], v[64:67], v[160:163], v[24:27]
	v_mfma_f32_16x16x32_bf16 v[56:59], v[68:71], v[160:163], v[56:59]
	v_mfma_f32_16x16x32_bf16 v[240:243], v[72:75], v[160:163], v[240:243]
	v_mfma_f32_16x16x32_bf16 v[120:123], v[76:79], v[160:163], v[120:123]
	ds_read_b128 v[196:199], v212 offset:6144
	s_add_u32 m0, s1, 45056
	s_nop 0
	global_load_lds_dwordx4 v159, s[86:87]
	s_add_u32 s86, s86, 128
	s_addc_u32 s87, s87, 0
	s_waitcnt lgkmcnt(4)
	v_mfma_f32_16x16x32_bf16 v[28:31], v[64:67], v[176:179], v[28:31]
	v_mfma_f32_16x16x32_bf16 v[60:63], v[68:71], v[176:179], v[60:63]
	v_mfma_f32_16x16x32_bf16 v[248:251], v[72:75], v[176:179], v[248:251]
	v_mfma_f32_16x16x32_bf16 v[124:127], v[76:79], v[176:179], v[124:127]
	s_waitcnt vmcnt(8)
	ds_read_b128 v[160:163], v212 offset:8192
	global_load_dwordx4 v[64:67], v142, s[84:85] offset:0
	s_waitcnt lgkmcnt(4)
	v_mfma_f32_16x16x32_bf16 v[0:3], v[80:83], v[180:183], v[0:3]
	v_mfma_f32_16x16x32_bf16 v[32:35], v[84:87], v[180:183], v[32:35]
	v_mfma_f32_16x16x32_bf16 v[144:147], v[88:91], v[180:183], v[144:147]
	v_mfma_f32_16x16x32_bf16 v[252:255], v[92:95], v[180:183], v[252:255]
	ds_read_b128 v[176:179], v212 offset:10240
	global_load_dwordx4 v[68:71], v150, s[84:85] offset:0
	s_waitcnt lgkmcnt(4)
	v_mfma_f32_16x16x32_bf16 v[4:7], v[80:83], v[188:191], v[4:7]
	v_mfma_f32_16x16x32_bf16 v[36:39], v[84:87], v[188:191], v[36:39]
	v_mfma_f32_16x16x32_bf16 v[184:187], v[88:91], v[188:191], v[184:187]
	v_mfma_f32_16x16x32_bf16 v[100:103], v[92:95], v[188:191], v[100:103]
	ds_read_b128 v[180:183], v212 offset:12288
	global_load_dwordx4 v[72:75], v142, s[92:93] offset:0
	s_waitcnt lgkmcnt(4)
	v_mfma_f32_16x16x32_bf16 v[8:11], v[80:83], v[192:195], v[8:11]
	v_mfma_f32_16x16x32_bf16 v[40:43], v[84:87], v[192:195], v[40:43]
	v_mfma_f32_16x16x32_bf16 v[204:207], v[88:91], v[192:195], v[204:207]
	v_mfma_f32_16x16x32_bf16 v[104:107], v[92:95], v[192:195], v[104:107]
	ds_read_b128 v[188:191], v212 offset:14336
	global_load_dwordx4 v[76:79], v150, s[92:93] offset:0
	s_waitcnt lgkmcnt(4)
	v_mfma_f32_16x16x32_bf16 v[12:15], v[80:83], v[196:199], v[12:15]
	v_mfma_f32_16x16x32_bf16 v[44:47], v[84:87], v[196:199], v[44:47]
	v_mfma_f32_16x16x32_bf16 v[208:211], v[88:91], v[196:199], v[208:211]
	v_mfma_f32_16x16x32_bf16 v[108:111], v[92:95], v[196:199], v[108:111]
	ds_read_b128 v[192:195], v213 offset:0
	s_waitcnt lgkmcnt(4)
	v_mfma_f32_16x16x32_bf16 v[16:19], v[80:83], v[160:163], v[16:19]
	v_mfma_f32_16x16x32_bf16 v[48:51], v[84:87], v[160:163], v[48:51]
	v_mfma_f32_16x16x32_bf16 v[232:235], v[88:91], v[160:163], v[232:235]
	v_mfma_f32_16x16x32_bf16 v[112:115], v[92:95], v[160:163], v[112:115]
	ds_read_b128 v[196:199], v213 offset:2048
	s_waitcnt lgkmcnt(4)
	v_mfma_f32_16x16x32_bf16 v[20:23], v[80:83], v[176:179], v[20:23]
	v_mfma_f32_16x16x32_bf16 v[52:55], v[84:87], v[176:179], v[52:55]
	v_mfma_f32_16x16x32_bf16 v[236:239], v[88:91], v[176:179], v[236:239]
	v_mfma_f32_16x16x32_bf16 v[116:119], v[92:95], v[176:179], v[116:119]
	ds_read_b128 v[160:163], v213 offset:4096
	s_waitcnt lgkmcnt(4)
	v_mfma_f32_16x16x32_bf16 v[24:27], v[80:83], v[180:183], v[24:27]
	v_mfma_f32_16x16x32_bf16 v[56:59], v[84:87], v[180:183], v[56:59]
	v_mfma_f32_16x16x32_bf16 v[240:243], v[88:91], v[180:183], v[240:243]
	v_mfma_f32_16x16x32_bf16 v[120:123], v[92:95], v[180:183], v[120:123]
	ds_read_b128 v[176:179], v213 offset:6144
	s_waitcnt lgkmcnt(4)
	v_mfma_f32_16x16x32_bf16 v[28:31], v[80:83], v[188:191], v[28:31]
	v_mfma_f32_16x16x32_bf16 v[60:63], v[84:87], v[188:191], v[60:63]
	v_mfma_f32_16x16x32_bf16 v[248:251], v[88:91], v[188:191], v[248:251]
	v_mfma_f32_16x16x32_bf16 v[124:127], v[92:95], v[188:191], v[124:127]
	s_waitcnt vmcnt(16)
	s_barrier
	s_waitcnt vmcnt(8)
	ds_read_b128 v[180:183], v213 offset:8192
	global_load_dwordx4 v[80:83], v142, s[84:85] offset:1024
	s_waitcnt lgkmcnt(4)
	v_mfma_f32_16x16x32_bf16 v[0:3], v[96:99], v[192:195], v[0:3]
	v_mfma_f32_16x16x32_bf16 v[32:35], v[164:167], v[192:195], v[32:35]
	v_mfma_f32_16x16x32_bf16 v[144:147], v[168:171], v[192:195], v[144:147]
	v_mfma_f32_16x16x32_bf16 v[252:255], v[172:175], v[192:195], v[252:255]
	ds_read_b128 v[188:191], v213 offset:10240
	global_load_dwordx4 v[84:87], v150, s[84:85] offset:1024
	s_waitcnt lgkmcnt(4)
	v_mfma_f32_16x16x32_bf16 v[4:7], v[96:99], v[196:199], v[4:7]
	v_mfma_f32_16x16x32_bf16 v[36:39], v[164:167], v[196:199], v[36:39]
	v_mfma_f32_16x16x32_bf16 v[184:187], v[168:171], v[196:199], v[184:187]
	v_mfma_f32_16x16x32_bf16 v[100:103], v[172:175], v[196:199], v[100:103]
	ds_read_b128 v[192:195], v213 offset:12288
	global_load_dwordx4 v[88:91], v142, s[92:93] offset:1024
	s_waitcnt lgkmcnt(4)
	v_mfma_f32_16x16x32_bf16 v[8:11], v[96:99], v[160:163], v[8:11]
	v_mfma_f32_16x16x32_bf16 v[40:43], v[164:167], v[160:163], v[40:43]
	v_mfma_f32_16x16x32_bf16 v[204:207], v[168:171], v[160:163], v[204:207]
	v_mfma_f32_16x16x32_bf16 v[104:107], v[172:175], v[160:163], v[104:107]
	ds_read_b128 v[196:199], v213 offset:14336
	global_load_dwordx4 v[92:95], v150, s[92:93] offset:1024
	s_add_u32 s84, s84, 0x800
	s_addc_u32 s85, s85, 0
	s_add_u32 s92, s92, 0x800
	s_addc_u32 s93, s93, 0
	s_waitcnt lgkmcnt(4)
	v_mfma_f32_16x16x32_bf16 v[12:15], v[96:99], v[176:179], v[12:15]
	v_mfma_f32_16x16x32_bf16 v[44:47], v[164:167], v[176:179], v[44:47]
	v_mfma_f32_16x16x32_bf16 v[208:211], v[168:171], v[176:179], v[208:211]
	v_mfma_f32_16x16x32_bf16 v[108:111], v[172:175], v[176:179], v[108:111]
	ds_read_b128 v[160:163], v212 offset:16384
	s_add_u32 m0, s1, 49152
	s_nop 0
	global_load_lds_dwordx4 v151, s[86:87]
	s_waitcnt lgkmcnt(4)
	v_mfma_f32_16x16x32_bf16 v[16:19], v[96:99], v[180:183], v[16:19]
	v_mfma_f32_16x16x32_bf16 v[48:51], v[164:167], v[180:183], v[48:51]
	v_mfma_f32_16x16x32_bf16 v[232:235], v[168:171], v[180:183], v[232:235]
	v_mfma_f32_16x16x32_bf16 v[112:115], v[172:175], v[180:183], v[112:115]
	ds_read_b128 v[176:179], v212 offset:18432
	s_add_u32 m0, s1, 53248
	s_nop 0
	global_load_lds_dwordx4 v156, s[86:87]
	s_waitcnt lgkmcnt(4)
	v_mfma_f32_16x16x32_bf16 v[20:23], v[96:99], v[188:191], v[20:23]
	v_mfma_f32_16x16x32_bf16 v[52:55], v[164:167], v[188:191], v[52:55]
	v_mfma_f32_16x16x32_bf16 v[236:239], v[168:171], v[188:191], v[236:239]
	v_mfma_f32_16x16x32_bf16 v[116:119], v[172:175], v[188:191], v[116:119]
	ds_read_b128 v[180:183], v212 offset:20480
	s_add_u32 m0, s1, 57344
	s_nop 0
	global_load_lds_dwordx4 v158, s[86:87]
	s_waitcnt lgkmcnt(4)
	v_mfma_f32_16x16x32_bf16 v[24:27], v[96:99], v[192:195], v[24:27]
	v_mfma_f32_16x16x32_bf16 v[56:59], v[164:167], v[192:195], v[56:59]
	v_mfma_f32_16x16x32_bf16 v[240:243], v[168:171], v[192:195], v[240:243]
	v_mfma_f32_16x16x32_bf16 v[120:123], v[172:175], v[192:195], v[120:123]
	ds_read_b128 v[188:191], v212 offset:22528
	s_add_u32 m0, s1, 61440
	s_nop 0
	global_load_lds_dwordx4 v159, s[86:87]
	s_add_u32 s86, s86, 128
	s_addc_u32 s87, s87, 0
	s_waitcnt lgkmcnt(4)
	v_mfma_f32_16x16x32_bf16 v[28:31], v[96:99], v[196:199], v[28:31]
	v_mfma_f32_16x16x32_bf16 v[60:63], v[164:167], v[196:199], v[60:63]
	v_mfma_f32_16x16x32_bf16 v[248:251], v[168:171], v[196:199], v[248:251]
	v_mfma_f32_16x16x32_bf16 v[124:127], v[172:175], v[196:199], v[124:127]
	s_waitcnt vmcnt(8)
	ds_read_b128 v[192:195], v212 offset:24576
	global_load_dwordx4 v[96:99], v142, s[84:85] offset:0
	s_waitcnt lgkmcnt(4)
	v_mfma_f32_16x16x32_bf16 v[0:3], v[64:67], v[160:163], v[0:3]
	v_mfma_f32_16x16x32_bf16 v[32:35], v[68:71], v[160:163], v[32:35]
	v_mfma_f32_16x16x32_bf16 v[144:147], v[72:75], v[160:163], v[144:147]
	v_mfma_f32_16x16x32_bf16 v[252:255], v[76:79], v[160:163], v[252:255]
	ds_read_b128 v[196:199], v212 offset:26624
	global_load_dwordx4 v[164:167], v150, s[84:85] offset:0
	s_waitcnt lgkmcnt(4)
	v_mfma_f32_16x16x32_bf16 v[4:7], v[64:67], v[176:179], v[4:7]
	v_mfma_f32_16x16x32_bf16 v[36:39], v[68:71], v[176:179], v[36:39]
	v_mfma_f32_16x16x32_bf16 v[184:187], v[72:75], v[176:179], v[184:187]
	v_mfma_f32_16x16x32_bf16 v[100:103], v[76:79], v[176:179], v[100:103]
	ds_read_b128 v[160:163], v212 offset:28672
	global_load_dwordx4 v[168:171], v142, s[92:93] offset:0
	s_waitcnt lgkmcnt(4)
	v_mfma_f32_16x16x32_bf16 v[8:11], v[64:67], v[180:183], v[8:11]
	v_mfma_f32_16x16x32_bf16 v[40:43], v[68:71], v[180:183], v[40:43]
	v_mfma_f32_16x16x32_bf16 v[204:207], v[72:75], v[180:183], v[204:207]
	v_mfma_f32_16x16x32_bf16 v[104:107], v[76:79], v[180:183], v[104:107]
	ds_read_b128 v[176:179], v212 offset:30720
	global_load_dwordx4 v[172:175], v150, s[92:93] offset:0
	s_waitcnt lgkmcnt(4)
	v_mfma_f32_16x16x32_bf16 v[12:15], v[64:67], v[188:191], v[12:15]
	v_mfma_f32_16x16x32_bf16 v[44:47], v[68:71], v[188:191], v[44:47]
	v_mfma_f32_16x16x32_bf16 v[208:211], v[72:75], v[188:191], v[208:211]
	v_mfma_f32_16x16x32_bf16 v[108:111], v[76:79], v[188:191], v[108:111]
	ds_read_b128 v[180:183], v213 offset:16384
	s_waitcnt lgkmcnt(4)
	v_mfma_f32_16x16x32_bf16 v[16:19], v[64:67], v[192:195], v[16:19]
	v_mfma_f32_16x16x32_bf16 v[48:51], v[68:71], v[192:195], v[48:51]
	v_mfma_f32_16x16x32_bf16 v[232:235], v[72:75], v[192:195], v[232:235]
	v_mfma_f32_16x16x32_bf16 v[112:115], v[76:79], v[192:195], v[112:115]
	ds_read_b128 v[188:191], v213 offset:18432
	s_waitcnt lgkmcnt(4)
	v_mfma_f32_16x16x32_bf16 v[20:23], v[64:67], v[196:199], v[20:23]
	v_mfma_f32_16x16x32_bf16 v[52:55], v[68:71], v[196:199], v[52:55]
	v_mfma_f32_16x16x32_bf16 v[236:239], v[72:75], v[196:199], v[236:239]
	v_mfma_f32_16x16x32_bf16 v[116:119], v[76:79], v[196:199], v[116:119]
	ds_read_b128 v[192:195], v213 offset:20480
	s_waitcnt lgkmcnt(4)
	v_mfma_f32_16x16x32_bf16 v[24:27], v[64:67], v[160:163], v[24:27]
	v_mfma_f32_16x16x32_bf16 v[56:59], v[68:71], v[160:163], v[56:59]
	v_mfma_f32_16x16x32_bf16 v[240:243], v[72:75], v[160:163], v[240:243]
	v_mfma_f32_16x16x32_bf16 v[120:123], v[76:79], v[160:163], v[120:123]
	ds_read_b128 v[196:199], v213 offset:22528
	s_waitcnt lgkmcnt(4)
	v_mfma_f32_16x16x32_bf16 v[28:31], v[64:67], v[176:179], v[28:31]
	v_mfma_f32_16x16x32_bf16 v[60:63], v[68:71], v[176:179], v[60:63]
	v_mfma_f32_16x16x32_bf16 v[248:251], v[72:75], v[176:179], v[248:251]
	v_mfma_f32_16x16x32_bf16 v[124:127], v[76:79], v[176:179], v[124:127]
	s_waitcnt vmcnt(16)
	s_barrier
	s_waitcnt vmcnt(8)
	ds_read_b128 v[160:163], v213 offset:24576
	global_load_dwordx4 v[64:67], v142, s[84:85] offset:1024
	s_waitcnt lgkmcnt(4)
	v_mfma_f32_16x16x32_bf16 v[0:3], v[80:83], v[180:183], v[0:3]
	v_mfma_f32_16x16x32_bf16 v[32:35], v[84:87], v[180:183], v[32:35]
	v_mfma_f32_16x16x32_bf16 v[144:147], v[88:91], v[180:183], v[144:147]
	v_mfma_f32_16x16x32_bf16 v[252:255], v[92:95], v[180:183], v[252:255]
	ds_read_b128 v[176:179], v213 offset:26624
	global_load_dwordx4 v[68:71], v150, s[84:85] offset:1024
	s_waitcnt lgkmcnt(4)
	v_mfma_f32_16x16x32_bf16 v[4:7], v[80:83], v[188:191], v[4:7]
	v_mfma_f32_16x16x32_bf16 v[36:39], v[84:87], v[188:191], v[36:39]
	v_mfma_f32_16x16x32_bf16 v[184:187], v[88:91], v[188:191], v[184:187]
	v_mfma_f32_16x16x32_bf16 v[100:103], v[92:95], v[188:191], v[100:103]
	ds_read_b128 v[180:183], v213 offset:28672
	global_load_dwordx4 v[72:75], v142, s[92:93] offset:1024
	s_waitcnt lgkmcnt(4)
	v_mfma_f32_16x16x32_bf16 v[8:11], v[80:83], v[192:195], v[8:11]
	v_mfma_f32_16x16x32_bf16 v[40:43], v[84:87], v[192:195], v[40:43]
	v_mfma_f32_16x16x32_bf16 v[204:207], v[88:91], v[192:195], v[204:207]
	v_mfma_f32_16x16x32_bf16 v[104:107], v[92:95], v[192:195], v[104:107]
	ds_read_b128 v[188:191], v213 offset:30720
	global_load_dwordx4 v[76:79], v150, s[92:93] offset:1024
	s_add_u32 s84, s84, 0x800
	s_addc_u32 s85, s85, 0
	s_add_u32 s92, s92, 0x800
	s_addc_u32 s93, s93, 0
	s_waitcnt lgkmcnt(4)
	v_mfma_f32_16x16x32_bf16 v[12:15], v[80:83], v[196:199], v[12:15]
	v_mfma_f32_16x16x32_bf16 v[44:47], v[84:87], v[196:199], v[44:47]
	v_mfma_f32_16x16x32_bf16 v[208:211], v[88:91], v[196:199], v[208:211]
	v_mfma_f32_16x16x32_bf16 v[108:111], v[92:95], v[196:199], v[108:111]
	ds_read_b128 v[192:195], v212 offset:32768
	s_add_u32 m0, s1, 0
	s_nop 0
	global_load_lds_dwordx4 v151, s[86:87]
	s_waitcnt lgkmcnt(4)
	v_mfma_f32_16x16x32_bf16 v[16:19], v[80:83], v[160:163], v[16:19]
	v_mfma_f32_16x16x32_bf16 v[48:51], v[84:87], v[160:163], v[48:51]
	v_mfma_f32_16x16x32_bf16 v[232:235], v[88:91], v[160:163], v[232:235]
	v_mfma_f32_16x16x32_bf16 v[112:115], v[92:95], v[160:163], v[112:115]
	ds_read_b128 v[196:199], v212 offset:34816
	s_add_u32 m0, s1, 4096
	s_nop 0
	global_load_lds_dwordx4 v156, s[86:87]
	s_waitcnt lgkmcnt(4)
	v_mfma_f32_16x16x32_bf16 v[20:23], v[80:83], v[176:179], v[20:23]
	v_mfma_f32_16x16x32_bf16 v[52:55], v[84:87], v[176:179], v[52:55]
	v_mfma_f32_16x16x32_bf16 v[236:239], v[88:91], v[176:179], v[236:239]
	v_mfma_f32_16x16x32_bf16 v[116:119], v[92:95], v[176:179], v[116:119]
	ds_read_b128 v[160:163], v212 offset:36864
	s_add_u32 m0, s1, 8192
	s_nop 0
	global_load_lds_dwordx4 v158, s[86:87]
	s_waitcnt lgkmcnt(4)
	v_mfma_f32_16x16x32_bf16 v[24:27], v[80:83], v[180:183], v[24:27]
	v_mfma_f32_16x16x32_bf16 v[56:59], v[84:87], v[180:183], v[56:59]
	v_mfma_f32_16x16x32_bf16 v[240:243], v[88:91], v[180:183], v[240:243]
	v_mfma_f32_16x16x32_bf16 v[120:123], v[92:95], v[180:183], v[120:123]
	ds_read_b128 v[176:179], v212 offset:38912
	s_add_u32 m0, s1, 12288
	s_nop 0
	global_load_lds_dwordx4 v159, s[86:87]
	s_add_u32 s86, s86, 128
	s_addc_u32 s87, s87, 0
	s_waitcnt lgkmcnt(4)
	v_mfma_f32_16x16x32_bf16 v[28:31], v[80:83], v[188:191], v[28:31]
	v_mfma_f32_16x16x32_bf16 v[60:63], v[84:87], v[188:191], v[60:63]
	v_mfma_f32_16x16x32_bf16 v[248:251], v[88:91], v[188:191], v[248:251]
	v_mfma_f32_16x16x32_bf16 v[124:127], v[92:95], v[188:191], v[124:127]
	s_waitcnt vmcnt(8)
	ds_read_b128 v[180:183], v212 offset:40960
	global_load_dwordx4 v[80:83], v142, s[84:85] offset:0
	s_waitcnt lgkmcnt(4)
	v_mfma_f32_16x16x32_bf16 v[0:3], v[96:99], v[192:195], v[0:3]
	v_mfma_f32_16x16x32_bf16 v[32:35], v[164:167], v[192:195], v[32:35]
	v_mfma_f32_16x16x32_bf16 v[144:147], v[168:171], v[192:195], v[144:147]
	v_mfma_f32_16x16x32_bf16 v[252:255], v[172:175], v[192:195], v[252:255]
	ds_read_b128 v[188:191], v212 offset:43008
	global_load_dwordx4 v[84:87], v150, s[84:85] offset:0
	s_waitcnt lgkmcnt(4)
	v_mfma_f32_16x16x32_bf16 v[4:7], v[96:99], v[196:199], v[4:7]
	v_mfma_f32_16x16x32_bf16 v[36:39], v[164:167], v[196:199], v[36:39]
	v_mfma_f32_16x16x32_bf16 v[184:187], v[168:171], v[196:199], v[184:187]
	v_mfma_f32_16x16x32_bf16 v[100:103], v[172:175], v[196:199], v[100:103]
	ds_read_b128 v[192:195], v212 offset:45056
	global_load_dwordx4 v[88:91], v142, s[92:93] offset:0
	s_waitcnt lgkmcnt(4)
	v_mfma_f32_16x16x32_bf16 v[8:11], v[96:99], v[160:163], v[8:11]
	v_mfma_f32_16x16x32_bf16 v[40:43], v[164:167], v[160:163], v[40:43]
	v_mfma_f32_16x16x32_bf16 v[204:207], v[168:171], v[160:163], v[204:207]
	v_mfma_f32_16x16x32_bf16 v[104:107], v[172:175], v[160:163], v[104:107]
	ds_read_b128 v[196:199], v212 offset:47104
	global_load_dwordx4 v[92:95], v150, s[92:93] offset:0
	s_waitcnt lgkmcnt(4)
	v_mfma_f32_16x16x32_bf16 v[12:15], v[96:99], v[176:179], v[12:15]
	v_mfma_f32_16x16x32_bf16 v[44:47], v[164:167], v[176:179], v[44:47]
	v_mfma_f32_16x16x32_bf16 v[208:211], v[168:171], v[176:179], v[208:211]
	v_mfma_f32_16x16x32_bf16 v[108:111], v[172:175], v[176:179], v[108:111]
	ds_read_b128 v[160:163], v213 offset:32768
	s_waitcnt lgkmcnt(4)
	v_mfma_f32_16x16x32_bf16 v[16:19], v[96:99], v[180:183], v[16:19]
	v_mfma_f32_16x16x32_bf16 v[48:51], v[164:167], v[180:183], v[48:51]
	v_mfma_f32_16x16x32_bf16 v[232:235], v[168:171], v[180:183], v[232:235]
	v_mfma_f32_16x16x32_bf16 v[112:115], v[172:175], v[180:183], v[112:115]
	ds_read_b128 v[176:179], v213 offset:34816
	s_waitcnt lgkmcnt(4)
	v_mfma_f32_16x16x32_bf16 v[20:23], v[96:99], v[188:191], v[20:23]
	v_mfma_f32_16x16x32_bf16 v[52:55], v[164:167], v[188:191], v[52:55]
	v_mfma_f32_16x16x32_bf16 v[236:239], v[168:171], v[188:191], v[236:239]
	v_mfma_f32_16x16x32_bf16 v[116:119], v[172:175], v[188:191], v[116:119]
	ds_read_b128 v[180:183], v213 offset:36864
	s_waitcnt lgkmcnt(4)
	v_mfma_f32_16x16x32_bf16 v[24:27], v[96:99], v[192:195], v[24:27]
	v_mfma_f32_16x16x32_bf16 v[56:59], v[164:167], v[192:195], v[56:59]
	v_mfma_f32_16x16x32_bf16 v[240:243], v[168:171], v[192:195], v[240:243]
	v_mfma_f32_16x16x32_bf16 v[120:123], v[172:175], v[192:195], v[120:123]
	ds_read_b128 v[188:191], v213 offset:38912
	s_waitcnt lgkmcnt(4)
	v_mfma_f32_16x16x32_bf16 v[28:31], v[96:99], v[196:199], v[28:31]
	v_mfma_f32_16x16x32_bf16 v[60:63], v[164:167], v[196:199], v[60:63]
	v_mfma_f32_16x16x32_bf16 v[248:251], v[168:171], v[196:199], v[248:251]
	v_mfma_f32_16x16x32_bf16 v[124:127], v[172:175], v[196:199], v[124:127]
	s_waitcnt vmcnt(16)
	s_barrier
	s_waitcnt vmcnt(8)
	ds_read_b128 v[192:195], v213 offset:40960
	global_load_dwordx4 v[96:99], v142, s[84:85] offset:1024
	s_waitcnt lgkmcnt(4)
	v_mfma_f32_16x16x32_bf16 v[0:3], v[64:67], v[160:163], v[0:3]
	v_mfma_f32_16x16x32_bf16 v[32:35], v[68:71], v[160:163], v[32:35]
	v_mfma_f32_16x16x32_bf16 v[144:147], v[72:75], v[160:163], v[144:147]
	v_mfma_f32_16x16x32_bf16 v[252:255], v[76:79], v[160:163], v[252:255]
	ds_read_b128 v[196:199], v213 offset:43008
	global_load_dwordx4 v[164:167], v150, s[84:85] offset:1024
	s_waitcnt lgkmcnt(4)
	v_mfma_f32_16x16x32_bf16 v[4:7], v[64:67], v[176:179], v[4:7]
	v_mfma_f32_16x16x32_bf16 v[36:39], v[68:71], v[176:179], v[36:39]
	v_mfma_f32_16x16x32_bf16 v[184:187], v[72:75], v[176:179], v[184:187]
	v_mfma_f32_16x16x32_bf16 v[100:103], v[76:79], v[176:179], v[100:103]
	ds_read_b128 v[160:163], v213 offset:45056
	global_load_dwordx4 v[168:171], v142, s[92:93] offset:1024
	s_waitcnt lgkmcnt(4)
	v_mfma_f32_16x16x32_bf16 v[8:11], v[64:67], v[180:183], v[8:11]
	v_mfma_f32_16x16x32_bf16 v[40:43], v[68:71], v[180:183], v[40:43]
	v_mfma_f32_16x16x32_bf16 v[204:207], v[72:75], v[180:183], v[204:207]
	v_mfma_f32_16x16x32_bf16 v[104:107], v[76:79], v[180:183], v[104:107]
	ds_read_b128 v[176:179], v213 offset:47104
	global_load_dwordx4 v[172:175], v150, s[92:93] offset:1024
	s_add_u32 s84, s84, 0x800
	s_addc_u32 s85, s85, 0
	s_add_u32 s92, s92, 0x800
	s_addc_u32 s93, s93, 0
	s_waitcnt lgkmcnt(4)
	v_mfma_f32_16x16x32_bf16 v[12:15], v[64:67], v[188:191], v[12:15]
	v_mfma_f32_16x16x32_bf16 v[44:47], v[68:71], v[188:191], v[44:47]
	v_mfma_f32_16x16x32_bf16 v[208:211], v[72:75], v[188:191], v[208:211]
	v_mfma_f32_16x16x32_bf16 v[108:111], v[76:79], v[188:191], v[108:111]
	ds_read_b128 v[180:183], v212 offset:49152
	s_add_u32 m0, s1, 16384
	s_nop 0
	global_load_lds_dwordx4 v151, s[86:87]
	s_waitcnt lgkmcnt(4)
	v_mfma_f32_16x16x32_bf16 v[16:19], v[64:67], v[192:195], v[16:19]
	v_mfma_f32_16x16x32_bf16 v[48:51], v[68:71], v[192:195], v[48:51]
	v_mfma_f32_16x16x32_bf16 v[232:235], v[72:75], v[192:195], v[232:235]
	v_mfma_f32_16x16x32_bf16 v[112:115], v[76:79], v[192:195], v[112:115]
	ds_read_b128 v[188:191], v212 offset:51200
	s_add_u32 m0, s1, 20480
	s_nop 0
	global_load_lds_dwordx4 v156, s[86:87]
	s_waitcnt lgkmcnt(4)
	v_mfma_f32_16x16x32_bf16 v[20:23], v[64:67], v[196:199], v[20:23]
	v_mfma_f32_16x16x32_bf16 v[52:55], v[68:71], v[196:199], v[52:55]
	v_mfma_f32_16x16x32_bf16 v[236:239], v[72:75], v[196:199], v[236:239]
	v_mfma_f32_16x16x32_bf16 v[116:119], v[76:79], v[196:199], v[116:119]
	ds_read_b128 v[192:195], v212 offset:53248
	s_add_u32 m0, s1, 24576
	s_nop 0
	global_load_lds_dwordx4 v158, s[86:87]
	s_waitcnt lgkmcnt(4)
	v_mfma_f32_16x16x32_bf16 v[24:27], v[64:67], v[160:163], v[24:27]
	v_mfma_f32_16x16x32_bf16 v[56:59], v[68:71], v[160:163], v[56:59]
	v_mfma_f32_16x16x32_bf16 v[240:243], v[72:75], v[160:163], v[240:243]
	v_mfma_f32_16x16x32_bf16 v[120:123], v[76:79], v[160:163], v[120:123]
	ds_read_b128 v[196:199], v212 offset:55296
	s_add_u32 m0, s1, 28672
	s_nop 0
	global_load_lds_dwordx4 v159, s[86:87]
	s_add_u32 s86, s86, 128
	s_addc_u32 s87, s87, 0
	s_waitcnt lgkmcnt(4)
	v_mfma_f32_16x16x32_bf16 v[28:31], v[64:67], v[176:179], v[28:31]
	v_mfma_f32_16x16x32_bf16 v[60:63], v[68:71], v[176:179], v[60:63]
	v_mfma_f32_16x16x32_bf16 v[248:251], v[72:75], v[176:179], v[248:251]
	v_mfma_f32_16x16x32_bf16 v[124:127], v[76:79], v[176:179], v[124:127]
	s_waitcnt vmcnt(8)
	ds_read_b128 v[160:163], v212 offset:57344
	global_load_dwordx4 v[64:67], v142, s[84:85] offset:0
	s_waitcnt lgkmcnt(4)
	v_mfma_f32_16x16x32_bf16 v[0:3], v[80:83], v[180:183], v[0:3]
	v_mfma_f32_16x16x32_bf16 v[32:35], v[84:87], v[180:183], v[32:35]
	v_mfma_f32_16x16x32_bf16 v[144:147], v[88:91], v[180:183], v[144:147]
	v_mfma_f32_16x16x32_bf16 v[252:255], v[92:95], v[180:183], v[252:255]
	ds_read_b128 v[176:179], v212 offset:59392
	global_load_dwordx4 v[68:71], v150, s[84:85] offset:0
	s_waitcnt lgkmcnt(4)
	v_mfma_f32_16x16x32_bf16 v[4:7], v[80:83], v[188:191], v[4:7]
	v_mfma_f32_16x16x32_bf16 v[36:39], v[84:87], v[188:191], v[36:39]
	v_mfma_f32_16x16x32_bf16 v[184:187], v[88:91], v[188:191], v[184:187]
	v_mfma_f32_16x16x32_bf16 v[100:103], v[92:95], v[188:191], v[100:103]
	ds_read_b128 v[180:183], v212 offset:61440
	global_load_dwordx4 v[72:75], v142, s[92:93] offset:0
	s_waitcnt lgkmcnt(4)
	v_mfma_f32_16x16x32_bf16 v[8:11], v[80:83], v[192:195], v[8:11]
	v_mfma_f32_16x16x32_bf16 v[40:43], v[84:87], v[192:195], v[40:43]
	v_mfma_f32_16x16x32_bf16 v[204:207], v[88:91], v[192:195], v[204:207]
	v_mfma_f32_16x16x32_bf16 v[104:107], v[92:95], v[192:195], v[104:107]
	ds_read_b128 v[188:191], v212 offset:63488
	global_load_dwordx4 v[76:79], v150, s[92:93] offset:0
	s_waitcnt lgkmcnt(4)
	v_mfma_f32_16x16x32_bf16 v[12:15], v[80:83], v[196:199], v[12:15]
	v_mfma_f32_16x16x32_bf16 v[44:47], v[84:87], v[196:199], v[44:47]
	v_mfma_f32_16x16x32_bf16 v[208:211], v[88:91], v[196:199], v[208:211]
	v_mfma_f32_16x16x32_bf16 v[108:111], v[92:95], v[196:199], v[108:111]
	ds_read_b128 v[192:195], v213 offset:49152
	s_waitcnt lgkmcnt(4)
	v_mfma_f32_16x16x32_bf16 v[16:19], v[80:83], v[160:163], v[16:19]
	v_mfma_f32_16x16x32_bf16 v[48:51], v[84:87], v[160:163], v[48:51]
	v_mfma_f32_16x16x32_bf16 v[232:235], v[88:91], v[160:163], v[232:235]
	v_mfma_f32_16x16x32_bf16 v[112:115], v[92:95], v[160:163], v[112:115]
	ds_read_b128 v[196:199], v213 offset:51200
	s_waitcnt lgkmcnt(4)
	v_mfma_f32_16x16x32_bf16 v[20:23], v[80:83], v[176:179], v[20:23]
	v_mfma_f32_16x16x32_bf16 v[52:55], v[84:87], v[176:179], v[52:55]
	v_mfma_f32_16x16x32_bf16 v[236:239], v[88:91], v[176:179], v[236:239]
	v_mfma_f32_16x16x32_bf16 v[116:119], v[92:95], v[176:179], v[116:119]
	ds_read_b128 v[160:163], v213 offset:53248
	s_waitcnt lgkmcnt(4)
	v_mfma_f32_16x16x32_bf16 v[24:27], v[80:83], v[180:183], v[24:27]
	v_mfma_f32_16x16x32_bf16 v[56:59], v[84:87], v[180:183], v[56:59]
	v_mfma_f32_16x16x32_bf16 v[240:243], v[88:91], v[180:183], v[240:243]
	v_mfma_f32_16x16x32_bf16 v[120:123], v[92:95], v[180:183], v[120:123]
	ds_read_b128 v[176:179], v213 offset:55296
	s_waitcnt lgkmcnt(4)
	v_mfma_f32_16x16x32_bf16 v[28:31], v[80:83], v[188:191], v[28:31]
	v_mfma_f32_16x16x32_bf16 v[60:63], v[84:87], v[188:191], v[60:63]
	v_mfma_f32_16x16x32_bf16 v[248:251], v[88:91], v[188:191], v[248:251]
	v_mfma_f32_16x16x32_bf16 v[124:127], v[92:95], v[188:191], v[124:127]
	s_waitcnt vmcnt(16)
	s_barrier
	s_waitcnt vmcnt(8)
	ds_read_b128 v[180:183], v213 offset:57344
	global_load_dwordx4 v[80:83], v142, s[84:85] offset:1024
	s_waitcnt lgkmcnt(4)
	v_mfma_f32_16x16x32_bf16 v[0:3], v[96:99], v[192:195], v[0:3]
	v_mfma_f32_16x16x32_bf16 v[32:35], v[164:167], v[192:195], v[32:35]
	v_mfma_f32_16x16x32_bf16 v[144:147], v[168:171], v[192:195], v[144:147]
	v_mfma_f32_16x16x32_bf16 v[252:255], v[172:175], v[192:195], v[252:255]
	ds_read_b128 v[188:191], v213 offset:59392
	global_load_dwordx4 v[84:87], v150, s[84:85] offset:1024
	s_waitcnt lgkmcnt(4)
	v_mfma_f32_16x16x32_bf16 v[4:7], v[96:99], v[196:199], v[4:7]
	v_mfma_f32_16x16x32_bf16 v[36:39], v[164:167], v[196:199], v[36:39]
	v_mfma_f32_16x16x32_bf16 v[184:187], v[168:171], v[196:199], v[184:187]
	v_mfma_f32_16x16x32_bf16 v[100:103], v[172:175], v[196:199], v[100:103]
	ds_read_b128 v[192:195], v213 offset:61440
	global_load_dwordx4 v[88:91], v142, s[92:93] offset:1024
	s_waitcnt lgkmcnt(4)
	v_mfma_f32_16x16x32_bf16 v[8:11], v[96:99], v[160:163], v[8:11]
	v_mfma_f32_16x16x32_bf16 v[40:43], v[164:167], v[160:163], v[40:43]
	v_mfma_f32_16x16x32_bf16 v[204:207], v[168:171], v[160:163], v[204:207]
	v_mfma_f32_16x16x32_bf16 v[104:107], v[172:175], v[160:163], v[104:107]
	ds_read_b128 v[196:199], v213 offset:63488
	global_load_dwordx4 v[92:95], v150, s[92:93] offset:1024
	s_add_u32 s84, s84, 0x800
	s_addc_u32 s85, s85, 0
	s_add_u32 s92, s92, 0x800
	s_addc_u32 s93, s93, 0
	s_waitcnt lgkmcnt(4)
	v_mfma_f32_16x16x32_bf16 v[12:15], v[96:99], v[176:179], v[12:15]
	v_mfma_f32_16x16x32_bf16 v[44:47], v[164:167], v[176:179], v[44:47]
	v_mfma_f32_16x16x32_bf16 v[208:211], v[168:171], v[176:179], v[208:211]
	v_mfma_f32_16x16x32_bf16 v[108:111], v[172:175], v[176:179], v[108:111]
	ds_read_b128 v[160:163], v212 offset:0
	s_add_u32 m0, s1, 32768
	s_nop 0
	global_load_lds_dwordx4 v151, s[86:87]
	s_waitcnt lgkmcnt(4)
	v_mfma_f32_16x16x32_bf16 v[16:19], v[96:99], v[180:183], v[16:19]
	v_mfma_f32_16x16x32_bf16 v[48:51], v[164:167], v[180:183], v[48:51]
	v_mfma_f32_16x16x32_bf16 v[232:235], v[168:171], v[180:183], v[232:235]
	v_mfma_f32_16x16x32_bf16 v[112:115], v[172:175], v[180:183], v[112:115]
	ds_read_b128 v[176:179], v212 offset:2048
	s_add_u32 m0, s1, 36864
	s_nop 0
	global_load_lds_dwordx4 v156, s[86:87]
	s_waitcnt lgkmcnt(4)
	v_mfma_f32_16x16x32_bf16 v[20:23], v[96:99], v[188:191], v[20:23]
	v_mfma_f32_16x16x32_bf16 v[52:55], v[164:167], v[188:191], v[52:55]
	v_mfma_f32_16x16x32_bf16 v[236:239], v[168:171], v[188:191], v[236:239]
	v_mfma_f32_16x16x32_bf16 v[116:119], v[172:175], v[188:191], v[116:119]
	ds_read_b128 v[180:183], v212 offset:4096
	s_add_u32 m0, s1, 40960
	s_nop 0
	global_load_lds_dwordx4 v158, s[86:87]
	s_waitcnt lgkmcnt(4)
	v_mfma_f32_16x16x32_bf16 v[24:27], v[96:99], v[192:195], v[24:27]
	v_mfma_f32_16x16x32_bf16 v[56:59], v[164:167], v[192:195], v[56:59]
	v_mfma_f32_16x16x32_bf16 v[240:243], v[168:171], v[192:195], v[240:243]
	v_mfma_f32_16x16x32_bf16 v[120:123], v[172:175], v[192:195], v[120:123]
	ds_read_b128 v[188:191], v212 offset:6144
	s_add_u32 m0, s1, 45056
	s_nop 0
	global_load_lds_dwordx4 v159, s[86:87]
	s_add_u32 s86, s86, 128
	s_addc_u32 s87, s87, 0
	s_waitcnt lgkmcnt(4)
	v_mfma_f32_16x16x32_bf16 v[28:31], v[96:99], v[196:199], v[28:31]
	v_mfma_f32_16x16x32_bf16 v[60:63], v[164:167], v[196:199], v[60:63]
	v_mfma_f32_16x16x32_bf16 v[248:251], v[168:171], v[196:199], v[248:251]
	v_mfma_f32_16x16x32_bf16 v[124:127], v[172:175], v[196:199], v[124:127]
	s_waitcnt vmcnt(8)
	ds_read_b128 v[192:195], v212 offset:8192
	global_load_dwordx4 v[96:99], v142, s[84:85] offset:0
	s_waitcnt lgkmcnt(4)
	v_mfma_f32_16x16x32_bf16 v[0:3], v[64:67], v[160:163], v[0:3]
	v_mfma_f32_16x16x32_bf16 v[32:35], v[68:71], v[160:163], v[32:35]
	v_mfma_f32_16x16x32_bf16 v[144:147], v[72:75], v[160:163], v[144:147]
	v_mfma_f32_16x16x32_bf16 v[252:255], v[76:79], v[160:163], v[252:255]
	ds_read_b128 v[196:199], v212 offset:10240
	global_load_dwordx4 v[164:167], v150, s[84:85] offset:0
	s_waitcnt lgkmcnt(4)
	v_mfma_f32_16x16x32_bf16 v[4:7], v[64:67], v[176:179], v[4:7]
	v_mfma_f32_16x16x32_bf16 v[36:39], v[68:71], v[176:179], v[36:39]
	v_mfma_f32_16x16x32_bf16 v[184:187], v[72:75], v[176:179], v[184:187]
	v_mfma_f32_16x16x32_bf16 v[100:103], v[76:79], v[176:179], v[100:103]
	ds_read_b128 v[160:163], v212 offset:12288
	global_load_dwordx4 v[168:171], v142, s[92:93] offset:0
	s_waitcnt lgkmcnt(4)
	v_mfma_f32_16x16x32_bf16 v[8:11], v[64:67], v[180:183], v[8:11]
	v_mfma_f32_16x16x32_bf16 v[40:43], v[68:71], v[180:183], v[40:43]
	v_mfma_f32_16x16x32_bf16 v[204:207], v[72:75], v[180:183], v[204:207]
	v_mfma_f32_16x16x32_bf16 v[104:107], v[76:79], v[180:183], v[104:107]
	ds_read_b128 v[176:179], v212 offset:14336
	global_load_dwordx4 v[172:175], v150, s[92:93] offset:0
	s_waitcnt lgkmcnt(4)
	v_mfma_f32_16x16x32_bf16 v[12:15], v[64:67], v[188:191], v[12:15]
	v_mfma_f32_16x16x32_bf16 v[44:47], v[68:71], v[188:191], v[44:47]
	v_mfma_f32_16x16x32_bf16 v[208:211], v[72:75], v[188:191], v[208:211]
	v_mfma_f32_16x16x32_bf16 v[108:111], v[76:79], v[188:191], v[108:111]
	ds_read_b128 v[180:183], v213 offset:0
	s_waitcnt lgkmcnt(4)
	v_mfma_f32_16x16x32_bf16 v[16:19], v[64:67], v[192:195], v[16:19]
	v_mfma_f32_16x16x32_bf16 v[48:51], v[68:71], v[192:195], v[48:51]
	v_mfma_f32_16x16x32_bf16 v[232:235], v[72:75], v[192:195], v[232:235]
	v_mfma_f32_16x16x32_bf16 v[112:115], v[76:79], v[192:195], v[112:115]
	ds_read_b128 v[188:191], v213 offset:2048
	s_waitcnt lgkmcnt(4)
	v_mfma_f32_16x16x32_bf16 v[20:23], v[64:67], v[196:199], v[20:23]
	v_mfma_f32_16x16x32_bf16 v[52:55], v[68:71], v[196:199], v[52:55]
	v_mfma_f32_16x16x32_bf16 v[236:239], v[72:75], v[196:199], v[236:239]
	v_mfma_f32_16x16x32_bf16 v[116:119], v[76:79], v[196:199], v[116:119]
	ds_read_b128 v[192:195], v213 offset:4096
	s_waitcnt lgkmcnt(4)
	v_mfma_f32_16x16x32_bf16 v[24:27], v[64:67], v[160:163], v[24:27]
	v_mfma_f32_16x16x32_bf16 v[56:59], v[68:71], v[160:163], v[56:59]
	v_mfma_f32_16x16x32_bf16 v[240:243], v[72:75], v[160:163], v[240:243]
	v_mfma_f32_16x16x32_bf16 v[120:123], v[76:79], v[160:163], v[120:123]
	ds_read_b128 v[196:199], v213 offset:6144
	s_waitcnt lgkmcnt(4)
	v_mfma_f32_16x16x32_bf16 v[28:31], v[64:67], v[176:179], v[28:31]
	v_mfma_f32_16x16x32_bf16 v[60:63], v[68:71], v[176:179], v[60:63]
	v_mfma_f32_16x16x32_bf16 v[248:251], v[72:75], v[176:179], v[248:251]
	v_mfma_f32_16x16x32_bf16 v[124:127], v[76:79], v[176:179], v[124:127]
	s_waitcnt vmcnt(16)
	s_barrier
	s_waitcnt vmcnt(8)
	ds_read_b128 v[160:163], v213 offset:8192
	global_load_dwordx4 v[64:67], v142, s[84:85] offset:1024
	s_waitcnt lgkmcnt(4)
	v_mfma_f32_16x16x32_bf16 v[0:3], v[80:83], v[180:183], v[0:3]
	v_mfma_f32_16x16x32_bf16 v[32:35], v[84:87], v[180:183], v[32:35]
	v_mfma_f32_16x16x32_bf16 v[144:147], v[88:91], v[180:183], v[144:147]
	v_mfma_f32_16x16x32_bf16 v[252:255], v[92:95], v[180:183], v[252:255]
	ds_read_b128 v[176:179], v213 offset:10240
	global_load_dwordx4 v[68:71], v150, s[84:85] offset:1024
	s_waitcnt lgkmcnt(4)
	v_mfma_f32_16x16x32_bf16 v[4:7], v[80:83], v[188:191], v[4:7]
	v_mfma_f32_16x16x32_bf16 v[36:39], v[84:87], v[188:191], v[36:39]
	v_mfma_f32_16x16x32_bf16 v[184:187], v[88:91], v[188:191], v[184:187]
	v_mfma_f32_16x16x32_bf16 v[100:103], v[92:95], v[188:191], v[100:103]
	ds_read_b128 v[180:183], v213 offset:12288
	global_load_dwordx4 v[72:75], v142, s[92:93] offset:1024
	s_waitcnt lgkmcnt(4)
	v_mfma_f32_16x16x32_bf16 v[8:11], v[80:83], v[192:195], v[8:11]
	v_mfma_f32_16x16x32_bf16 v[40:43], v[84:87], v[192:195], v[40:43]
	v_mfma_f32_16x16x32_bf16 v[204:207], v[88:91], v[192:195], v[204:207]
	v_mfma_f32_16x16x32_bf16 v[104:107], v[92:95], v[192:195], v[104:107]
	ds_read_b128 v[188:191], v213 offset:14336
	global_load_dwordx4 v[76:79], v150, s[92:93] offset:1024
	s_add_u32 s84, s84, 0x800
	s_addc_u32 s85, s85, 0
	s_add_u32 s92, s92, 0x800
	s_addc_u32 s93, s93, 0
	s_waitcnt lgkmcnt(4)
	v_mfma_f32_16x16x32_bf16 v[12:15], v[80:83], v[196:199], v[12:15]
	v_mfma_f32_16x16x32_bf16 v[44:47], v[84:87], v[196:199], v[44:47]
	v_mfma_f32_16x16x32_bf16 v[208:211], v[88:91], v[196:199], v[208:211]
	v_mfma_f32_16x16x32_bf16 v[108:111], v[92:95], v[196:199], v[108:111]
	ds_read_b128 v[192:195], v212 offset:16384
	s_add_u32 m0, s1, 49152
	s_nop 0
	global_load_lds_dwordx4 v151, s[86:87]
	s_waitcnt lgkmcnt(4)
	v_mfma_f32_16x16x32_bf16 v[16:19], v[80:83], v[160:163], v[16:19]
	v_mfma_f32_16x16x32_bf16 v[48:51], v[84:87], v[160:163], v[48:51]
	v_mfma_f32_16x16x32_bf16 v[232:235], v[88:91], v[160:163], v[232:235]
	v_mfma_f32_16x16x32_bf16 v[112:115], v[92:95], v[160:163], v[112:115]
	ds_read_b128 v[196:199], v212 offset:18432
	s_add_u32 m0, s1, 53248
	s_nop 0
	global_load_lds_dwordx4 v156, s[86:87]
	s_waitcnt lgkmcnt(4)
	v_mfma_f32_16x16x32_bf16 v[20:23], v[80:83], v[176:179], v[20:23]
	v_mfma_f32_16x16x32_bf16 v[52:55], v[84:87], v[176:179], v[52:55]
	v_mfma_f32_16x16x32_bf16 v[236:239], v[88:91], v[176:179], v[236:239]
	v_mfma_f32_16x16x32_bf16 v[116:119], v[92:95], v[176:179], v[116:119]
	ds_read_b128 v[160:163], v212 offset:20480
	s_add_u32 m0, s1, 57344
	s_nop 0
	global_load_lds_dwordx4 v158, s[86:87]
	s_waitcnt lgkmcnt(4)
	v_mfma_f32_16x16x32_bf16 v[24:27], v[80:83], v[180:183], v[24:27]
	v_mfma_f32_16x16x32_bf16 v[56:59], v[84:87], v[180:183], v[56:59]
	v_mfma_f32_16x16x32_bf16 v[240:243], v[88:91], v[180:183], v[240:243]
	v_mfma_f32_16x16x32_bf16 v[120:123], v[92:95], v[180:183], v[120:123]
	ds_read_b128 v[176:179], v212 offset:22528
	s_add_u32 m0, s1, 61440
	s_nop 0
	global_load_lds_dwordx4 v159, s[86:87]
	s_add_u32 s86, s86, 128
	s_addc_u32 s87, s87, 0
	s_waitcnt lgkmcnt(4)
	v_mfma_f32_16x16x32_bf16 v[28:31], v[80:83], v[188:191], v[28:31]
	v_mfma_f32_16x16x32_bf16 v[60:63], v[84:87], v[188:191], v[60:63]
	v_mfma_f32_16x16x32_bf16 v[248:251], v[88:91], v[188:191], v[248:251]
	v_mfma_f32_16x16x32_bf16 v[124:127], v[92:95], v[188:191], v[124:127]
	s_waitcnt vmcnt(8)
	ds_read_b128 v[180:183], v212 offset:24576
	global_load_dwordx4 v[80:83], v142, s[84:85] offset:0
	s_waitcnt lgkmcnt(4)
	v_mfma_f32_16x16x32_bf16 v[0:3], v[96:99], v[192:195], v[0:3]
	v_mfma_f32_16x16x32_bf16 v[32:35], v[164:167], v[192:195], v[32:35]
	v_mfma_f32_16x16x32_bf16 v[144:147], v[168:171], v[192:195], v[144:147]
	v_mfma_f32_16x16x32_bf16 v[252:255], v[172:175], v[192:195], v[252:255]
	ds_read_b128 v[188:191], v212 offset:26624
	global_load_dwordx4 v[84:87], v150, s[84:85] offset:0
	s_waitcnt lgkmcnt(4)
	v_mfma_f32_16x16x32_bf16 v[4:7], v[96:99], v[196:199], v[4:7]
	v_mfma_f32_16x16x32_bf16 v[36:39], v[164:167], v[196:199], v[36:39]
	v_mfma_f32_16x16x32_bf16 v[184:187], v[168:171], v[196:199], v[184:187]
	v_mfma_f32_16x16x32_bf16 v[100:103], v[172:175], v[196:199], v[100:103]
	ds_read_b128 v[192:195], v212 offset:28672
	global_load_dwordx4 v[88:91], v142, s[92:93] offset:0
	s_waitcnt lgkmcnt(4)
	v_mfma_f32_16x16x32_bf16 v[8:11], v[96:99], v[160:163], v[8:11]
	v_mfma_f32_16x16x32_bf16 v[40:43], v[164:167], v[160:163], v[40:43]
	v_mfma_f32_16x16x32_bf16 v[204:207], v[168:171], v[160:163], v[204:207]
	v_mfma_f32_16x16x32_bf16 v[104:107], v[172:175], v[160:163], v[104:107]
	ds_read_b128 v[196:199], v212 offset:30720
	global_load_dwordx4 v[92:95], v150, s[92:93] offset:0
	s_waitcnt lgkmcnt(4)
	v_mfma_f32_16x16x32_bf16 v[12:15], v[96:99], v[176:179], v[12:15]
	v_mfma_f32_16x16x32_bf16 v[44:47], v[164:167], v[176:179], v[44:47]
	v_mfma_f32_16x16x32_bf16 v[208:211], v[168:171], v[176:179], v[208:211]
	v_mfma_f32_16x16x32_bf16 v[108:111], v[172:175], v[176:179], v[108:111]
	ds_read_b128 v[160:163], v213 offset:16384
	s_waitcnt lgkmcnt(4)
	v_mfma_f32_16x16x32_bf16 v[16:19], v[96:99], v[180:183], v[16:19]
	v_mfma_f32_16x16x32_bf16 v[48:51], v[164:167], v[180:183], v[48:51]
	v_mfma_f32_16x16x32_bf16 v[232:235], v[168:171], v[180:183], v[232:235]
	v_mfma_f32_16x16x32_bf16 v[112:115], v[172:175], v[180:183], v[112:115]
	ds_read_b128 v[176:179], v213 offset:18432
	s_waitcnt lgkmcnt(4)
	v_mfma_f32_16x16x32_bf16 v[20:23], v[96:99], v[188:191], v[20:23]
	v_mfma_f32_16x16x32_bf16 v[52:55], v[164:167], v[188:191], v[52:55]
	v_mfma_f32_16x16x32_bf16 v[236:239], v[168:171], v[188:191], v[236:239]
	v_mfma_f32_16x16x32_bf16 v[116:119], v[172:175], v[188:191], v[116:119]
	ds_read_b128 v[180:183], v213 offset:20480
	s_waitcnt lgkmcnt(4)
	v_mfma_f32_16x16x32_bf16 v[24:27], v[96:99], v[192:195], v[24:27]
	v_mfma_f32_16x16x32_bf16 v[56:59], v[164:167], v[192:195], v[56:59]
	v_mfma_f32_16x16x32_bf16 v[240:243], v[168:171], v[192:195], v[240:243]
	v_mfma_f32_16x16x32_bf16 v[120:123], v[172:175], v[192:195], v[120:123]
	ds_read_b128 v[188:191], v213 offset:22528
	s_waitcnt lgkmcnt(4)
	v_mfma_f32_16x16x32_bf16 v[28:31], v[96:99], v[196:199], v[28:31]
	v_mfma_f32_16x16x32_bf16 v[60:63], v[164:167], v[196:199], v[60:63]
	v_mfma_f32_16x16x32_bf16 v[248:251], v[168:171], v[196:199], v[248:251]
	v_mfma_f32_16x16x32_bf16 v[124:127], v[172:175], v[196:199], v[124:127]
	s_waitcnt vmcnt(16)
	s_barrier
	s_waitcnt vmcnt(8)
	ds_read_b128 v[192:195], v213 offset:24576
	global_load_dwordx4 v[96:99], v142, s[84:85] offset:1024
	s_waitcnt lgkmcnt(4)
	v_mfma_f32_16x16x32_bf16 v[0:3], v[64:67], v[160:163], v[0:3]
	v_mfma_f32_16x16x32_bf16 v[32:35], v[68:71], v[160:163], v[32:35]
	v_mfma_f32_16x16x32_bf16 v[144:147], v[72:75], v[160:163], v[144:147]
	v_mfma_f32_16x16x32_bf16 v[252:255], v[76:79], v[160:163], v[252:255]
	ds_read_b128 v[196:199], v213 offset:26624
	global_load_dwordx4 v[164:167], v150, s[84:85] offset:1024
	s_waitcnt lgkmcnt(4)
	v_mfma_f32_16x16x32_bf16 v[4:7], v[64:67], v[176:179], v[4:7]
	v_mfma_f32_16x16x32_bf16 v[36:39], v[68:71], v[176:179], v[36:39]
	v_mfma_f32_16x16x32_bf16 v[184:187], v[72:75], v[176:179], v[184:187]
	v_mfma_f32_16x16x32_bf16 v[100:103], v[76:79], v[176:179], v[100:103]
	ds_read_b128 v[160:163], v213 offset:28672
	global_load_dwordx4 v[168:171], v142, s[92:93] offset:1024
	s_waitcnt lgkmcnt(4)
	v_mfma_f32_16x16x32_bf16 v[8:11], v[64:67], v[180:183], v[8:11]
	v_mfma_f32_16x16x32_bf16 v[40:43], v[68:71], v[180:183], v[40:43]
	v_mfma_f32_16x16x32_bf16 v[204:207], v[72:75], v[180:183], v[204:207]
	v_mfma_f32_16x16x32_bf16 v[104:107], v[76:79], v[180:183], v[104:107]
	ds_read_b128 v[176:179], v213 offset:30720
	global_load_dwordx4 v[172:175], v150, s[92:93] offset:1024
	s_add_u32 s84, s84, 0x800
	s_addc_u32 s85, s85, 0
	s_add_u32 s92, s92, 0x800
	s_addc_u32 s93, s93, 0
	s_waitcnt lgkmcnt(4)
	v_mfma_f32_16x16x32_bf16 v[12:15], v[64:67], v[188:191], v[12:15]
	v_mfma_f32_16x16x32_bf16 v[44:47], v[68:71], v[188:191], v[44:47]
	v_mfma_f32_16x16x32_bf16 v[208:211], v[72:75], v[188:191], v[208:211]
	v_mfma_f32_16x16x32_bf16 v[108:111], v[76:79], v[188:191], v[108:111]
	ds_read_b128 v[180:183], v212 offset:32768
	s_waitcnt lgkmcnt(4)
	v_mfma_f32_16x16x32_bf16 v[16:19], v[64:67], v[192:195], v[16:19]
	v_mfma_f32_16x16x32_bf16 v[48:51], v[68:71], v[192:195], v[48:51]
	v_mfma_f32_16x16x32_bf16 v[232:235], v[72:75], v[192:195], v[232:235]
	v_mfma_f32_16x16x32_bf16 v[112:115], v[76:79], v[192:195], v[112:115]
	ds_read_b128 v[188:191], v212 offset:34816
	s_waitcnt lgkmcnt(4)
	v_mfma_f32_16x16x32_bf16 v[20:23], v[64:67], v[196:199], v[20:23]
	v_mfma_f32_16x16x32_bf16 v[52:55], v[68:71], v[196:199], v[52:55]
	v_mfma_f32_16x16x32_bf16 v[236:239], v[72:75], v[196:199], v[236:239]
	v_mfma_f32_16x16x32_bf16 v[116:119], v[76:79], v[196:199], v[116:119]
	ds_read_b128 v[192:195], v212 offset:36864
	s_waitcnt lgkmcnt(4)
	v_mfma_f32_16x16x32_bf16 v[24:27], v[64:67], v[160:163], v[24:27]
	v_mfma_f32_16x16x32_bf16 v[56:59], v[68:71], v[160:163], v[56:59]
	v_mfma_f32_16x16x32_bf16 v[240:243], v[72:75], v[160:163], v[240:243]
	v_mfma_f32_16x16x32_bf16 v[120:123], v[76:79], v[160:163], v[120:123]
	ds_read_b128 v[196:199], v212 offset:38912
	s_waitcnt lgkmcnt(4)
	v_mfma_f32_16x16x32_bf16 v[28:31], v[64:67], v[176:179], v[28:31]
	v_mfma_f32_16x16x32_bf16 v[60:63], v[68:71], v[176:179], v[60:63]
	v_mfma_f32_16x16x32_bf16 v[248:251], v[72:75], v[176:179], v[248:251]
	v_mfma_f32_16x16x32_bf16 v[124:127], v[76:79], v[176:179], v[124:127]
	s_waitcnt vmcnt(4)
	ds_read_b128 v[160:163], v212 offset:40960
	global_load_dwordx4 v[64:67], v142, s[84:85] offset:0
	s_waitcnt lgkmcnt(4)
	v_mfma_f32_16x16x32_bf16 v[0:3], v[80:83], v[180:183], v[0:3]
	v_mfma_f32_16x16x32_bf16 v[32:35], v[84:87], v[180:183], v[32:35]
	v_mfma_f32_16x16x32_bf16 v[144:147], v[88:91], v[180:183], v[144:147]
	v_mfma_f32_16x16x32_bf16 v[252:255], v[92:95], v[180:183], v[252:255]
	ds_read_b128 v[176:179], v212 offset:43008
	global_load_dwordx4 v[68:71], v150, s[84:85] offset:0
	s_waitcnt lgkmcnt(4)
	v_mfma_f32_16x16x32_bf16 v[4:7], v[80:83], v[188:191], v[4:7]
	v_mfma_f32_16x16x32_bf16 v[36:39], v[84:87], v[188:191], v[36:39]
	v_mfma_f32_16x16x32_bf16 v[184:187], v[88:91], v[188:191], v[184:187]
	v_mfma_f32_16x16x32_bf16 v[100:103], v[92:95], v[188:191], v[100:103]
	ds_read_b128 v[180:183], v212 offset:45056
	global_load_dwordx4 v[72:75], v142, s[92:93] offset:0
	s_waitcnt lgkmcnt(4)
	v_mfma_f32_16x16x32_bf16 v[8:11], v[80:83], v[192:195], v[8:11]
	v_mfma_f32_16x16x32_bf16 v[40:43], v[84:87], v[192:195], v[40:43]
	v_mfma_f32_16x16x32_bf16 v[204:207], v[88:91], v[192:195], v[204:207]
	v_mfma_f32_16x16x32_bf16 v[104:107], v[92:95], v[192:195], v[104:107]
	ds_read_b128 v[188:191], v212 offset:47104
	global_load_dwordx4 v[76:79], v150, s[92:93] offset:0
	s_waitcnt lgkmcnt(4)
	v_mfma_f32_16x16x32_bf16 v[12:15], v[80:83], v[196:199], v[12:15]
	v_mfma_f32_16x16x32_bf16 v[44:47], v[84:87], v[196:199], v[44:47]
	v_mfma_f32_16x16x32_bf16 v[208:211], v[88:91], v[196:199], v[208:211]
	v_mfma_f32_16x16x32_bf16 v[108:111], v[92:95], v[196:199], v[108:111]
	ds_read_b128 v[192:195], v213 offset:32768
	s_waitcnt lgkmcnt(4)
	v_mfma_f32_16x16x32_bf16 v[16:19], v[80:83], v[160:163], v[16:19]
	v_mfma_f32_16x16x32_bf16 v[48:51], v[84:87], v[160:163], v[48:51]
	v_mfma_f32_16x16x32_bf16 v[232:235], v[88:91], v[160:163], v[232:235]
	v_mfma_f32_16x16x32_bf16 v[112:115], v[92:95], v[160:163], v[112:115]
	ds_read_b128 v[196:199], v213 offset:34816
	s_waitcnt lgkmcnt(4)
	v_mfma_f32_16x16x32_bf16 v[20:23], v[80:83], v[176:179], v[20:23]
	v_mfma_f32_16x16x32_bf16 v[52:55], v[84:87], v[176:179], v[52:55]
	v_mfma_f32_16x16x32_bf16 v[236:239], v[88:91], v[176:179], v[236:239]
	v_mfma_f32_16x16x32_bf16 v[116:119], v[92:95], v[176:179], v[116:119]
	ds_read_b128 v[160:163], v213 offset:36864
	s_waitcnt lgkmcnt(4)
	v_mfma_f32_16x16x32_bf16 v[24:27], v[80:83], v[180:183], v[24:27]
	v_mfma_f32_16x16x32_bf16 v[56:59], v[84:87], v[180:183], v[56:59]
	v_mfma_f32_16x16x32_bf16 v[240:243], v[88:91], v[180:183], v[240:243]
	v_mfma_f32_16x16x32_bf16 v[120:123], v[92:95], v[180:183], v[120:123]
	ds_read_b128 v[176:179], v213 offset:38912
	s_waitcnt lgkmcnt(4)
	v_mfma_f32_16x16x32_bf16 v[28:31], v[80:83], v[188:191], v[28:31]
	v_mfma_f32_16x16x32_bf16 v[60:63], v[84:87], v[188:191], v[60:63]
	v_mfma_f32_16x16x32_bf16 v[248:251], v[88:91], v[188:191], v[248:251]
	v_mfma_f32_16x16x32_bf16 v[124:127], v[92:95], v[188:191], v[124:127]
	s_waitcnt vmcnt(12)
	s_barrier
	s_waitcnt vmcnt(4)
	ds_read_b128 v[180:183], v213 offset:40960
	global_load_dwordx4 v[80:83], v142, s[84:85] offset:1024
	s_waitcnt lgkmcnt(4)
	v_mfma_f32_16x16x32_bf16 v[0:3], v[96:99], v[192:195], v[0:3]
	v_mfma_f32_16x16x32_bf16 v[32:35], v[164:167], v[192:195], v[32:35]
	v_mfma_f32_16x16x32_bf16 v[144:147], v[168:171], v[192:195], v[144:147]
	v_mfma_f32_16x16x32_bf16 v[252:255], v[172:175], v[192:195], v[252:255]
	ds_read_b128 v[188:191], v213 offset:43008
	global_load_dwordx4 v[84:87], v150, s[84:85] offset:1024
	s_waitcnt lgkmcnt(4)
	v_mfma_f32_16x16x32_bf16 v[4:7], v[96:99], v[196:199], v[4:7]
	v_mfma_f32_16x16x32_bf16 v[36:39], v[164:167], v[196:199], v[36:39]
	v_mfma_f32_16x16x32_bf16 v[184:187], v[168:171], v[196:199], v[184:187]
	v_mfma_f32_16x16x32_bf16 v[100:103], v[172:175], v[196:199], v[100:103]
	ds_read_b128 v[192:195], v213 offset:45056
	global_load_dwordx4 v[88:91], v142, s[92:93] offset:1024
	s_waitcnt lgkmcnt(4)
	v_mfma_f32_16x16x32_bf16 v[8:11], v[96:99], v[160:163], v[8:11]
	v_mfma_f32_16x16x32_bf16 v[40:43], v[164:167], v[160:163], v[40:43]
	v_mfma_f32_16x16x32_bf16 v[204:207], v[168:171], v[160:163], v[204:207]
	v_mfma_f32_16x16x32_bf16 v[104:107], v[172:175], v[160:163], v[104:107]
	ds_read_b128 v[196:199], v213 offset:47104
	global_load_dwordx4 v[92:95], v150, s[92:93] offset:1024
	s_add_u32 s84, s84, 0x800
	s_addc_u32 s85, s85, 0
	s_add_u32 s92, s92, 0x800
	s_addc_u32 s93, s93, 0
	s_waitcnt lgkmcnt(4)
	v_mfma_f32_16x16x32_bf16 v[12:15], v[96:99], v[176:179], v[12:15]
	v_mfma_f32_16x16x32_bf16 v[44:47], v[164:167], v[176:179], v[44:47]
	v_mfma_f32_16x16x32_bf16 v[208:211], v[168:171], v[176:179], v[208:211]
	v_mfma_f32_16x16x32_bf16 v[108:111], v[172:175], v[176:179], v[108:111]
	ds_read_b128 v[160:163], v212 offset:49152
	s_waitcnt lgkmcnt(4)
	v_mfma_f32_16x16x32_bf16 v[16:19], v[96:99], v[180:183], v[16:19]
	v_mfma_f32_16x16x32_bf16 v[48:51], v[164:167], v[180:183], v[48:51]
	v_mfma_f32_16x16x32_bf16 v[232:235], v[168:171], v[180:183], v[232:235]
	v_mfma_f32_16x16x32_bf16 v[112:115], v[172:175], v[180:183], v[112:115]
	ds_read_b128 v[176:179], v212 offset:51200
	s_waitcnt lgkmcnt(4)
	v_mfma_f32_16x16x32_bf16 v[20:23], v[96:99], v[188:191], v[20:23]
	v_mfma_f32_16x16x32_bf16 v[52:55], v[164:167], v[188:191], v[52:55]
	v_mfma_f32_16x16x32_bf16 v[236:239], v[168:171], v[188:191], v[236:239]
	v_mfma_f32_16x16x32_bf16 v[116:119], v[172:175], v[188:191], v[116:119]
	ds_read_b128 v[180:183], v212 offset:53248
	s_waitcnt lgkmcnt(4)
	v_mfma_f32_16x16x32_bf16 v[24:27], v[96:99], v[192:195], v[24:27]
	v_mfma_f32_16x16x32_bf16 v[56:59], v[164:167], v[192:195], v[56:59]
	v_mfma_f32_16x16x32_bf16 v[240:243], v[168:171], v[192:195], v[240:243]
	v_mfma_f32_16x16x32_bf16 v[120:123], v[172:175], v[192:195], v[120:123]
	ds_read_b128 v[188:191], v212 offset:55296
	s_waitcnt lgkmcnt(4)
	v_mfma_f32_16x16x32_bf16 v[28:31], v[96:99], v[196:199], v[28:31]
	v_mfma_f32_16x16x32_bf16 v[60:63], v[164:167], v[196:199], v[60:63]
	v_mfma_f32_16x16x32_bf16 v[248:251], v[168:171], v[196:199], v[248:251]
	v_mfma_f32_16x16x32_bf16 v[124:127], v[172:175], v[196:199], v[124:127]
	s_waitcnt vmcnt(4)
	ds_read_b128 v[192:195], v212 offset:57344
	s_waitcnt lgkmcnt(4)
	v_mfma_f32_16x16x32_bf16 v[0:3], v[64:67], v[160:163], v[0:3]
	v_mfma_f32_16x16x32_bf16 v[32:35], v[68:71], v[160:163], v[32:35]
	v_mfma_f32_16x16x32_bf16 v[144:147], v[72:75], v[160:163], v[144:147]
	v_mfma_f32_16x16x32_bf16 v[252:255], v[76:79], v[160:163], v[252:255]
	ds_read_b128 v[196:199], v212 offset:59392
	s_waitcnt lgkmcnt(4)
	v_mfma_f32_16x16x32_bf16 v[4:7], v[64:67], v[176:179], v[4:7]
	v_mfma_f32_16x16x32_bf16 v[36:39], v[68:71], v[176:179], v[36:39]
	v_mfma_f32_16x16x32_bf16 v[184:187], v[72:75], v[176:179], v[184:187]
	v_mfma_f32_16x16x32_bf16 v[100:103], v[76:79], v[176:179], v[100:103]
	ds_read_b128 v[160:163], v212 offset:61440
	s_waitcnt lgkmcnt(4)
	v_mfma_f32_16x16x32_bf16 v[8:11], v[64:67], v[180:183], v[8:11]
	v_mfma_f32_16x16x32_bf16 v[40:43], v[68:71], v[180:183], v[40:43]
	v_mfma_f32_16x16x32_bf16 v[204:207], v[72:75], v[180:183], v[204:207]
	v_mfma_f32_16x16x32_bf16 v[104:107], v[76:79], v[180:183], v[104:107]
	ds_read_b128 v[176:179], v212 offset:63488
	s_waitcnt lgkmcnt(4)
	v_mfma_f32_16x16x32_bf16 v[12:15], v[64:67], v[188:191], v[12:15]
	v_mfma_f32_16x16x32_bf16 v[44:47], v[68:71], v[188:191], v[44:47]
	v_mfma_f32_16x16x32_bf16 v[208:211], v[72:75], v[188:191], v[208:211]
	v_mfma_f32_16x16x32_bf16 v[108:111], v[76:79], v[188:191], v[108:111]
	ds_read_b128 v[180:183], v213 offset:49152
	s_waitcnt lgkmcnt(4)
	v_mfma_f32_16x16x32_bf16 v[16:19], v[64:67], v[192:195], v[16:19]
	v_mfma_f32_16x16x32_bf16 v[48:51], v[68:71], v[192:195], v[48:51]
	v_mfma_f32_16x16x32_bf16 v[232:235], v[72:75], v[192:195], v[232:235]
	v_mfma_f32_16x16x32_bf16 v[112:115], v[76:79], v[192:195], v[112:115]
	ds_read_b128 v[188:191], v213 offset:51200
	s_waitcnt lgkmcnt(4)
	v_mfma_f32_16x16x32_bf16 v[20:23], v[64:67], v[196:199], v[20:23]
	v_mfma_f32_16x16x32_bf16 v[52:55], v[68:71], v[196:199], v[52:55]
	v_mfma_f32_16x16x32_bf16 v[236:239], v[72:75], v[196:199], v[236:239]
	v_mfma_f32_16x16x32_bf16 v[116:119], v[76:79], v[196:199], v[116:119]
	ds_read_b128 v[192:195], v213 offset:53248
	s_waitcnt lgkmcnt(4)
	v_mfma_f32_16x16x32_bf16 v[24:27], v[64:67], v[160:163], v[24:27]
	v_mfma_f32_16x16x32_bf16 v[56:59], v[68:71], v[160:163], v[56:59]
	v_mfma_f32_16x16x32_bf16 v[240:243], v[72:75], v[160:163], v[240:243]
	v_mfma_f32_16x16x32_bf16 v[120:123], v[76:79], v[160:163], v[120:123]
	ds_read_b128 v[196:199], v213 offset:55296
	s_waitcnt lgkmcnt(4)
	v_mfma_f32_16x16x32_bf16 v[28:31], v[64:67], v[176:179], v[28:31]
	v_mfma_f32_16x16x32_bf16 v[60:63], v[68:71], v[176:179], v[60:63]
	v_mfma_f32_16x16x32_bf16 v[248:251], v[72:75], v[176:179], v[248:251]
	v_mfma_f32_16x16x32_bf16 v[124:127], v[76:79], v[176:179], v[124:127]
	s_waitcnt vmcnt(0)
	ds_read_b128 v[160:163], v213 offset:57344
	s_waitcnt lgkmcnt(4)
	v_mfma_f32_16x16x32_bf16 v[0:3], v[80:83], v[180:183], v[0:3]
	v_mfma_f32_16x16x32_bf16 v[32:35], v[84:87], v[180:183], v[32:35]
	v_mfma_f32_16x16x32_bf16 v[144:147], v[88:91], v[180:183], v[144:147]
	v_mfma_f32_16x16x32_bf16 v[252:255], v[92:95], v[180:183], v[252:255]
	ds_read_b128 v[176:179], v213 offset:59392
	s_waitcnt lgkmcnt(4)
	v_mfma_f32_16x16x32_bf16 v[4:7], v[80:83], v[188:191], v[4:7]
	v_mfma_f32_16x16x32_bf16 v[36:39], v[84:87], v[188:191], v[36:39]
	v_mfma_f32_16x16x32_bf16 v[184:187], v[88:91], v[188:191], v[184:187]
	v_mfma_f32_16x16x32_bf16 v[100:103], v[92:95], v[188:191], v[100:103]
	ds_read_b128 v[180:183], v213 offset:61440
	s_waitcnt lgkmcnt(4)
	v_mfma_f32_16x16x32_bf16 v[8:11], v[80:83], v[192:195], v[8:11]
	v_mfma_f32_16x16x32_bf16 v[40:43], v[84:87], v[192:195], v[40:43]
	v_mfma_f32_16x16x32_bf16 v[204:207], v[88:91], v[192:195], v[204:207]
	v_mfma_f32_16x16x32_bf16 v[104:107], v[92:95], v[192:195], v[104:107]
	ds_read_b128 v[188:191], v213 offset:63488
	s_waitcnt lgkmcnt(4)
	v_mfma_f32_16x16x32_bf16 v[12:15], v[80:83], v[196:199], v[12:15]
	v_mfma_f32_16x16x32_bf16 v[44:47], v[84:87], v[196:199], v[44:47]
	v_mfma_f32_16x16x32_bf16 v[208:211], v[88:91], v[196:199], v[208:211]
	v_mfma_f32_16x16x32_bf16 v[108:111], v[92:95], v[196:199], v[108:111]
	s_waitcnt lgkmcnt(3)
	v_mfma_f32_16x16x32_bf16 v[16:19], v[80:83], v[160:163], v[16:19]
	v_mfma_f32_16x16x32_bf16 v[48:51], v[84:87], v[160:163], v[48:51]
	v_mfma_f32_16x16x32_bf16 v[232:235], v[88:91], v[160:163], v[232:235]
	v_mfma_f32_16x16x32_bf16 v[112:115], v[92:95], v[160:163], v[112:115]
	s_waitcnt lgkmcnt(2)
	v_mfma_f32_16x16x32_bf16 v[20:23], v[80:83], v[176:179], v[20:23]
	v_mfma_f32_16x16x32_bf16 v[52:55], v[84:87], v[176:179], v[52:55]
	v_mfma_f32_16x16x32_bf16 v[236:239], v[88:91], v[176:179], v[236:239]
	v_mfma_f32_16x16x32_bf16 v[116:119], v[92:95], v[176:179], v[116:119]
	s_waitcnt lgkmcnt(1)
	v_mfma_f32_16x16x32_bf16 v[24:27], v[80:83], v[180:183], v[24:27]
	v_mfma_f32_16x16x32_bf16 v[56:59], v[84:87], v[180:183], v[56:59]
	v_mfma_f32_16x16x32_bf16 v[240:243], v[88:91], v[180:183], v[240:243]
	v_mfma_f32_16x16x32_bf16 v[120:123], v[92:95], v[180:183], v[120:123]
	s_waitcnt lgkmcnt(0)
	v_mfma_f32_16x16x32_bf16 v[28:31], v[80:83], v[188:191], v[28:31]
	v_mfma_f32_16x16x32_bf16 v[60:63], v[84:87], v[188:191], v[60:63]
	v_mfma_f32_16x16x32_bf16 v[248:251], v[88:91], v[188:191], v[248:251]
	v_mfma_f32_16x16x32_bf16 v[124:127], v[92:95], v[188:191], v[124:127]
	s_nop 7
	s_nop 7
	s_waitcnt vmcnt(0) lgkmcnt(0)
	s_barrier
	v_mov_b32_e32 v150, v100
	v_mov_b32_e32 v151, v101
	v_mov_b32_e32 v156, v102
	v_mov_b32_e32 v158, v103
	v_mov_b32_e32 v159, v104
	v_mov_b32_e32 v160, v105
	v_mov_b32_e32 v183, v106
	v_mov_b32_e32 v188, v107
	v_mov_b32_e32 v189, v108
	v_mov_b32_e32 v212, v109
	v_mov_b32_e32 v213, v110
	v_mov_b32_e32 v214, v111
	v_mov_b32_e32 v216, v112
	v_mov_b32_e32 v218, v113
	v_mov_b32_e32 v220, v114
	v_mov_b32_e32 v222, v115
	v_mov_b32_e32 v224, v116
	v_mov_b32_e32 v226, v117
	v_mov_b32_e32 v228, v118
	v_mov_b32_e32 v230, v119
	v_mov_b32_e32 v231, v120
	v_mov_b32_e32 v244, v121
	v_mov_b32_e32 v245, v122
	ds_write_b32 v140, v123 offset:40960
	ds_write_b32 v140, v124 offset:41984
	ds_write_b32 v140, v125 offset:43008
	ds_write_b32 v140, v126 offset:44032
	ds_write_b32 v140, v127 offset:45056
	v_lshlrev_b32_e32 v64, 13, v135
	v_lshl_add_u32 v65, v134, 3, v138
	v_lshl_or_b32 v66, v134, 11, v64
	v_lshlrev_b32_e32 v68, 5, v138
	v_or3_b32 v161, v64, v137, v68
	v_lshl_or_b32 v162, v65, 2, v66
	v_add_u32_e32 v68, 0x60, v65
	v_add_u32_e32 v65, 0x70, v65
	v_and_b32_e32 v68, 0x7f, v68
	v_and_b32_e32 v65, 0x7f, v65
	v_lshl_or_b32 v163, v68, 2, v66
	v_lshl_or_b32 v164, v65, 2, v66
	v_add_u32_e32 v66, 8, v133
	v_and_b32_e32 v66, 0x78, v66
	v_lshlrev_b32_e32 v65, 9, v136
	v_lshlrev_b32_e32 v66, 2, v66
	v_or3_b32 v166, v64, v65, v66
	v_add_u32_e32 v66, 16, v133
	v_and_b32_e32 v66, 0x78, v66
	v_lshlrev_b32_e32 v65, 9, v132
	v_lshlrev_b32_e32 v66, 2, v66
	v_or3_b32 v168, v64, v65, v66
	v_add_u32_e32 v66, 24, v133
	v_and_b32_e32 v66, 0x78, v66
	v_lshlrev_b32_e32 v67, 5, v135
	v_lshlrev_b32_e32 v65, 9, v130
	v_lshlrev_b32_e32 v66, 2, v66
	v_or3_b32 v170, v64, v65, v66
	v_or_b32_e32 v64, 16, v67
	v_add_u32_e32 v68, 0x100, v131
	v_add_u32_e32 v69, 0x200, v131
	v_add_u32_e32 v70, 0x300, v131
	v_add_u32_e32 v71, 0x500, v131
	v_add_u32_e32 v72, 0x600, v131
	v_add_u32_e32 v73, 0x700, v131
	v_or_b32_e32 v172, v64, v134
	v_or_b32_e32 v173, v136, v64
	v_or_b32_e32 v174, v132, v64
	v_or_b32_e32 v175, v130, v64
	v_and_b32_e32 v64, 24, v153
	s_movk_i32 s90, 0x3c0
	v_lshrrev_b32_e32 v176, 4, v68
	v_lshrrev_b32_e32 v177, 4, v69
	v_lshrrev_b32_e32 v178, 4, v70
	v_lshrrev_b32_e32 v180, 4, v71
	v_lshrrev_b32_e32 v181, 4, v72
	v_lshrrev_b32_e32 v182, 4, v73
	v_or_b32_e32 v165, v134, v67
	v_or_b32_e32 v167, v136, v67
	v_or_b32_e32 v169, v132, v67
	v_or_b32_e32 v171, v130, v67
	v_and_or_b32 v64, v131, s90, v64
	v_mul_u32_u24_e32 v65, 0x110, v138
	v_lshlrev_b32_e32 v66, 4, v138
	v_mul_u32_u24_e32 v67, 0x110, v128
	v_mul_u32_u24_e32 v68, 0x110, v176
	v_mul_u32_u24_e32 v69, 0x110, v177
	v_mul_u32_u24_e32 v70, 0x110, v178
	v_mul_u32_u24_e32 v71, 0x110, v180
	v_mul_u32_u24_e32 v72, 0x110, v181
	v_mul_u32_u24_e32 v73, 0x110, v182
	v_or_b32_e32 v179, 64, v128
	v_lshlrev_b32_e32 v190, 2, v138
	v_add_u32_e32 v191, v64, v65
	v_add_u32_e32 v192, v66, v67
	v_add_u32_e32 v193, v66, v68
	v_add_u32_e32 v194, v66, v69
	v_add_u32_e32 v195, v66, v70
	v_add_u32_e32 v196, v66, v71
	v_add_u32_e32 v197, v66, v72
	v_add_u32_e32 v198, v66, v73
	v_mbcnt_hi_u32_b32 v199, -1, v155
	s_waitcnt lgkmcnt(0)
	s_mov_b64 s[6:7], -1
	s_cmp_lt_i32 s77, 5
	s_branch .Lmy_ip0_epi
.Lmy_ip0_pass2:
	s_barrier
	v_mov_b32_e32 v0, v144
	v_mov_b32_e32 v1, v145
	v_mov_b32_e32 v2, v146
	v_mov_b32_e32 v3, v147
	v_mov_b32_e32 v4, v184
	v_mov_b32_e32 v5, v185
	v_mov_b32_e32 v6, v186
	v_mov_b32_e32 v7, v187
	v_mov_b32_e32 v8, v204
	v_mov_b32_e32 v9, v205
	v_mov_b32_e32 v10, v206
	v_mov_b32_e32 v11, v207
	v_mov_b32_e32 v12, v208
	v_mov_b32_e32 v13, v209
	v_mov_b32_e32 v14, v210
	v_mov_b32_e32 v15, v211
	v_mov_b32_e32 v16, v232
	v_mov_b32_e32 v17, v233
	v_mov_b32_e32 v18, v234
	v_mov_b32_e32 v19, v235
	v_mov_b32_e32 v20, v236
	v_mov_b32_e32 v21, v237
	v_mov_b32_e32 v22, v238
	v_mov_b32_e32 v23, v239
	v_mov_b32_e32 v24, v240
	v_mov_b32_e32 v25, v241
	v_mov_b32_e32 v26, v242
	v_mov_b32_e32 v27, v243
	v_mov_b32_e32 v28, v248
	v_mov_b32_e32 v29, v249
	v_mov_b32_e32 v30, v250
	v_mov_b32_e32 v31, v251
	v_mov_b32_e32 v32, v252
	v_mov_b32_e32 v33, v253
	v_mov_b32_e32 v34, v254
	v_mov_b32_e32 v35, v255
	v_mov_b32_e32 v36, v150
	v_mov_b32_e32 v37, v151
	v_mov_b32_e32 v38, v156
	v_mov_b32_e32 v39, v158
	v_mov_b32_e32 v40, v159
	v_mov_b32_e32 v41, v160
	v_mov_b32_e32 v42, v183
	v_mov_b32_e32 v43, v188
	v_mov_b32_e32 v44, v189
	v_mov_b32_e32 v45, v212
	v_mov_b32_e32 v46, v213
	v_mov_b32_e32 v47, v214
	v_mov_b32_e32 v48, v216
	v_mov_b32_e32 v49, v218
	v_mov_b32_e32 v50, v220
	v_mov_b32_e32 v51, v222
	v_mov_b32_e32 v52, v224
	v_mov_b32_e32 v53, v226
	v_mov_b32_e32 v54, v228
	v_mov_b32_e32 v55, v230
	v_mov_b32_e32 v56, v231
	v_mov_b32_e32 v57, v244
	v_mov_b32_e32 v58, v245
	ds_read_b32 v59, v140 offset:40960
	ds_read_b32 v60, v140 offset:41984
	ds_read_b32 v61, v140 offset:43008
	ds_read_b32 v62, v140 offset:44032
	ds_read_b32 v63, v140 offset:45056
	s_waitcnt lgkmcnt(0)
	s_lshl_b64 s[64:65], s[66:67], 17
	s_mov_b64 s[6:7], -1
	s_cmp_lt_i32 s77, 5
.Lmy_ip0_epi:
	s_cbranch_scc1 .LBB0_175
	v_mul_f32_e32 v64, 0xbfb8aa3b, v2
	v_mul_f32_e32 v65, 0xbfb8aa3b, v3
	v_exp_f32_e32 v64, v64
	v_exp_f32_e32 v65, v65
	v_mul_f32_e32 v66, 0xbfb8aa3b, v0
	v_mul_f32_e32 v67, 0xbfb8aa3b, v1
	v_exp_f32_e32 v66, v66
	v_pk_add_f32 v[64:65], v[64:65], 1.0 op_sel_hi:[1,0]
	v_exp_f32_e32 v67, v67
	v_div_scale_f32 v70, s[4:5], v65, v65, v3
	v_rcp_f32_e32 v71, v70
	v_pk_add_f32 v[68:69], v[66:67], 1.0 op_sel_hi:[1,0]
	v_mul_f32_e32 v73, 0xbfb8aa3b, v5
	v_exp_f32_e32 v73, v73
	v_fma_f32 v66, -v70, v71, 1.0
	v_fmac_f32_e32 v71, v66, v71
	v_div_scale_f32 v66, vcc, v3, v65, v3
	v_mul_f32_e32 v67, v66, v71
	v_fma_f32 v72, -v70, v67, v66
	v_fmac_f32_e32 v67, v72, v71
	v_fma_f32 v66, -v70, v67, v66
	v_div_scale_f32 v70, s[4:5], v64, v64, v2
	v_rcp_f32_e32 v72, v70
	v_div_fmas_f32 v66, v66, v71, v67
	v_div_fixup_f32 v67, v66, v65, v3
	v_mul_f32_e32 v81, 0xbfb8aa3b, v13
	v_fma_f32 v65, -v70, v72, 1.0
	v_fmac_f32_e32 v72, v65, v72
	v_div_scale_f32 v65, vcc, v2, v64, v2
	v_mul_f32_e32 v66, v65, v72
	v_fma_f32 v71, -v70, v66, v65
	v_fmac_f32_e32 v66, v71, v72
	v_fma_f32 v65, -v70, v66, v65
	v_div_scale_f32 v70, s[4:5], v69, v69, v1
	v_rcp_f32_e32 v71, v70
	v_div_fmas_f32 v65, v65, v72, v66
	v_div_fixup_f32 v66, v65, v64, v2
	v_exp_f32_e32 v81, v81
	v_fma_f32 v64, -v70, v71, 1.0
	v_fmac_f32_e32 v71, v64, v71
	v_div_scale_f32 v64, vcc, v1, v69, v1
	v_mul_f32_e32 v65, v64, v71
	v_fma_f32 v72, -v70, v65, v64
	v_fmac_f32_e32 v65, v72, v71
	v_fma_f32 v64, -v70, v65, v64
	v_div_scale_f32 v70, s[4:5], v68, v68, v0
	v_rcp_f32_e32 v74, v70
	v_div_fmas_f32 v64, v64, v71, v65
	v_div_fixup_f32 v65, v64, v69, v1
	v_mul_f32_e32 v72, 0xbfb8aa3b, v4
	v_fma_f32 v64, -v70, v74, 1.0
	v_fmac_f32_e32 v74, v64, v74
	v_div_scale_f32 v64, vcc, v0, v68, v0
	v_mul_f32_e32 v69, v64, v74
	v_fma_f32 v71, -v70, v69, v64
	v_fmac_f32_e32 v69, v71, v74
	v_fma_f32 v64, -v70, v69, v64
	v_mul_f32_e32 v70, 0xbfb8aa3b, v6
	v_mul_f32_e32 v71, 0xbfb8aa3b, v7
	v_exp_f32_e32 v70, v70
	v_exp_f32_e32 v71, v71
	v_exp_f32_e32 v72, v72
	v_div_fmas_f32 v64, v64, v74, v69
	v_div_fixup_f32 v64, v64, v68, v0
	v_pk_add_f32 v[70:71], v[70:71], 1.0 op_sel_hi:[1,0]
	v_pk_add_f32 v[68:69], v[72:73], 1.0 op_sel_hi:[1,0]
	v_div_scale_f32 v75, s[4:5], v71, v71, v7
	v_rcp_f32_e32 v76, v75
	v_mul_f32_e32 v89, 0xbfb8aa3b, v21
	v_exp_f32_e32 v89, v89
	v_mul_f32_e32 v97, 0xbfb8aa3b, v29
	v_fma_f32 v72, -v75, v76, 1.0
	v_fmac_f32_e32 v76, v72, v76
	v_div_scale_f32 v72, vcc, v7, v71, v7
	v_mul_f32_e32 v73, v72, v76
	v_fma_f32 v74, -v75, v73, v72
	v_fmac_f32_e32 v73, v74, v76
	v_div_scale_f32 v74, s[4:5], v70, v70, v6
	v_fma_f32 v72, -v75, v73, v72
	v_rcp_f32_e32 v75, v74
	v_div_fmas_f32 v72, v72, v76, v73
	v_div_fixup_f32 v71, v72, v71, v7
	v_exp_f32_e32 v97, v97
	v_fma_f32 v72, -v74, v75, 1.0
	v_fmac_f32_e32 v75, v72, v75
	v_div_scale_f32 v72, vcc, v6, v70, v6
	v_mul_f32_e32 v73, v72, v75
	v_fma_f32 v76, -v74, v73, v72
	v_fmac_f32_e32 v73, v76, v75
	v_fma_f32 v72, -v74, v73, v72
	v_div_scale_f32 v74, s[4:5], v69, v69, v5
	v_rcp_f32_e32 v76, v74
	v_div_fmas_f32 v72, v72, v75, v73
	v_div_fixup_f32 v70, v72, v70, v6
	v_mul_f32_e32 v105, 0xbfb8aa3b, v37
	v_fma_f32 v72, -v74, v76, 1.0
	v_fmac_f32_e32 v76, v72, v76
	v_div_scale_f32 v72, vcc, v5, v69, v5
	v_mul_f32_e32 v73, v72, v76
	v_fma_f32 v75, -v74, v73, v72
	v_fmac_f32_e32 v73, v75, v76
	v_fma_f32 v72, -v74, v73, v72
	v_div_scale_f32 v74, s[4:5], v68, v68, v4
	v_rcp_f32_e32 v77, v74
	v_div_fmas_f32 v72, v72, v76, v73
	v_div_fixup_f32 v69, v72, v69, v5
	v_mul_f32_e32 v75, 0xbfb8aa3b, v9
	v_fma_f32 v72, -v74, v77, 1.0
	v_fmac_f32_e32 v77, v72, v77
	v_div_scale_f32 v72, vcc, v4, v68, v4
	v_mul_f32_e32 v76, v72, v77
	v_fma_f32 v73, -v74, v76, v72
	v_fmac_f32_e32 v76, v73, v77
	v_fma_f32 v78, -v74, v76, v72
	v_mul_f32_e32 v72, 0xbfb8aa3b, v10
	v_mul_f32_e32 v73, 0xbfb8aa3b, v11
	v_exp_f32_e32 v72, v72
	v_exp_f32_e32 v73, v73
	v_mul_f32_e32 v74, 0xbfb8aa3b, v8
	v_exp_f32_e32 v74, v74
	v_exp_f32_e32 v75, v75
	v_pk_add_f32 v[72:73], v[72:73], 1.0 op_sel_hi:[1,0]
	v_div_fmas_f32 v76, v78, v77, v76
	v_div_scale_f32 v79, s[4:5], v73, v73, v11
	v_rcp_f32_e32 v80, v79
	v_div_fixup_f32 v68, v76, v68, v4
	v_pk_add_f32 v[76:77], v[74:75], 1.0 op_sel_hi:[1,0]
	v_exp_f32_e32 v105, v105
	v_fma_f32 v74, -v79, v80, 1.0
	v_fmac_f32_e32 v80, v74, v80
	v_div_scale_f32 v74, vcc, v11, v73, v11
	v_mul_f32_e32 v75, v74, v80
	v_fma_f32 v78, -v79, v75, v74
	v_fmac_f32_e32 v75, v78, v80
	v_div_scale_f32 v78, s[4:5], v72, v72, v10
	v_fma_f32 v74, -v79, v75, v74
	v_rcp_f32_e32 v79, v78
	v_div_fmas_f32 v74, v74, v80, v75
	v_div_fixup_f32 v75, v74, v73, v11
	v_mul_f32_e32 v113, 0xbfb8aa3b, v45
	v_fma_f32 v73, -v78, v79, 1.0
	v_fmac_f32_e32 v79, v73, v79
	v_div_scale_f32 v73, vcc, v10, v72, v10
	v_mul_f32_e32 v74, v73, v79
	v_fma_f32 v80, -v78, v74, v73
	v_fmac_f32_e32 v74, v80, v79
	v_fma_f32 v73, -v78, v74, v73
	v_div_scale_f32 v78, s[4:5], v77, v77, v9
	v_rcp_f32_e32 v80, v78
	v_div_fmas_f32 v73, v73, v79, v74
	v_div_fixup_f32 v74, v73, v72, v10
	v_exp_f32_e32 v113, v113
	v_fma_f32 v72, -v78, v80, 1.0
	v_fmac_f32_e32 v80, v72, v80
	v_div_scale_f32 v72, vcc, v9, v77, v9
	v_mul_f32_e32 v73, v72, v80
	v_fma_f32 v79, -v78, v73, v72
	v_fmac_f32_e32 v73, v79, v80
	v_fma_f32 v72, -v78, v73, v72
	v_div_scale_f32 v78, s[4:5], v76, v76, v8
	v_rcp_f32_e32 v82, v78
	v_div_fmas_f32 v72, v72, v80, v73
	v_div_fixup_f32 v73, v72, v77, v9
	v_mul_f32_e32 v80, 0xbfb8aa3b, v12
	v_fma_f32 v72, -v78, v82, 1.0
	v_fmac_f32_e32 v82, v72, v82
	v_div_scale_f32 v72, vcc, v8, v76, v8
	v_mul_f32_e32 v77, v72, v82
	v_fma_f32 v79, -v78, v77, v72
	v_fmac_f32_e32 v77, v79, v82
	v_fma_f32 v72, -v78, v77, v72
	v_mul_f32_e32 v78, 0xbfb8aa3b, v14
	v_mul_f32_e32 v79, 0xbfb8aa3b, v15
	v_exp_f32_e32 v78, v78
	v_exp_f32_e32 v79, v79
	v_exp_f32_e32 v80, v80
	v_div_fmas_f32 v72, v72, v82, v77
	v_div_fixup_f32 v72, v72, v76, v8
	v_pk_add_f32 v[78:79], v[78:79], 1.0 op_sel_hi:[1,0]
	v_pk_add_f32 v[76:77], v[80:81], 1.0 op_sel_hi:[1,0]
	v_div_scale_f32 v83, s[4:5], v79, v79, v15
	v_rcp_f32_e32 v84, v83
	v_mul_f32_e32 v121, 0xbfb8aa3b, v53
	v_exp_f32_e32 v121, v121
	s_mov_b64 s[6:7], 0
	v_fma_f32 v80, -v83, v84, 1.0
	v_fmac_f32_e32 v84, v80, v84
	v_div_scale_f32 v80, vcc, v15, v79, v15
	v_mul_f32_e32 v81, v80, v84
	v_fma_f32 v82, -v83, v81, v80
	v_fmac_f32_e32 v81, v82, v84
	v_div_scale_f32 v82, s[4:5], v78, v78, v14
	v_fma_f32 v80, -v83, v81, v80
	v_rcp_f32_e32 v83, v82
	v_div_fmas_f32 v80, v80, v84, v81
	v_div_fixup_f32 v79, v80, v79, v15
	v_fma_f32 v80, -v82, v83, 1.0
	v_fmac_f32_e32 v83, v80, v83
	v_div_scale_f32 v80, vcc, v14, v78, v14
	v_mul_f32_e32 v81, v80, v83
	v_fma_f32 v84, -v82, v81, v80
	v_fmac_f32_e32 v81, v84, v83
	v_fma_f32 v80, -v82, v81, v80
	v_div_scale_f32 v82, s[4:5], v77, v77, v13
	v_rcp_f32_e32 v84, v82
	v_div_fmas_f32 v80, v80, v83, v81
	v_div_fixup_f32 v78, v80, v78, v14
	v_fma_f32 v80, -v82, v84, 1.0
	v_fmac_f32_e32 v84, v80, v84
	v_div_scale_f32 v80, vcc, v13, v77, v13
	v_mul_f32_e32 v81, v80, v84
	v_fma_f32 v83, -v82, v81, v80
	v_fmac_f32_e32 v81, v83, v84
	v_fma_f32 v80, -v82, v81, v80
	v_div_scale_f32 v82, s[4:5], v76, v76, v12
	v_rcp_f32_e32 v85, v82
	v_div_fmas_f32 v80, v80, v84, v81
	v_div_fixup_f32 v77, v80, v77, v13
	v_mul_f32_e32 v83, 0xbfb8aa3b, v17
	v_fma_f32 v80, -v82, v85, 1.0
	v_fmac_f32_e32 v85, v80, v85
	v_div_scale_f32 v80, vcc, v12, v76, v12
	v_mul_f32_e32 v84, v80, v85
	v_fma_f32 v81, -v82, v84, v80
	v_fmac_f32_e32 v84, v81, v85
	v_fma_f32 v86, -v82, v84, v80
	v_mul_f32_e32 v80, 0xbfb8aa3b, v18
	v_mul_f32_e32 v81, 0xbfb8aa3b, v19
	v_exp_f32_e32 v80, v80
	v_exp_f32_e32 v81, v81
	v_mul_f32_e32 v82, 0xbfb8aa3b, v16
	v_exp_f32_e32 v82, v82
	v_exp_f32_e32 v83, v83
	v_pk_add_f32 v[80:81], v[80:81], 1.0 op_sel_hi:[1,0]
	v_div_fmas_f32 v84, v86, v85, v84
	v_div_scale_f32 v87, s[4:5], v81, v81, v19
	v_rcp_f32_e32 v88, v87
	v_div_fixup_f32 v76, v84, v76, v12
	v_pk_add_f32 v[84:85], v[82:83], 1.0 op_sel_hi:[1,0]
	v_fma_f32 v82, -v87, v88, 1.0
	v_fmac_f32_e32 v88, v82, v88
	v_div_scale_f32 v82, vcc, v19, v81, v19
	v_mul_f32_e32 v83, v82, v88
	v_fma_f32 v86, -v87, v83, v82
	v_fmac_f32_e32 v83, v86, v88
	v_div_scale_f32 v86, s[4:5], v80, v80, v18
	v_fma_f32 v82, -v87, v83, v82
	v_rcp_f32_e32 v87, v86
	v_div_fmas_f32 v82, v82, v88, v83
	v_div_fixup_f32 v83, v82, v81, v19
	v_fma_f32 v81, -v86, v87, 1.0
	v_fmac_f32_e32 v87, v81, v87
	v_div_scale_f32 v81, vcc, v18, v80, v18
	v_mul_f32_e32 v82, v81, v87
	v_fma_f32 v88, -v86, v82, v81
	v_fmac_f32_e32 v82, v88, v87
	v_fma_f32 v81, -v86, v82, v81
	v_div_scale_f32 v86, s[4:5], v85, v85, v17
	v_rcp_f32_e32 v88, v86
	v_div_fmas_f32 v81, v81, v87, v82
	v_div_fixup_f32 v82, v81, v80, v18
	v_fma_f32 v80, -v86, v88, 1.0
	v_fmac_f32_e32 v88, v80, v88
	v_div_scale_f32 v80, vcc, v17, v85, v17
	v_mul_f32_e32 v81, v80, v88
	v_fma_f32 v87, -v86, v81, v80
	v_fmac_f32_e32 v81, v87, v88
	v_fma_f32 v80, -v86, v81, v80
	v_div_scale_f32 v86, s[4:5], v84, v84, v16
	v_rcp_f32_e32 v90, v86
	v_div_fmas_f32 v80, v80, v88, v81
	v_div_fixup_f32 v81, v80, v85, v17
	v_mul_f32_e32 v88, 0xbfb8aa3b, v20
	v_fma_f32 v80, -v86, v90, 1.0
	v_fmac_f32_e32 v90, v80, v90
	v_div_scale_f32 v80, vcc, v16, v84, v16
	v_mul_f32_e32 v85, v80, v90
	v_fma_f32 v87, -v86, v85, v80
	v_fmac_f32_e32 v85, v87, v90
	v_fma_f32 v80, -v86, v85, v80
	v_mul_f32_e32 v86, 0xbfb8aa3b, v22
	v_mul_f32_e32 v87, 0xbfb8aa3b, v23
	v_exp_f32_e32 v86, v86
	v_exp_f32_e32 v87, v87
	v_exp_f32_e32 v88, v88
	v_div_fmas_f32 v80, v80, v90, v85
	v_div_fixup_f32 v80, v80, v84, v16
	v_pk_add_f32 v[86:87], v[86:87], 1.0 op_sel_hi:[1,0]
	v_pk_add_f32 v[84:85], v[88:89], 1.0 op_sel_hi:[1,0]
	v_div_scale_f32 v91, s[4:5], v87, v87, v23
	v_rcp_f32_e32 v92, v91
	s_nop 0
	v_fma_f32 v88, -v91, v92, 1.0
	v_fmac_f32_e32 v92, v88, v92
	v_div_scale_f32 v88, vcc, v23, v87, v23
	v_mul_f32_e32 v89, v88, v92
	v_fma_f32 v90, -v91, v89, v88
	v_fmac_f32_e32 v89, v90, v92
	v_div_scale_f32 v90, s[4:5], v86, v86, v22
	v_fma_f32 v88, -v91, v89, v88
	v_rcp_f32_e32 v91, v90
	v_div_fmas_f32 v88, v88, v92, v89
	v_div_fixup_f32 v87, v88, v87, v23
	v_fma_f32 v88, -v90, v91, 1.0
	v_fmac_f32_e32 v91, v88, v91
	v_div_scale_f32 v88, vcc, v22, v86, v22
	v_mul_f32_e32 v89, v88, v91
	v_fma_f32 v92, -v90, v89, v88
	v_fmac_f32_e32 v89, v92, v91
	v_fma_f32 v88, -v90, v89, v88
	v_div_scale_f32 v90, s[4:5], v85, v85, v21
	v_rcp_f32_e32 v92, v90
	v_div_fmas_f32 v88, v88, v91, v89
	v_div_fixup_f32 v86, v88, v86, v22
	v_fma_f32 v88, -v90, v92, 1.0
	v_fmac_f32_e32 v92, v88, v92
	v_div_scale_f32 v88, vcc, v21, v85, v21
	v_mul_f32_e32 v89, v88, v92
	v_fma_f32 v91, -v90, v89, v88
	v_fmac_f32_e32 v89, v91, v92
	v_fma_f32 v88, -v90, v89, v88
	v_div_scale_f32 v90, s[4:5], v84, v84, v20
	v_rcp_f32_e32 v93, v90
	v_div_fmas_f32 v88, v88, v92, v89
	v_div_fixup_f32 v85, v88, v85, v21
	v_mul_f32_e32 v91, 0xbfb8aa3b, v25
	v_fma_f32 v88, -v90, v93, 1.0
	v_fmac_f32_e32 v93, v88, v93
	v_div_scale_f32 v88, vcc, v20, v84, v20
	v_mul_f32_e32 v92, v88, v93
	v_fma_f32 v89, -v90, v92, v88
	v_fmac_f32_e32 v92, v89, v93
	v_fma_f32 v94, -v90, v92, v88
	v_mul_f32_e32 v88, 0xbfb8aa3b, v26
	v_mul_f32_e32 v89, 0xbfb8aa3b, v27
	v_exp_f32_e32 v88, v88
	v_exp_f32_e32 v89, v89
	v_mul_f32_e32 v90, 0xbfb8aa3b, v24
	v_exp_f32_e32 v90, v90
	v_exp_f32_e32 v91, v91
	v_pk_add_f32 v[88:89], v[88:89], 1.0 op_sel_hi:[1,0]
	v_div_fmas_f32 v92, v94, v93, v92
	v_div_scale_f32 v95, s[4:5], v89, v89, v27
	v_rcp_f32_e32 v96, v95
	v_div_fixup_f32 v84, v92, v84, v20
	v_pk_add_f32 v[92:93], v[90:91], 1.0 op_sel_hi:[1,0]
	v_fma_f32 v90, -v95, v96, 1.0
	v_fmac_f32_e32 v96, v90, v96
	v_div_scale_f32 v90, vcc, v27, v89, v27
	v_mul_f32_e32 v91, v90, v96
	v_fma_f32 v94, -v95, v91, v90
	v_fmac_f32_e32 v91, v94, v96
	v_div_scale_f32 v94, s[4:5], v88, v88, v26
	v_fma_f32 v90, -v95, v91, v90
	v_rcp_f32_e32 v95, v94
	v_div_fmas_f32 v90, v90, v96, v91
	v_div_fixup_f32 v91, v90, v89, v27
	v_fma_f32 v89, -v94, v95, 1.0
	v_fmac_f32_e32 v95, v89, v95
	v_div_scale_f32 v89, vcc, v26, v88, v26
	v_mul_f32_e32 v90, v89, v95
	v_fma_f32 v96, -v94, v90, v89
	v_fmac_f32_e32 v90, v96, v95
	v_fma_f32 v89, -v94, v90, v89
	v_div_scale_f32 v94, s[4:5], v93, v93, v25
	v_rcp_f32_e32 v96, v94
	v_div_fmas_f32 v89, v89, v95, v90
	v_div_fixup_f32 v90, v89, v88, v26
	v_fma_f32 v88, -v94, v96, 1.0
	v_fmac_f32_e32 v96, v88, v96
	v_div_scale_f32 v88, vcc, v25, v93, v25
	v_mul_f32_e32 v89, v88, v96
	v_fma_f32 v95, -v94, v89, v88
	v_fmac_f32_e32 v89, v95, v96
	v_fma_f32 v88, -v94, v89, v88
	v_div_scale_f32 v94, s[4:5], v92, v92, v24
	v_rcp_f32_e32 v98, v94
	v_div_fmas_f32 v88, v88, v96, v89
	v_div_fixup_f32 v89, v88, v93, v25
	v_mul_f32_e32 v96, 0xbfb8aa3b, v28
	v_fma_f32 v88, -v94, v98, 1.0
	v_fmac_f32_e32 v98, v88, v98
	v_div_scale_f32 v88, vcc, v24, v92, v24
	v_mul_f32_e32 v93, v88, v98
	v_fma_f32 v95, -v94, v93, v88
	v_fmac_f32_e32 v93, v95, v98
	v_fma_f32 v88, -v94, v93, v88
	v_mul_f32_e32 v94, 0xbfb8aa3b, v30
	v_mul_f32_e32 v95, 0xbfb8aa3b, v31
	v_exp_f32_e32 v94, v94
	v_exp_f32_e32 v95, v95
	v_exp_f32_e32 v96, v96
	v_div_fmas_f32 v88, v88, v98, v93
	v_div_fixup_f32 v88, v88, v92, v24
	v_pk_add_f32 v[94:95], v[94:95], 1.0 op_sel_hi:[1,0]
	v_pk_add_f32 v[92:93], v[96:97], 1.0 op_sel_hi:[1,0]
	v_div_scale_f32 v99, s[4:5], v95, v95, v31
	v_rcp_f32_e32 v100, v99
	s_nop 0
	v_fma_f32 v96, -v99, v100, 1.0
	v_fmac_f32_e32 v100, v96, v100
	v_div_scale_f32 v96, vcc, v31, v95, v31
	v_mul_f32_e32 v97, v96, v100
	v_fma_f32 v98, -v99, v97, v96
	v_fmac_f32_e32 v97, v98, v100
	v_div_scale_f32 v98, s[4:5], v94, v94, v30
	v_fma_f32 v96, -v99, v97, v96
	v_rcp_f32_e32 v99, v98
	v_div_fmas_f32 v96, v96, v100, v97
	v_div_fixup_f32 v95, v96, v95, v31
	v_fma_f32 v96, -v98, v99, 1.0
	v_fmac_f32_e32 v99, v96, v99
	v_div_scale_f32 v96, vcc, v30, v94, v30
	v_mul_f32_e32 v97, v96, v99
	v_fma_f32 v100, -v98, v97, v96
	v_fmac_f32_e32 v97, v100, v99
	v_fma_f32 v96, -v98, v97, v96
	v_div_scale_f32 v98, s[4:5], v93, v93, v29
	v_rcp_f32_e32 v100, v98
	v_div_fmas_f32 v96, v96, v99, v97
	v_div_fixup_f32 v94, v96, v94, v30
	v_fma_f32 v96, -v98, v100, 1.0
	v_fmac_f32_e32 v100, v96, v100
	v_div_scale_f32 v96, vcc, v29, v93, v29
	v_mul_f32_e32 v97, v96, v100
	v_fma_f32 v99, -v98, v97, v96
	v_fmac_f32_e32 v97, v99, v100
	v_fma_f32 v96, -v98, v97, v96
	v_div_scale_f32 v98, s[4:5], v92, v92, v28
	v_rcp_f32_e32 v101, v98
	v_div_fmas_f32 v96, v96, v100, v97
	v_div_fixup_f32 v93, v96, v93, v29
	v_mul_f32_e32 v99, 0xbfb8aa3b, v33
	v_fma_f32 v96, -v98, v101, 1.0
	v_fmac_f32_e32 v101, v96, v101
	v_div_scale_f32 v96, vcc, v28, v92, v28
	v_mul_f32_e32 v100, v96, v101
	v_fma_f32 v97, -v98, v100, v96
	v_fmac_f32_e32 v100, v97, v101
	v_fma_f32 v102, -v98, v100, v96
	v_mul_f32_e32 v96, 0xbfb8aa3b, v34
	v_mul_f32_e32 v97, 0xbfb8aa3b, v35
	v_exp_f32_e32 v96, v96
	v_exp_f32_e32 v97, v97
	v_mul_f32_e32 v98, 0xbfb8aa3b, v32
	v_exp_f32_e32 v98, v98
	v_exp_f32_e32 v99, v99
	v_pk_add_f32 v[96:97], v[96:97], 1.0 op_sel_hi:[1,0]
	v_div_fmas_f32 v100, v102, v101, v100
	v_div_scale_f32 v103, s[4:5], v97, v97, v35
	v_rcp_f32_e32 v104, v103
	v_div_fixup_f32 v92, v100, v92, v28
	v_pk_add_f32 v[100:101], v[98:99], 1.0 op_sel_hi:[1,0]
	v_fma_f32 v98, -v103, v104, 1.0
	v_fmac_f32_e32 v104, v98, v104
	v_div_scale_f32 v98, vcc, v35, v97, v35
	v_mul_f32_e32 v99, v98, v104
	v_fma_f32 v102, -v103, v99, v98
	v_fmac_f32_e32 v99, v102, v104
	v_div_scale_f32 v102, s[4:5], v96, v96, v34
	v_fma_f32 v98, -v103, v99, v98
	v_rcp_f32_e32 v103, v102
	v_div_fmas_f32 v98, v98, v104, v99
	v_div_fixup_f32 v99, v98, v97, v35
	v_fma_f32 v97, -v102, v103, 1.0
	v_fmac_f32_e32 v103, v97, v103
	v_div_scale_f32 v97, vcc, v34, v96, v34
	v_mul_f32_e32 v98, v97, v103
	v_fma_f32 v104, -v102, v98, v97
	v_fmac_f32_e32 v98, v104, v103
	v_fma_f32 v97, -v102, v98, v97
	v_div_scale_f32 v102, s[4:5], v101, v101, v33
	v_rcp_f32_e32 v104, v102
	v_div_fmas_f32 v97, v97, v103, v98
	v_div_fixup_f32 v98, v97, v96, v34
	v_fma_f32 v96, -v102, v104, 1.0
	v_fmac_f32_e32 v104, v96, v104
	v_div_scale_f32 v96, vcc, v33, v101, v33
	v_mul_f32_e32 v97, v96, v104
	v_fma_f32 v103, -v102, v97, v96
	v_fmac_f32_e32 v97, v103, v104
	v_fma_f32 v96, -v102, v97, v96
	v_div_scale_f32 v102, s[4:5], v100, v100, v32
	v_rcp_f32_e32 v106, v102
	v_div_fmas_f32 v96, v96, v104, v97
	v_div_fixup_f32 v97, v96, v101, v33
	v_mul_f32_e32 v104, 0xbfb8aa3b, v36
	v_fma_f32 v96, -v102, v106, 1.0
	v_fmac_f32_e32 v106, v96, v106
	v_div_scale_f32 v96, vcc, v32, v100, v32
	v_mul_f32_e32 v101, v96, v106
	v_fma_f32 v103, -v102, v101, v96
	v_fmac_f32_e32 v101, v103, v106
	v_fma_f32 v96, -v102, v101, v96
	v_mul_f32_e32 v102, 0xbfb8aa3b, v38
	v_mul_f32_e32 v103, 0xbfb8aa3b, v39
	v_exp_f32_e32 v102, v102
	v_exp_f32_e32 v103, v103
	v_exp_f32_e32 v104, v104
	v_div_fmas_f32 v96, v96, v106, v101
	v_div_fixup_f32 v96, v96, v100, v32
	v_pk_add_f32 v[102:103], v[102:103], 1.0 op_sel_hi:[1,0]
	v_pk_add_f32 v[100:101], v[104:105], 1.0 op_sel_hi:[1,0]
	v_div_scale_f32 v107, s[4:5], v103, v103, v39
	v_rcp_f32_e32 v108, v107
	s_nop 0
	v_fma_f32 v104, -v107, v108, 1.0
	v_fmac_f32_e32 v108, v104, v108
	v_div_scale_f32 v104, vcc, v39, v103, v39
	v_mul_f32_e32 v105, v104, v108
	v_fma_f32 v106, -v107, v105, v104
	v_fmac_f32_e32 v105, v106, v108
	v_div_scale_f32 v106, s[4:5], v102, v102, v38
	v_fma_f32 v104, -v107, v105, v104
	v_rcp_f32_e32 v107, v106
	v_div_fmas_f32 v104, v104, v108, v105
	v_div_fixup_f32 v103, v104, v103, v39
	v_fma_f32 v104, -v106, v107, 1.0
	v_fmac_f32_e32 v107, v104, v107
	v_div_scale_f32 v104, vcc, v38, v102, v38
	v_mul_f32_e32 v105, v104, v107
	v_fma_f32 v108, -v106, v105, v104
	v_fmac_f32_e32 v105, v108, v107
	v_fma_f32 v104, -v106, v105, v104
	v_div_scale_f32 v106, s[4:5], v101, v101, v37
	v_rcp_f32_e32 v108, v106
	v_div_fmas_f32 v104, v104, v107, v105
	v_div_fixup_f32 v102, v104, v102, v38
	v_fma_f32 v104, -v106, v108, 1.0
	v_fmac_f32_e32 v108, v104, v108
	v_div_scale_f32 v104, vcc, v37, v101, v37
	v_mul_f32_e32 v105, v104, v108
	v_fma_f32 v107, -v106, v105, v104
	v_fmac_f32_e32 v105, v107, v108
	v_fma_f32 v104, -v106, v105, v104
	v_div_scale_f32 v106, s[4:5], v100, v100, v36
	v_rcp_f32_e32 v109, v106
	v_div_fmas_f32 v104, v104, v108, v105
	v_div_fixup_f32 v101, v104, v101, v37
	v_mul_f32_e32 v107, 0xbfb8aa3b, v41
	v_fma_f32 v104, -v106, v109, 1.0
	v_fmac_f32_e32 v109, v104, v109
	v_div_scale_f32 v104, vcc, v36, v100, v36
	v_mul_f32_e32 v108, v104, v109
	v_fma_f32 v105, -v106, v108, v104
	v_fmac_f32_e32 v108, v105, v109
	v_fma_f32 v110, -v106, v108, v104
	v_mul_f32_e32 v104, 0xbfb8aa3b, v42
	v_mul_f32_e32 v105, 0xbfb8aa3b, v43
	v_exp_f32_e32 v104, v104
	v_exp_f32_e32 v105, v105
	v_mul_f32_e32 v106, 0xbfb8aa3b, v40
	v_exp_f32_e32 v106, v106
	v_exp_f32_e32 v107, v107
	v_pk_add_f32 v[104:105], v[104:105], 1.0 op_sel_hi:[1,0]
	v_div_fmas_f32 v108, v110, v109, v108
	v_div_scale_f32 v111, s[4:5], v105, v105, v43
	v_rcp_f32_e32 v112, v111
	v_div_fixup_f32 v100, v108, v100, v36
	v_pk_add_f32 v[108:109], v[106:107], 1.0 op_sel_hi:[1,0]
	v_fma_f32 v106, -v111, v112, 1.0
	v_fmac_f32_e32 v112, v106, v112
	v_div_scale_f32 v106, vcc, v43, v105, v43
	v_mul_f32_e32 v107, v106, v112
	v_fma_f32 v110, -v111, v107, v106
	v_fmac_f32_e32 v107, v110, v112
	v_div_scale_f32 v110, s[4:5], v104, v104, v42
	v_fma_f32 v106, -v111, v107, v106
	v_rcp_f32_e32 v111, v110
	v_div_fmas_f32 v106, v106, v112, v107
	v_div_fixup_f32 v107, v106, v105, v43
	v_fma_f32 v105, -v110, v111, 1.0
	v_fmac_f32_e32 v111, v105, v111
	v_div_scale_f32 v105, vcc, v42, v104, v42
	v_mul_f32_e32 v106, v105, v111
	v_fma_f32 v112, -v110, v106, v105
	v_fmac_f32_e32 v106, v112, v111
	v_fma_f32 v105, -v110, v106, v105
	v_div_scale_f32 v110, s[4:5], v109, v109, v41
	v_rcp_f32_e32 v112, v110
	v_div_fmas_f32 v105, v105, v111, v106
	v_div_fixup_f32 v106, v105, v104, v42
	v_fma_f32 v104, -v110, v112, 1.0
	v_fmac_f32_e32 v112, v104, v112
	v_div_scale_f32 v104, vcc, v41, v109, v41
	v_mul_f32_e32 v105, v104, v112
	v_fma_f32 v111, -v110, v105, v104
	v_fmac_f32_e32 v105, v111, v112
	v_fma_f32 v104, -v110, v105, v104
	v_div_scale_f32 v110, s[4:5], v108, v108, v40
	v_rcp_f32_e32 v114, v110
	v_div_fmas_f32 v104, v104, v112, v105
	v_div_fixup_f32 v105, v104, v109, v41
	v_mul_f32_e32 v112, 0xbfb8aa3b, v44
	v_fma_f32 v104, -v110, v114, 1.0
	v_fmac_f32_e32 v114, v104, v114
	v_div_scale_f32 v104, vcc, v40, v108, v40
	v_mul_f32_e32 v109, v104, v114
	v_fma_f32 v111, -v110, v109, v104
	v_fmac_f32_e32 v109, v111, v114
	v_fma_f32 v104, -v110, v109, v104
	v_mul_f32_e32 v110, 0xbfb8aa3b, v46
	v_mul_f32_e32 v111, 0xbfb8aa3b, v47
	v_exp_f32_e32 v110, v110
	v_exp_f32_e32 v111, v111
	v_exp_f32_e32 v112, v112
	v_div_fmas_f32 v104, v104, v114, v109
	v_div_fixup_f32 v104, v104, v108, v40
	v_pk_add_f32 v[110:111], v[110:111], 1.0 op_sel_hi:[1,0]
	v_pk_add_f32 v[108:109], v[112:113], 1.0 op_sel_hi:[1,0]
	v_div_scale_f32 v115, s[4:5], v111, v111, v47
	v_rcp_f32_e32 v116, v115
	s_nop 0
	v_fma_f32 v112, -v115, v116, 1.0
	v_fmac_f32_e32 v116, v112, v116
	v_div_scale_f32 v112, vcc, v47, v111, v47
	v_mul_f32_e32 v113, v112, v116
	v_fma_f32 v114, -v115, v113, v112
	v_fmac_f32_e32 v113, v114, v116
	v_div_scale_f32 v114, s[4:5], v110, v110, v46
	v_fma_f32 v112, -v115, v113, v112
	v_rcp_f32_e32 v115, v114
	v_div_fmas_f32 v112, v112, v116, v113
	v_div_fixup_f32 v111, v112, v111, v47
	v_fma_f32 v112, -v114, v115, 1.0
	v_fmac_f32_e32 v115, v112, v115
	v_div_scale_f32 v112, vcc, v46, v110, v46
	v_mul_f32_e32 v113, v112, v115
	v_fma_f32 v116, -v114, v113, v112
	v_fmac_f32_e32 v113, v116, v115
	v_fma_f32 v112, -v114, v113, v112
	v_div_scale_f32 v114, s[4:5], v109, v109, v45
	v_rcp_f32_e32 v116, v114
	v_div_fmas_f32 v112, v112, v115, v113
	v_div_fixup_f32 v110, v112, v110, v46
	v_fma_f32 v112, -v114, v116, 1.0
	v_fmac_f32_e32 v116, v112, v116
	v_div_scale_f32 v112, vcc, v45, v109, v45
	v_mul_f32_e32 v113, v112, v116
	v_fma_f32 v115, -v114, v113, v112
	v_fmac_f32_e32 v113, v115, v116
	v_fma_f32 v112, -v114, v113, v112
	v_div_scale_f32 v114, s[4:5], v108, v108, v44
	v_rcp_f32_e32 v117, v114
	v_div_fmas_f32 v112, v112, v116, v113
	v_div_fixup_f32 v109, v112, v109, v45
	v_mul_f32_e32 v115, 0xbfb8aa3b, v49
	v_fma_f32 v112, -v114, v117, 1.0
	v_fmac_f32_e32 v117, v112, v117
	v_div_scale_f32 v112, vcc, v44, v108, v44
	v_mul_f32_e32 v116, v112, v117
	v_fma_f32 v113, -v114, v116, v112
	v_fmac_f32_e32 v116, v113, v117
	v_fma_f32 v118, -v114, v116, v112
	v_mul_f32_e32 v112, 0xbfb8aa3b, v50
	v_mul_f32_e32 v113, 0xbfb8aa3b, v51
	v_exp_f32_e32 v112, v112
	v_exp_f32_e32 v113, v113
	v_mul_f32_e32 v114, 0xbfb8aa3b, v48
	v_exp_f32_e32 v114, v114
	v_exp_f32_e32 v115, v115
	v_pk_add_f32 v[112:113], v[112:113], 1.0 op_sel_hi:[1,0]
	v_div_fmas_f32 v116, v118, v117, v116
	v_div_scale_f32 v119, s[4:5], v113, v113, v51
	v_rcp_f32_e32 v120, v119
	v_div_fixup_f32 v108, v116, v108, v44
	v_pk_add_f32 v[116:117], v[114:115], 1.0 op_sel_hi:[1,0]
	v_fma_f32 v114, -v119, v120, 1.0
	v_fmac_f32_e32 v120, v114, v120
	v_div_scale_f32 v114, vcc, v51, v113, v51
	v_mul_f32_e32 v115, v114, v120
	v_fma_f32 v118, -v119, v115, v114
	v_fmac_f32_e32 v115, v118, v120
	v_div_scale_f32 v118, s[4:5], v112, v112, v50
	v_fma_f32 v114, -v119, v115, v114
	v_rcp_f32_e32 v119, v118
	v_div_fmas_f32 v114, v114, v120, v115
	v_div_fixup_f32 v115, v114, v113, v51
	v_fma_f32 v113, -v118, v119, 1.0
	v_fmac_f32_e32 v119, v113, v119
	v_div_scale_f32 v113, vcc, v50, v112, v50
	v_mul_f32_e32 v114, v113, v119
	v_fma_f32 v120, -v118, v114, v113
	v_fmac_f32_e32 v114, v120, v119
	v_fma_f32 v113, -v118, v114, v113
	v_div_scale_f32 v118, s[4:5], v117, v117, v49
	v_rcp_f32_e32 v120, v118
	v_div_fmas_f32 v113, v113, v119, v114
	v_div_fixup_f32 v114, v113, v112, v50
	v_fma_f32 v112, -v118, v120, 1.0
	v_fmac_f32_e32 v120, v112, v120
	v_div_scale_f32 v112, vcc, v49, v117, v49
	v_mul_f32_e32 v113, v112, v120
	v_fma_f32 v119, -v118, v113, v112
	v_fmac_f32_e32 v113, v119, v120
	v_fma_f32 v112, -v118, v113, v112
	v_div_scale_f32 v118, s[4:5], v116, v116, v48
	v_rcp_f32_e32 v122, v118
	v_div_fmas_f32 v112, v112, v120, v113
	v_div_fixup_f32 v113, v112, v117, v49
	v_mul_f32_e32 v120, 0xbfb8aa3b, v52
	v_fma_f32 v112, -v118, v122, 1.0
	v_fmac_f32_e32 v122, v112, v122
	v_div_scale_f32 v112, vcc, v48, v116, v48
	v_mul_f32_e32 v117, v112, v122
	v_fma_f32 v119, -v118, v117, v112
	v_fmac_f32_e32 v117, v119, v122
	v_fma_f32 v112, -v118, v117, v112
	v_mul_f32_e32 v118, 0xbfb8aa3b, v54
	v_mul_f32_e32 v119, 0xbfb8aa3b, v55
	v_exp_f32_e32 v118, v118
	v_exp_f32_e32 v119, v119
	v_exp_f32_e32 v120, v120
	v_div_fmas_f32 v112, v112, v122, v117
	v_div_fixup_f32 v112, v112, v116, v48
	v_pk_add_f32 v[118:119], v[118:119], 1.0 op_sel_hi:[1,0]
	v_pk_add_f32 v[116:117], v[120:121], 1.0 op_sel_hi:[1,0]
	v_div_scale_f32 v123, s[4:5], v119, v119, v55
	v_rcp_f32_e32 v124, v123
	s_nop 0
	v_fma_f32 v120, -v123, v124, 1.0
	v_fmac_f32_e32 v124, v120, v124
	v_div_scale_f32 v120, vcc, v55, v119, v55
	v_mul_f32_e32 v121, v120, v124
	v_fma_f32 v122, -v123, v121, v120
	v_fmac_f32_e32 v121, v122, v124
	v_div_scale_f32 v122, s[4:5], v118, v118, v54
	v_fma_f32 v120, -v123, v121, v120
	v_rcp_f32_e32 v123, v122
	v_div_fmas_f32 v120, v120, v124, v121
	v_div_fixup_f32 v119, v120, v119, v55
	v_fma_f32 v120, -v122, v123, 1.0
	v_fmac_f32_e32 v123, v120, v123
	v_div_scale_f32 v120, vcc, v54, v118, v54
	v_mul_f32_e32 v121, v120, v123
	v_fma_f32 v124, -v122, v121, v120
	v_fmac_f32_e32 v121, v124, v123
	v_fma_f32 v120, -v122, v121, v120
	v_div_scale_f32 v122, s[4:5], v117, v117, v53
	v_rcp_f32_e32 v124, v122
	v_div_fmas_f32 v120, v120, v123, v121
	v_div_fixup_f32 v118, v120, v118, v54
	v_fma_f32 v120, -v122, v124, 1.0
	v_fmac_f32_e32 v124, v120, v124
	v_div_scale_f32 v120, vcc, v53, v117, v53
	v_mul_f32_e32 v121, v120, v124
	v_fma_f32 v123, -v122, v121, v120
	v_fmac_f32_e32 v121, v123, v124
	v_fma_f32 v120, -v122, v121, v120
	v_div_scale_f32 v122, s[4:5], v116, v116, v52
	v_rcp_f32_e32 v125, v122
	v_div_fmas_f32 v120, v120, v124, v121
	v_div_fixup_f32 v117, v120, v117, v53
	v_mul_f32_e32 v123, 0xbfb8aa3b, v57
	v_fma_f32 v120, -v122, v125, 1.0
	v_fmac_f32_e32 v125, v120, v125
	v_div_scale_f32 v120, vcc, v52, v116, v52
	v_mul_f32_e32 v124, v120, v125
	v_fma_f32 v121, -v122, v124, v120
	v_fmac_f32_e32 v124, v121, v125
	v_fma_f32 v126, -v122, v124, v120
	v_mul_f32_e32 v120, 0xbfb8aa3b, v58
	v_mul_f32_e32 v121, 0xbfb8aa3b, v59
	v_exp_f32_e32 v120, v120
	v_exp_f32_e32 v121, v121
	v_mul_f32_e32 v122, 0xbfb8aa3b, v56
	v_exp_f32_e32 v122, v122
	v_exp_f32_e32 v123, v123
	v_pk_add_f32 v[120:121], v[120:121], 1.0 op_sel_hi:[1,0]
	v_div_fmas_f32 v124, v126, v125, v124
	v_div_scale_f32 v127, s[4:5], v121, v121, v59
	v_rcp_f32_e32 v142, v127
	v_div_fixup_f32 v116, v124, v116, v52
	v_pk_add_f32 v[124:125], v[122:123], 1.0 op_sel_hi:[1,0]
	v_fma_f32 v122, -v127, v142, 1.0
	v_fmac_f32_e32 v142, v122, v142
	v_div_scale_f32 v122, vcc, v59, v121, v59
	v_mul_f32_e32 v123, v122, v142
	v_fma_f32 v126, -v127, v123, v122
	v_fmac_f32_e32 v123, v126, v142
	v_div_scale_f32 v126, s[4:5], v120, v120, v58
	v_fma_f32 v122, -v127, v123, v122
	v_rcp_f32_e32 v127, v126
	v_div_fmas_f32 v122, v122, v142, v123
	v_div_fixup_f32 v123, v122, v121, v59
	v_fma_f32 v121, -v126, v127, 1.0
	v_fmac_f32_e32 v127, v121, v127
	v_div_scale_f32 v121, vcc, v58, v120, v58
	v_mul_f32_e32 v122, v121, v127
	v_fma_f32 v142, -v126, v122, v121
	v_fmac_f32_e32 v122, v142, v127
	v_fma_f32 v121, -v126, v122, v121
	v_div_scale_f32 v126, s[4:5], v125, v125, v57
	v_rcp_f32_e32 v142, v126
	v_div_fmas_f32 v121, v121, v127, v122
	v_div_fixup_f32 v122, v121, v120, v58
	v_fma_f32 v120, -v126, v142, 1.0
	v_fmac_f32_e32 v142, v120, v142
	v_div_scale_f32 v120, vcc, v57, v125, v57
	v_mul_f32_e32 v121, v120, v142
	v_fma_f32 v127, -v126, v121, v120
	v_fmac_f32_e32 v121, v127, v142
	v_fma_f32 v120, -v126, v121, v120
	v_div_scale_f32 v126, s[4:5], v124, v124, v56
	v_rcp_f32_e32 v202, v126
	v_div_fmas_f32 v120, v120, v142, v121
	v_div_fixup_f32 v121, v120, v125, v57
	v_mul_f32_e32 v142, 0xbfb8aa3b, v60
	v_fma_f32 v120, -v126, v202, 1.0
	v_fmac_f32_e32 v202, v120, v202
	v_div_scale_f32 v120, vcc, v56, v124, v56
	v_mul_f32_e32 v125, v120, v202
	v_fma_f32 v127, -v126, v125, v120
	v_fmac_f32_e32 v125, v127, v202
	v_fma_f32 v120, -v126, v125, v120
	v_mul_f32_e32 v126, 0xbfb8aa3b, v62
	v_mul_f32_e32 v127, 0xbfb8aa3b, v63
	v_exp_f32_e32 v126, v126
	v_exp_f32_e32 v127, v127
	v_exp_f32_e32 v200, v142
	v_mul_f32_e32 v142, 0xbfb8aa3b, v61
	v_exp_f32_e32 v201, v142
	v_pk_add_f32 v[126:127], v[126:127], 1.0 op_sel_hi:[1,0]
	v_div_fmas_f32 v120, v120, v202, v125
	v_div_scale_f32 v142, s[4:5], v127, v127, v63
	v_rcp_f32_e32 v203, v142
	v_div_fixup_f32 v120, v120, v124, v56
	v_pk_add_f32 v[124:125], v[200:201], 1.0 op_sel_hi:[1,0]
	v_fma_f32 v200, -v142, v203, 1.0
	v_fmac_f32_e32 v203, v200, v203
	v_div_scale_f32 v200, vcc, v63, v127, v63
	v_mul_f32_e32 v201, v200, v203
	v_fma_f32 v202, -v142, v201, v200
	v_fmac_f32_e32 v201, v202, v203
	v_fma_f32 v142, -v142, v201, v200
	v_div_scale_f32 v200, s[4:5], v126, v126, v62
	v_rcp_f32_e32 v202, v200
	v_div_fmas_f32 v142, v142, v203, v201
	v_div_fixup_f32 v127, v142, v127, v63
	v_fma_f32 v142, -v200, v202, 1.0
	v_fmac_f32_e32 v202, v142, v202
	v_div_scale_f32 v142, vcc, v62, v126, v62
	v_mul_f32_e32 v201, v142, v202
	v_fma_f32 v203, -v200, v201, v142
	v_fmac_f32_e32 v201, v203, v202
	v_fma_f32 v142, -v200, v201, v142
	v_div_scale_f32 v200, s[4:5], v125, v125, v61
	v_rcp_f32_e32 v203, v200
	v_div_fmas_f32 v142, v142, v202, v201
	v_div_fixup_f32 v126, v142, v126, v62
	v_fma_f32 v142, -v200, v203, 1.0
	v_fmac_f32_e32 v203, v142, v203
	v_div_scale_f32 v142, vcc, v61, v125, v61
	v_mul_f32_e32 v201, v142, v203
	v_fma_f32 v202, -v200, v201, v142
	v_fmac_f32_e32 v201, v202, v203
	v_fma_f32 v142, -v200, v201, v142
	v_div_scale_f32 v200, s[4:5], v124, v124, v60
	v_rcp_f32_e32 v202, v200
	v_div_fmas_f32 v142, v142, v203, v201
	v_div_fixup_f32 v125, v142, v125, v61
	s_lshl_b64 s[4:5], s[66:67], 19
	v_fma_f32 v142, -v200, v202, 1.0
	v_fmac_f32_e32 v202, v142, v202
	v_div_scale_f32 v142, vcc, v60, v124, v60
	s_add_u32 s4, s36, s4
	v_mul_f32_e32 v201, v142, v202
	s_addc_u32 s5, s37, s5
	s_lshl_b32 s34, s0, 7
	v_fma_f32 v203, -v200, v201, v142
	s_lshl_b64 s[0:1], s[34:35], 1
	v_fmac_f32_e32 v201, v203, v202
	s_add_u32 s0, s4, s0
	v_fma_f32 v142, -v200, v201, v142
	s_addc_u32 s1, s5, s1
	v_div_fmas_f32 v142, v142, v202, v201
	s_add_u32 s4, s0, 0xffffd800
	v_div_fixup_f32 v124, v142, v124, v60
	s_addc_u32 s5, s1, -1

	.amdhsa_kernel _Z14fwd_megakernel6Params
		.amdhsa_group_segment_fixed_size 65568
		.amdhsa_private_segment_fixed_size 0
		.amdhsa_kernarg_size 448
		.amdhsa_user_sgpr_count 2
		.amdhsa_user_sgpr_dispatch_ptr 0
		.amdhsa_user_sgpr_queue_ptr 0
		.amdhsa_user_sgpr_kernarg_segment_ptr 1
		.amdhsa_user_sgpr_dispatch_id 0
		.amdhsa_user_sgpr_kernarg_preload_length 0
		.amdhsa_user_sgpr_kernarg_preload_offset 0
		.amdhsa_user_sgpr_private_segment_size 0
		.amdhsa_uses_dynamic_stack 0
		.amdhsa_enable_private_segment 0
		.amdhsa_system_sgpr_workgroup_id_x 1
		.amdhsa_system_sgpr_workgroup_id_y 0
		.amdhsa_system_sgpr_workgroup_id_z 0
		.amdhsa_system_sgpr_workgroup_info 0
		.amdhsa_system_vgpr_workitem_id 2
		.amdhsa_next_free_vgpr 256
		.amdhsa_next_free_sgpr 98
		.amdhsa_accum_offset 256
		.amdhsa_reserve_vcc 1
		.amdhsa_float_round_mode_32 0
		.amdhsa_float_round_mode_16_64 0
		.amdhsa_float_denorm_mode_32 3
		.amdhsa_float_denorm_mode_16_64 3
		.amdhsa_dx10_clamp 1
		.amdhsa_ieee_mode 1
		.amdhsa_fp16_overflow 0
		.amdhsa_tg_split 0
		.amdhsa_exception_fp_ieee_invalid_op 0
		.amdhsa_exception_fp_denorm_src 0
		.amdhsa_exception_fp_ieee_div_zero 0
		.amdhsa_exception_fp_ieee_overflow 0
		.amdhsa_exception_fp_ieee_underflow 0
		.amdhsa_exception_fp_ieee_inexact 0
		.amdhsa_exception_int_div_zero 0
	.end_amdhsa_kernel

amdhsa.kernels:
  - .agpr_count:     0
    .args:
      - .offset:         0
        .size:           192
        .value_kind:     by_value
      - .offset:         192
        .size:           4
        .value_kind:     hidden_block_count_x
      - .offset:         196
        .size:           4
        .value_kind:     hidden_block_count_y
      - .offset:         200
        .size:           4
        .value_kind:     hidden_block_count_z
      - .offset:         204
        .size:           2
        .value_kind:     hidden_group_size_x
      - .offset:         206
        .size:           2
        .value_kind:     hidden_group_size_y
      - .offset:         208
        .size:           2
        .value_kind:     hidden_group_size_z
      - .offset:         210
        .size:           2
        .value_kind:     hidden_remainder_x
      - .offset:         212
        .size:           2
        .value_kind:     hidden_remainder_y
      - .offset:         214
        .size:           2
        .value_kind:     hidden_remainder_z
      - .offset:         232
        .size:           8
        .value_kind:     hidden_global_offset_x
      - .offset:         240
        .size:           8
        .value_kind:     hidden_global_offset_y
      - .offset:         248
        .size:           8
        .value_kind:     hidden_global_offset_z
      - .offset:         256
        .size:           2
        .value_kind:     hidden_grid_dims
      - .offset:         280
        .size:           8
        .value_kind:     hidden_multigrid_sync_arg
    .group_segment_fixed_size: 65568
    .kernarg_segment_align: 8
    .kernarg_segment_size: 448
    .language:       OpenCL C
    .language_version:
      - 2
      - 0
    .max_flat_workgroup_size: 256
    .name:           _Z14fwd_megakernel6Params
    .private_segment_fixed_size: 0
    .sgpr_count:     104
    .sgpr_spill_count: 65
    .symbol:         _Z14fwd_megakernel6Params.kd
    .uniform_work_group_size: 1
    .uses_dynamic_stack: false
    .vgpr_count:     256
    .vgpr_spill_count: 0
    .wavefront_size: 64
